# P4a gate epilogues software-pipelined (6-deep prefetch, counted vmcnt) + fox_prep q/k RMSNorm rewritten coalesced (8 lanes per row, DPP row sums), V^T/cumsum kept
# speedup vs baseline: 1.0419x; 1.0419x over previous
; __device__ __forceinline__ float bflo(unsigned u) { return __uint_as_float(u << 16); }
; __device__ __forceinline__ float bfhi(unsigned u) { return __uint_as_float(u & 0xffff0000u); }
; DI float bflo(unsigned u) { return __uint_as_float(u << 16); }
; DI float bfhi(unsigned u) { return __uint_as_float(u & 0xffff0000u); }
; DI unsigned pk2(float lo, float hi) { f32x2_t v = {lo, hi}; bf16x2_t b = __builtin_convertvector(v, bf16x2_t); return __builtin_bit_cast(unsigned, b); }
; DI void fox_prep_unit(const Params& P, int n, unsigned char* lds, int tid) {
;     ...
; #pragma unroll
;     for (int which = 0; which < 2; ++which) {
;         bf16_t* ptr = which ? FK : FQ; const float* nw = which ? P.in[10] : P.in[9]; const float sc = which ? 1.0f : 0.125f * 1.4426950408889634f;
;         u32x4 raw[8]; float ss = 0.f;
; #pragma unroll
;         for (int i = 0; i < 8; ++i) { raw[i] = *(const u32x4*)(ptr + 8 * i);
;             const float a0 = bflo(raw[i].x), a1 = bfhi(raw[i].x), a2 = bflo(raw[i].y), a3 = bfhi(raw[i].y), a4 = bflo(raw[i].z), a5 = bfhi(raw[i].z), a6 = bflo(raw[i].w), a7 = bfhi(raw[i].w);
;             ss += (a0 * a0 + a1 * a1) + (a2 * a2 + a3 * a3) + (a4 * a4 + a5 * a5) + (a6 * a6 + a7 * a7); }
;         const float rstd = rsqrtf(ss * (1.f / 64.f) + EPS) * sc;
; #pragma unroll
;         for (int i = 0; i < 8; ++i) { const f32x4 w0 = *(const f32x4*)(nw + 8 * i), w1 = *(const f32x4*)(nw + 8 * i + 4); u32x4 o;
;             o.x = pk2(bflo(raw[i].x) * rstd * w0.x, bfhi(raw[i].x) * rstd * w0.y); o.y = pk2(bflo(raw[i].y) * rstd * w0.z, bfhi(raw[i].y) * rstd * w0.w);
;             o.z = pk2(bflo(raw[i].z) * rstd * w1.x, bfhi(raw[i].z) * rstd * w1.y); o.w = pk2(bflo(raw[i].w) * rstd * w1.z, bfhi(raw[i].w) * rstd * w1.w);
;             *(u32x4*)(ptr + 8 * i) = o; }
;     }
;     ...
;       for (int i = 0; i < 8; ++i) { const u32x4 r = *(const u32x4*)(FV + 8 * i);
.LBB0_591:
	v_ashrrev_i32_e32 v27, 31, v26
	v_lshlrev_b64 v[30:31], 10, v[26:27]
	v_add_co_u32_e32 v78, vcc, s17, v28
	s_nop 1
	v_addc_co_u32_e32 v79, vcc, 0, v29, vcc
	v_add_co_u32_e32 v80, vcc, s18, v28
	s_nop 1
	v_addc_co_u32_e32 v81, vcc, 0, v29, vcc
	v_add_co_u32_e32 v82, vcc, s19, v28
	v_lshl_add_u64 v[74:75], v[18:19], 0, v[30:31]
	s_nop 1
	v_addc_co_u32_e32 v83, vcc, 0, v29, vcc
	v_add_co_u32_e32 v84, vcc, s20, v28
	s_nop 1
	v_addc_co_u32_e32 v85, vcc, 0, v29, vcc
	v_add_co_u32_e32 v86, vcc, s21, v28
	s_nop 1
	v_addc_co_u32_e32 v87, vcc, 0, v29, vcc
	global_load_dwordx4 v[30:33], v[74:75], off
	global_load_dwordx4 v[40:43], v[74:75], off offset:16
	global_load_dwordx4 v[54:57], v[74:75], off offset:32
	global_load_dwordx4 v[58:61], v[74:75], off offset:48
	global_load_dwordx4 v[62:65], v[74:75], off offset:64
	global_load_dwordx4 v[66:69], v[74:75], off offset:80
	global_load_dwordx4 v[70:73], v[74:75], off offset:96
	global_load_dwordx4 v[74:77], v[74:75], off offset:112
	v_readlane_b32 s36, v239, 3
	v_readlane_b32 s37, v239, 4
	v_readlane_b32 s40, v239, 14
	v_readlane_b32 s41, v239, 15
	v_readlane_b32 s42, v239, 16
	v_readlane_b32 s43, v239, 17
	s_lshl_b32 s28, s27, 16
	s_add_u32 s36, s36, s28
	s_addc_u32 s37, s37, 0
	s_add_u32 s38, s36, 0x8500000
	s_addc_u32 s39, s37, 0
	s_add_u32 s36, s36, 0x7500000
	s_addc_u32 s37, s37, 0
	s_mov_b64 s[44:45], s[36:37]
	s_mov_b64 s[46:47], s[38:39]
	v_lshlrev_b32_e32 v2, 4, v162
	v_and_b32_e32 v3, 7, v162
	v_lshlrev_b32_e32 v3, 5, v3
	s_nop 1
	global_load_dwordx4 v[240:243], v3, s[40:41]
	global_load_dwordx4 v[244:247], v3, s[40:41] offset:16
	global_load_dwordx4 v[110:113], v2, s[36:37]
	s_add_u32 s36, s36, 0x2000
	s_addc_u32 s37, s37, 0
	global_load_dwordx4 v[114:117], v2, s[36:37]
	s_add_u32 s36, s36, 0x2000
	s_addc_u32 s37, s37, 0
	global_load_dwordx4 v[118:121], v2, s[36:37]
	s_add_u32 s36, s36, 0x2000
	s_addc_u32 s37, s37, 0
	global_load_dwordx4 v[122:125], v2, s[36:37]
	s_add_u32 s36, s36, 0x2000
	s_addc_u32 s37, s37, 0
	global_load_dwordx4 v[126:129], v2, s[36:37]
	s_add_u32 s36, s36, 0x2000
	s_addc_u32 s37, s37, 0
	global_load_dwordx4 v[130:133], v2, s[36:37]
	s_add_u32 s36, s36, 0x2000
	s_addc_u32 s37, s37, 0
	global_load_dwordx4 v[134:137], v2, s[36:37]
	s_add_u32 s36, s36, 0x2000
	s_addc_u32 s37, s37, 0
	global_load_dwordx4 v[138:141], v2, s[36:37]
	global_load_dwordx4 v[88:91], v2, s[38:39]
	s_add_u32 s38, s38, 0x2000
	s_addc_u32 s39, s39, 0
	global_load_dwordx4 v[92:95], v2, s[38:39]
	s_add_u32 s38, s38, 0x2000
	s_addc_u32 s39, s39, 0
	global_load_dwordx4 v[96:99], v2, s[38:39]
	s_add_u32 s38, s38, 0x2000
	s_addc_u32 s39, s39, 0
	global_load_dwordx4 v[100:103], v2, s[38:39]
	s_add_u32 s38, s38, 0x2000
	s_addc_u32 s39, s39, 0
	global_load_dwordx4 v[44:47], v2, s[38:39]
	s_add_u32 s38, s38, 0x2000
	s_addc_u32 s39, s39, 0
	global_load_dwordx4 v[48:51], v2, s[38:39]
	s_add_u32 s38, s38, 0x2000
	s_addc_u32 s39, s39, 0
	global_load_dwordx4 v[4:7], v2, s[38:39]
	s_add_u32 s38, s38, 0x2000
	s_addc_u32 s39, s39, 0
	global_load_dwordx4 v[8:11], v2, s[38:39]
	s_waitcnt vmcnt(15)
	v_lshlrev_b32_e32 v34, 16, v110
	v_and_b32_e32 v35, 0xffff0000, v110
	v_lshlrev_b32_e32 v36, 16, v111
	v_and_b32_e32 v37, 0xffff0000, v111
	v_lshlrev_b32_e32 v38, 16, v112
	v_and_b32_e32 v39, 0xffff0000, v112
	v_lshlrev_b32_e32 v52, 16, v113
	v_and_b32_e32 v53, 0xffff0000, v113
	v_mul_f32_e32 v248, v34, v34
	v_fmac_f32_e32 v248, v35, v35
	v_fmac_f32_e32 v248, v36, v36
	v_fmac_f32_e32 v248, v37, v37
	v_fmac_f32_e32 v248, v38, v38
	v_fmac_f32_e32 v248, v39, v39
	v_fmac_f32_e32 v248, v52, v52
	v_fmac_f32_e32 v248, v53, v53
	s_waitcnt vmcnt(14)
	v_lshlrev_b32_e32 v34, 16, v114
	v_and_b32_e32 v35, 0xffff0000, v114
	v_lshlrev_b32_e32 v36, 16, v115
	v_and_b32_e32 v37, 0xffff0000, v115
	v_lshlrev_b32_e32 v38, 16, v116
	v_and_b32_e32 v39, 0xffff0000, v116
	v_lshlrev_b32_e32 v52, 16, v117
	v_and_b32_e32 v53, 0xffff0000, v117
	v_mul_f32_e32 v249, v34, v34
	v_fmac_f32_e32 v249, v35, v35
	v_fmac_f32_e32 v249, v36, v36
	v_fmac_f32_e32 v249, v37, v37
	v_fmac_f32_e32 v249, v38, v38
	v_fmac_f32_e32 v249, v39, v39
	v_fmac_f32_e32 v249, v52, v52
	v_fmac_f32_e32 v249, v53, v53
	s_waitcnt vmcnt(13)
	v_lshlrev_b32_e32 v34, 16, v118
	v_and_b32_e32 v35, 0xffff0000, v118
	v_lshlrev_b32_e32 v36, 16, v119
	v_and_b32_e32 v37, 0xffff0000, v119
	v_lshlrev_b32_e32 v38, 16, v120
	v_and_b32_e32 v39, 0xffff0000, v120
	v_lshlrev_b32_e32 v52, 16, v121
	v_and_b32_e32 v53, 0xffff0000, v121
	v_mul_f32_e32 v250, v34, v34
	v_fmac_f32_e32 v250, v35, v35
	v_fmac_f32_e32 v250, v36, v36
	v_fmac_f32_e32 v250, v37, v37
	v_fmac_f32_e32 v250, v38, v38
	v_fmac_f32_e32 v250, v39, v39
	v_fmac_f32_e32 v250, v52, v52
	v_fmac_f32_e32 v250, v53, v53
	s_waitcnt vmcnt(12)
	v_lshlrev_b32_e32 v34, 16, v122
	v_and_b32_e32 v35, 0xffff0000, v122
	v_lshlrev_b32_e32 v36, 16, v123
	v_and_b32_e32 v37, 0xffff0000, v123
	v_lshlrev_b32_e32 v38, 16, v124
	v_and_b32_e32 v39, 0xffff0000, v124
	v_lshlrev_b32_e32 v52, 16, v125
	v_and_b32_e32 v53, 0xffff0000, v125
	v_mul_f32_e32 v251, v34, v34
	v_fmac_f32_e32 v251, v35, v35
	v_fmac_f32_e32 v251, v36, v36
	v_fmac_f32_e32 v251, v37, v37
	v_fmac_f32_e32 v251, v38, v38
	v_fmac_f32_e32 v251, v39, v39
	v_fmac_f32_e32 v251, v52, v52
	v_fmac_f32_e32 v251, v53, v53
	s_waitcnt vmcnt(11)
	v_lshlrev_b32_e32 v34, 16, v126
	v_and_b32_e32 v35, 0xffff0000, v126
	v_lshlrev_b32_e32 v36, 16, v127
	v_and_b32_e32 v37, 0xffff0000, v127
	v_lshlrev_b32_e32 v38, 16, v128
	v_and_b32_e32 v39, 0xffff0000, v128
	v_lshlrev_b32_e32 v52, 16, v129
	v_and_b32_e32 v53, 0xffff0000, v129
	v_mul_f32_e32 v252, v34, v34
	v_fmac_f32_e32 v252, v35, v35
	v_fmac_f32_e32 v252, v36, v36
	v_fmac_f32_e32 v252, v37, v37
	v_fmac_f32_e32 v252, v38, v38
	v_fmac_f32_e32 v252, v39, v39
	v_fmac_f32_e32 v252, v52, v52
	v_fmac_f32_e32 v252, v53, v53
	s_waitcnt vmcnt(10)
; __device__ __forceinline__ float bflo(unsigned u) { return __uint_as_float(u << 16); }
; __device__ __forceinline__ float bfhi(unsigned u) { return __uint_as_float(u & 0xffff0000u); }
; DI float bflo(unsigned u) { return __uint_as_float(u << 16); }
; DI float bfhi(unsigned u) { return __uint_as_float(u & 0xffff0000u); }
; DI unsigned pk2(float lo, float hi) { f32x2_t v = {lo, hi}; bf16x2_t b = __builtin_convertvector(v, bf16x2_t); return __builtin_bit_cast(unsigned, b); }
; DI void fox_prep_unit(const Params& P, int n, unsigned char* lds, int tid) {
;     ...
;         for (int i = 0; i < 8; ++i) { raw[i] = *(const u32x4*)(ptr + 8 * i);
;             const float a0 = bflo(raw[i].x), a1 = bfhi(raw[i].x), a2 = bflo(raw[i].y), a3 = bfhi(raw[i].y), a4 = bflo(raw[i].z), a5 = bfhi(raw[i].z), a6 = bflo(raw[i].w), a7 = bfhi(raw[i].w);
;             ss += (a0 * a0 + a1 * a1) + (a2 * a2 + a3 * a3) + (a4 * a4 + a5 * a5) + (a6 * a6 + a7 * a7); }
;         const float rstd = rsqrtf(ss * (1.f / 64.f) + EPS) * sc;
; #pragma unroll
;         for (int i = 0; i < 8; ++i) { const f32x4 w0 = *(const f32x4*)(nw + 8 * i), w1 = *(const f32x4*)(nw + 8 * i + 4); u32x4 o;
;             o.x = pk2(bflo(raw[i].x) * rstd * w0.x, bfhi(raw[i].x) * rstd * w0.y); o.y = pk2(bflo(raw[i].y) * rstd * w0.z, bfhi(raw[i].y) * rstd * w0.w);
;             o.z = pk2(bflo(raw[i].z) * rstd * w1.x, bfhi(raw[i].z) * rstd * w1.y); o.w = pk2(bflo(raw[i].w) * rstd * w1.z, bfhi(raw[i].w) * rstd * w1.w);
;             *(u32x4*)(ptr + 8 * i) = o; }
	v_lshlrev_b32_e32 v34, 16, v130
	v_and_b32_e32 v35, 0xffff0000, v130
	v_lshlrev_b32_e32 v36, 16, v131
	v_and_b32_e32 v37, 0xffff0000, v131
	v_lshlrev_b32_e32 v38, 16, v132
	v_and_b32_e32 v39, 0xffff0000, v132
	v_lshlrev_b32_e32 v52, 16, v133
	v_and_b32_e32 v53, 0xffff0000, v133
	v_mul_f32_e32 v253, v34, v34
	v_fmac_f32_e32 v253, v35, v35
	v_fmac_f32_e32 v253, v36, v36
	v_fmac_f32_e32 v253, v37, v37
	v_fmac_f32_e32 v253, v38, v38
	v_fmac_f32_e32 v253, v39, v39
	v_fmac_f32_e32 v253, v52, v52
	v_fmac_f32_e32 v253, v53, v53
	s_waitcnt vmcnt(9)
	v_lshlrev_b32_e32 v34, 16, v134
	v_and_b32_e32 v35, 0xffff0000, v134
	v_lshlrev_b32_e32 v36, 16, v135
	v_and_b32_e32 v37, 0xffff0000, v135
	v_lshlrev_b32_e32 v38, 16, v136
	v_and_b32_e32 v39, 0xffff0000, v136
	v_lshlrev_b32_e32 v52, 16, v137
	v_and_b32_e32 v53, 0xffff0000, v137
	v_mul_f32_e32 v254, v34, v34
	v_fmac_f32_e32 v254, v35, v35
	v_fmac_f32_e32 v254, v36, v36
	v_fmac_f32_e32 v254, v37, v37
	v_fmac_f32_e32 v254, v38, v38
	v_fmac_f32_e32 v254, v39, v39
	v_fmac_f32_e32 v254, v52, v52
	v_fmac_f32_e32 v254, v53, v53
	s_waitcnt vmcnt(8)
	v_lshlrev_b32_e32 v34, 16, v138
	v_and_b32_e32 v35, 0xffff0000, v138
	v_lshlrev_b32_e32 v36, 16, v139
	v_and_b32_e32 v37, 0xffff0000, v139
	v_lshlrev_b32_e32 v38, 16, v140
	v_and_b32_e32 v39, 0xffff0000, v140
	v_lshlrev_b32_e32 v52, 16, v141
	v_and_b32_e32 v53, 0xffff0000, v141
	v_mul_f32_e32 v255, v34, v34
	v_fmac_f32_e32 v255, v35, v35
	v_fmac_f32_e32 v255, v36, v36
	v_fmac_f32_e32 v255, v37, v37
	v_fmac_f32_e32 v255, v38, v38
	v_fmac_f32_e32 v255, v39, v39
	v_fmac_f32_e32 v255, v52, v52
	v_fmac_f32_e32 v255, v53, v53
	v_add_f32_dpp v248, v248, v248 quad_perm:[1,0,3,2] row_mask:0xf bank_mask:0xf bound_ctrl:1
	v_add_f32_dpp v249, v249, v249 quad_perm:[1,0,3,2] row_mask:0xf bank_mask:0xf bound_ctrl:1
	v_add_f32_dpp v250, v250, v250 quad_perm:[1,0,3,2] row_mask:0xf bank_mask:0xf bound_ctrl:1
	v_add_f32_dpp v251, v251, v251 quad_perm:[1,0,3,2] row_mask:0xf bank_mask:0xf bound_ctrl:1
	v_add_f32_dpp v252, v252, v252 quad_perm:[1,0,3,2] row_mask:0xf bank_mask:0xf bound_ctrl:1
	v_add_f32_dpp v253, v253, v253 quad_perm:[1,0,3,2] row_mask:0xf bank_mask:0xf bound_ctrl:1
	v_add_f32_dpp v254, v254, v254 quad_perm:[1,0,3,2] row_mask:0xf bank_mask:0xf bound_ctrl:1
	v_add_f32_dpp v255, v255, v255 quad_perm:[1,0,3,2] row_mask:0xf bank_mask:0xf bound_ctrl:1
	v_add_f32_dpp v248, v248, v248 quad_perm:[2,3,0,1] row_mask:0xf bank_mask:0xf bound_ctrl:1
	v_add_f32_dpp v249, v249, v249 quad_perm:[2,3,0,1] row_mask:0xf bank_mask:0xf bound_ctrl:1
	v_add_f32_dpp v250, v250, v250 quad_perm:[2,3,0,1] row_mask:0xf bank_mask:0xf bound_ctrl:1
	v_add_f32_dpp v251, v251, v251 quad_perm:[2,3,0,1] row_mask:0xf bank_mask:0xf bound_ctrl:1
	v_add_f32_dpp v252, v252, v252 quad_perm:[2,3,0,1] row_mask:0xf bank_mask:0xf bound_ctrl:1
	v_add_f32_dpp v253, v253, v253 quad_perm:[2,3,0,1] row_mask:0xf bank_mask:0xf bound_ctrl:1
	v_add_f32_dpp v254, v254, v254 quad_perm:[2,3,0,1] row_mask:0xf bank_mask:0xf bound_ctrl:1
	v_add_f32_dpp v255, v255, v255 quad_perm:[2,3,0,1] row_mask:0xf bank_mask:0xf bound_ctrl:1
	v_add_f32_dpp v248, v248, v248 row_half_mirror row_mask:0xf bank_mask:0xf bound_ctrl:1
	v_add_f32_dpp v249, v249, v249 row_half_mirror row_mask:0xf bank_mask:0xf bound_ctrl:1
	v_add_f32_dpp v250, v250, v250 row_half_mirror row_mask:0xf bank_mask:0xf bound_ctrl:1
	v_add_f32_dpp v251, v251, v251 row_half_mirror row_mask:0xf bank_mask:0xf bound_ctrl:1
	v_add_f32_dpp v252, v252, v252 row_half_mirror row_mask:0xf bank_mask:0xf bound_ctrl:1
	v_add_f32_dpp v253, v253, v253 row_half_mirror row_mask:0xf bank_mask:0xf bound_ctrl:1
	v_add_f32_dpp v254, v254, v254 row_half_mirror row_mask:0xf bank_mask:0xf bound_ctrl:1
	v_add_f32_dpp v255, v255, v255 row_half_mirror row_mask:0xf bank_mask:0xf bound_ctrl:1
	v_mov_b32_e32 v12, 0x358637bd
	v_fmamk_f32 v248, v248, 0x3c800000, v12
	v_fmamk_f32 v249, v249, 0x3c800000, v12
	v_fmamk_f32 v250, v250, 0x3c800000, v12
	v_fmamk_f32 v251, v251, 0x3c800000, v12
	v_fmamk_f32 v252, v252, 0x3c800000, v12
	v_fmamk_f32 v253, v253, 0x3c800000, v12
	v_fmamk_f32 v254, v254, 0x3c800000, v12
	v_fmamk_f32 v255, v255, 0x3c800000, v12
	v_rsq_f32_e32 v248, v248
	v_rsq_f32_e32 v249, v249
	v_rsq_f32_e32 v250, v250
	v_rsq_f32_e32 v251, v251
	v_rsq_f32_e32 v252, v252
	v_rsq_f32_e32 v253, v253
	v_rsq_f32_e32 v254, v254
	v_rsq_f32_e32 v255, v255
	v_mul_f32_e32 v248, 0x3e38aa3b, v248
	v_mul_f32_e32 v249, 0x3e38aa3b, v249
	v_mul_f32_e32 v250, 0x3e38aa3b, v250
	v_mul_f32_e32 v251, 0x3e38aa3b, v251
	v_mul_f32_e32 v252, 0x3e38aa3b, v252
	v_mul_f32_e32 v253, 0x3e38aa3b, v253
	v_mul_f32_e32 v254, 0x3e38aa3b, v254
	v_mul_f32_e32 v255, 0x3e38aa3b, v255
	v_lshlrev_b32_e32 v34, 16, v110
	v_and_b32_e32 v35, 0xffff0000, v110
	v_lshlrev_b32_e32 v36, 16, v111
	v_and_b32_e32 v37, 0xffff0000, v111
	v_lshlrev_b32_e32 v38, 16, v112
	v_and_b32_e32 v39, 0xffff0000, v112
	v_lshlrev_b32_e32 v52, 16, v113
	v_and_b32_e32 v53, 0xffff0000, v113
	v_pk_mul_f32 v[34:35], v[248:249], v[34:35] op_sel_hi:[0,1]
	v_pk_mul_f32 v[36:37], v[248:249], v[36:37] op_sel_hi:[0,1]
	v_pk_mul_f32 v[38:39], v[248:249], v[38:39] op_sel_hi:[0,1]
	v_pk_mul_f32 v[52:53], v[248:249], v[52:53] op_sel_hi:[0,1]
	v_pk_mul_f32 v[34:35], v[240:241], v[34:35]
	v_pk_mul_f32 v[36:37], v[242:243], v[36:37]
	v_pk_mul_f32 v[38:39], v[244:245], v[38:39]
	v_pk_mul_f32 v[52:53], v[246:247], v[52:53]
	v_cvt_pk_bf16_f32 v110, v34, v35
	v_cvt_pk_bf16_f32 v111, v36, v37
	v_cvt_pk_bf16_f32 v112, v38, v39
	v_cvt_pk_bf16_f32 v113, v52, v53
	global_store_dwordx4 v2, v[110:113], s[44:45]
	s_add_u32 s44, s44, 0x2000
	s_addc_u32 s45, s45, 0
	v_lshlrev_b32_e32 v34, 16, v114
; __device__ __forceinline__ float bflo(unsigned u) { return __uint_as_float(u << 16); }
; __device__ __forceinline__ float bfhi(unsigned u) { return __uint_as_float(u & 0xffff0000u); }
; DI float bflo(unsigned u) { return __uint_as_float(u << 16); }
; DI float bfhi(unsigned u) { return __uint_as_float(u & 0xffff0000u); }
; DI unsigned pk2(float lo, float hi) { f32x2_t v = {lo, hi}; bf16x2_t b = __builtin_convertvector(v, bf16x2_t); return __builtin_bit_cast(unsigned, b); }
; DI void fox_prep_unit(const Params& P, int n, unsigned char* lds, int tid) {
;     ...
;         const float rstd = rsqrtf(ss * (1.f / 64.f) + EPS) * sc;
; #pragma unroll
;         for (int i = 0; i < 8; ++i) { const f32x4 w0 = *(const f32x4*)(nw + 8 * i), w1 = *(const f32x4*)(nw + 8 * i + 4); u32x4 o;
;             o.x = pk2(bflo(raw[i].x) * rstd * w0.x, bfhi(raw[i].x) * rstd * w0.y); o.y = pk2(bflo(raw[i].y) * rstd * w0.z, bfhi(raw[i].y) * rstd * w0.w);
;             o.z = pk2(bflo(raw[i].z) * rstd * w1.x, bfhi(raw[i].z) * rstd * w1.y); o.w = pk2(bflo(raw[i].w) * rstd * w1.z, bfhi(raw[i].w) * rstd * w1.w);
;             *(u32x4*)(ptr + 8 * i) = o; }
	v_and_b32_e32 v35, 0xffff0000, v114
	v_lshlrev_b32_e32 v36, 16, v115
	v_and_b32_e32 v37, 0xffff0000, v115
	v_lshlrev_b32_e32 v38, 16, v116
	v_and_b32_e32 v39, 0xffff0000, v116
	v_lshlrev_b32_e32 v52, 16, v117
	v_and_b32_e32 v53, 0xffff0000, v117
	v_pk_mul_f32 v[34:35], v[248:249], v[34:35] op_sel:[1,0] op_sel_hi:[1,1]
	v_pk_mul_f32 v[36:37], v[248:249], v[36:37] op_sel:[1,0] op_sel_hi:[1,1]
	v_pk_mul_f32 v[38:39], v[248:249], v[38:39] op_sel:[1,0] op_sel_hi:[1,1]
	v_pk_mul_f32 v[52:53], v[248:249], v[52:53] op_sel:[1,0] op_sel_hi:[1,1]
	v_pk_mul_f32 v[34:35], v[240:241], v[34:35]
	v_pk_mul_f32 v[36:37], v[242:243], v[36:37]
	v_pk_mul_f32 v[38:39], v[244:245], v[38:39]
	v_pk_mul_f32 v[52:53], v[246:247], v[52:53]
	v_cvt_pk_bf16_f32 v114, v34, v35
	v_cvt_pk_bf16_f32 v115, v36, v37
	v_cvt_pk_bf16_f32 v116, v38, v39
	v_cvt_pk_bf16_f32 v117, v52, v53
	global_store_dwordx4 v2, v[114:117], s[44:45]
	s_add_u32 s44, s44, 0x2000
	s_addc_u32 s45, s45, 0
	global_load_dwordx4 v[110:113], v3, s[42:43]
	global_load_dwordx4 v[114:117], v3, s[42:43] offset:16
	v_lshlrev_b32_e32 v34, 16, v118
	v_and_b32_e32 v35, 0xffff0000, v118
	v_lshlrev_b32_e32 v36, 16, v119
	v_and_b32_e32 v37, 0xffff0000, v119
	v_lshlrev_b32_e32 v38, 16, v120
	v_and_b32_e32 v39, 0xffff0000, v120
	v_lshlrev_b32_e32 v52, 16, v121
	v_and_b32_e32 v53, 0xffff0000, v121
	v_pk_mul_f32 v[34:35], v[250:251], v[34:35] op_sel_hi:[0,1]
	v_pk_mul_f32 v[36:37], v[250:251], v[36:37] op_sel_hi:[0,1]
	v_pk_mul_f32 v[38:39], v[250:251], v[38:39] op_sel_hi:[0,1]
	v_pk_mul_f32 v[52:53], v[250:251], v[52:53] op_sel_hi:[0,1]
	v_pk_mul_f32 v[34:35], v[240:241], v[34:35]
	v_pk_mul_f32 v[36:37], v[242:243], v[36:37]
	v_pk_mul_f32 v[38:39], v[244:245], v[38:39]
	v_pk_mul_f32 v[52:53], v[246:247], v[52:53]
	v_cvt_pk_bf16_f32 v118, v34, v35
	v_cvt_pk_bf16_f32 v119, v36, v37
	v_cvt_pk_bf16_f32 v120, v38, v39
	v_cvt_pk_bf16_f32 v121, v52, v53
	global_store_dwordx4 v2, v[118:121], s[44:45]
	s_add_u32 s44, s44, 0x2000
	s_addc_u32 s45, s45, 0
	v_lshlrev_b32_e32 v34, 16, v122
	v_and_b32_e32 v35, 0xffff0000, v122
	v_lshlrev_b32_e32 v36, 16, v123
	v_and_b32_e32 v37, 0xffff0000, v123
	v_lshlrev_b32_e32 v38, 16, v124
	v_and_b32_e32 v39, 0xffff0000, v124
	v_lshlrev_b32_e32 v52, 16, v125
	v_and_b32_e32 v53, 0xffff0000, v125
	v_pk_mul_f32 v[34:35], v[250:251], v[34:35] op_sel:[1,0] op_sel_hi:[1,1]
	v_pk_mul_f32 v[36:37], v[250:251], v[36:37] op_sel:[1,0] op_sel_hi:[1,1]
	v_pk_mul_f32 v[38:39], v[250:251], v[38:39] op_sel:[1,0] op_sel_hi:[1,1]
	v_pk_mul_f32 v[52:53], v[250:251], v[52:53] op_sel:[1,0] op_sel_hi:[1,1]
	v_pk_mul_f32 v[34:35], v[240:241], v[34:35]
	v_pk_mul_f32 v[36:37], v[242:243], v[36:37]
	v_pk_mul_f32 v[38:39], v[244:245], v[38:39]
	v_pk_mul_f32 v[52:53], v[246:247], v[52:53]
	v_cvt_pk_bf16_f32 v122, v34, v35
	v_cvt_pk_bf16_f32 v123, v36, v37
	v_cvt_pk_bf16_f32 v124, v38, v39
	v_cvt_pk_bf16_f32 v125, v52, v53
	global_store_dwordx4 v2, v[122:125], s[44:45]
	s_add_u32 s44, s44, 0x2000
	s_addc_u32 s45, s45, 0
	v_lshlrev_b32_e32 v34, 16, v126
	v_and_b32_e32 v35, 0xffff0000, v126
	v_lshlrev_b32_e32 v36, 16, v127
	v_and_b32_e32 v37, 0xffff0000, v127
	v_lshlrev_b32_e32 v38, 16, v128
	v_and_b32_e32 v39, 0xffff0000, v128
	v_lshlrev_b32_e32 v52, 16, v129
	v_and_b32_e32 v53, 0xffff0000, v129
	v_pk_mul_f32 v[34:35], v[252:253], v[34:35] op_sel_hi:[0,1]
	v_pk_mul_f32 v[36:37], v[252:253], v[36:37] op_sel_hi:[0,1]
	v_pk_mul_f32 v[38:39], v[252:253], v[38:39] op_sel_hi:[0,1]
	v_pk_mul_f32 v[52:53], v[252:253], v[52:53] op_sel_hi:[0,1]
	v_pk_mul_f32 v[34:35], v[240:241], v[34:35]
	v_pk_mul_f32 v[36:37], v[242:243], v[36:37]
	v_pk_mul_f32 v[38:39], v[244:245], v[38:39]
	v_pk_mul_f32 v[52:53], v[246:247], v[52:53]
	v_cvt_pk_bf16_f32 v126, v34, v35
	v_cvt_pk_bf16_f32 v127, v36, v37
	v_cvt_pk_bf16_f32 v128, v38, v39
	v_cvt_pk_bf16_f32 v129, v52, v53
	global_store_dwordx4 v2, v[126:129], s[44:45]
	s_add_u32 s44, s44, 0x2000
	s_addc_u32 s45, s45, 0
	v_lshlrev_b32_e32 v34, 16, v130
	v_and_b32_e32 v35, 0xffff0000, v130
	v_lshlrev_b32_e32 v36, 16, v131
	v_and_b32_e32 v37, 0xffff0000, v131
	v_lshlrev_b32_e32 v38, 16, v132
	v_and_b32_e32 v39, 0xffff0000, v132
	v_lshlrev_b32_e32 v52, 16, v133
	v_and_b32_e32 v53, 0xffff0000, v133
	v_pk_mul_f32 v[34:35], v[252:253], v[34:35] op_sel:[1,0] op_sel_hi:[1,1]
	v_pk_mul_f32 v[36:37], v[252:253], v[36:37] op_sel:[1,0] op_sel_hi:[1,1]
	v_pk_mul_f32 v[38:39], v[252:253], v[38:39] op_sel:[1,0] op_sel_hi:[1,1]
	v_pk_mul_f32 v[52:53], v[252:253], v[52:53] op_sel:[1,0] op_sel_hi:[1,1]
	v_pk_mul_f32 v[34:35], v[240:241], v[34:35]
	v_pk_mul_f32 v[36:37], v[242:243], v[36:37]
	v_pk_mul_f32 v[38:39], v[244:245], v[38:39]
	v_pk_mul_f32 v[52:53], v[246:247], v[52:53]
	v_cvt_pk_bf16_f32 v130, v34, v35
	v_cvt_pk_bf16_f32 v131, v36, v37
	v_cvt_pk_bf16_f32 v132, v38, v39
	v_cvt_pk_bf16_f32 v133, v52, v53
	global_store_dwordx4 v2, v[130:133], s[44:45]
	s_add_u32 s44, s44, 0x2000
	s_addc_u32 s45, s45, 0
	v_lshlrev_b32_e32 v34, 16, v134
	v_and_b32_e32 v35, 0xffff0000, v134
	v_lshlrev_b32_e32 v36, 16, v135
	v_and_b32_e32 v37, 0xffff0000, v135
	v_lshlrev_b32_e32 v38, 16, v136
	v_and_b32_e32 v39, 0xffff0000, v136
	v_lshlrev_b32_e32 v52, 16, v137
	v_and_b32_e32 v53, 0xffff0000, v137
	v_pk_mul_f32 v[34:35], v[254:255], v[34:35] op_sel_hi:[0,1]
	v_pk_mul_f32 v[36:37], v[254:255], v[36:37] op_sel_hi:[0,1]
	v_pk_mul_f32 v[38:39], v[254:255], v[38:39] op_sel_hi:[0,1]
	v_pk_mul_f32 v[52:53], v[254:255], v[52:53] op_sel_hi:[0,1]
	v_pk_mul_f32 v[34:35], v[240:241], v[34:35]
	v_pk_mul_f32 v[36:37], v[242:243], v[36:37]
	v_pk_mul_f32 v[38:39], v[244:245], v[38:39]
	v_pk_mul_f32 v[52:53], v[246:247], v[52:53]
	v_cvt_pk_bf16_f32 v134, v34, v35
	v_cvt_pk_bf16_f32 v135, v36, v37
	v_cvt_pk_bf16_f32 v136, v38, v39
	v_cvt_pk_bf16_f32 v137, v52, v53
	global_store_dwordx4 v2, v[134:137], s[44:45]
	s_add_u32 s44, s44, 0x2000
	s_addc_u32 s45, s45, 0
	v_lshlrev_b32_e32 v34, 16, v138
	v_and_b32_e32 v35, 0xffff0000, v138
	v_lshlrev_b32_e32 v36, 16, v139
	v_and_b32_e32 v37, 0xffff0000, v139
	v_lshlrev_b32_e32 v38, 16, v140
	v_and_b32_e32 v39, 0xffff0000, v140
	v_lshlrev_b32_e32 v52, 16, v141
	v_and_b32_e32 v53, 0xffff0000, v141
	v_pk_mul_f32 v[34:35], v[254:255], v[34:35] op_sel:[1,0] op_sel_hi:[1,1]
	v_pk_mul_f32 v[36:37], v[254:255], v[36:37] op_sel:[1,0] op_sel_hi:[1,1]
	v_pk_mul_f32 v[38:39], v[254:255], v[38:39] op_sel:[1,0] op_sel_hi:[1,1]
	v_pk_mul_f32 v[52:53], v[254:255], v[52:53] op_sel:[1,0] op_sel_hi:[1,1]
	v_pk_mul_f32 v[34:35], v[240:241], v[34:35]
	v_pk_mul_f32 v[36:37], v[242:243], v[36:37]
	v_pk_mul_f32 v[38:39], v[244:245], v[38:39]
	v_pk_mul_f32 v[52:53], v[246:247], v[52:53]
	v_cvt_pk_bf16_f32 v138, v34, v35
	v_cvt_pk_bf16_f32 v139, v36, v37
	v_cvt_pk_bf16_f32 v140, v38, v39
	v_cvt_pk_bf16_f32 v141, v52, v53
	global_store_dwordx4 v2, v[138:141], s[44:45]
	s_add_u32 s44, s44, 0x2000
	s_addc_u32 s45, s45, 0
	s_waitcnt vmcnt(17)
; __device__ __forceinline__ float bflo(unsigned u) { return __uint_as_float(u << 16); }
; __device__ __forceinline__ float bfhi(unsigned u) { return __uint_as_float(u & 0xffff0000u); }
; DI float bflo(unsigned u) { return __uint_as_float(u << 16); }
; DI float bfhi(unsigned u) { return __uint_as_float(u & 0xffff0000u); }
; DI void fox_prep_unit(const Params& P, int n, unsigned char* lds, int tid) {
;     ...
;         for (int i = 0; i < 8; ++i) { raw[i] = *(const u32x4*)(ptr + 8 * i);
;             const float a0 = bflo(raw[i].x), a1 = bfhi(raw[i].x), a2 = bflo(raw[i].y), a3 = bfhi(raw[i].y), a4 = bflo(raw[i].z), a5 = bfhi(raw[i].z), a6 = bflo(raw[i].w), a7 = bfhi(raw[i].w);
;             ss += (a0 * a0 + a1 * a1) + (a2 * a2 + a3 * a3) + (a4 * a4 + a5 * a5) + (a6 * a6 + a7 * a7); }
	v_lshlrev_b32_e32 v34, 16, v88
	v_and_b32_e32 v35, 0xffff0000, v88
	v_lshlrev_b32_e32 v36, 16, v89
	v_and_b32_e32 v37, 0xffff0000, v89
	v_lshlrev_b32_e32 v38, 16, v90
	v_and_b32_e32 v39, 0xffff0000, v90
	v_lshlrev_b32_e32 v52, 16, v91
	v_and_b32_e32 v53, 0xffff0000, v91
	v_mul_f32_e32 v248, v34, v34
	v_fmac_f32_e32 v248, v35, v35
	v_fmac_f32_e32 v248, v36, v36
	v_fmac_f32_e32 v248, v37, v37
	v_fmac_f32_e32 v248, v38, v38
	v_fmac_f32_e32 v248, v39, v39
	v_fmac_f32_e32 v248, v52, v52
	v_fmac_f32_e32 v248, v53, v53
	s_waitcnt vmcnt(16)
	v_lshlrev_b32_e32 v34, 16, v92
	v_and_b32_e32 v35, 0xffff0000, v92
	v_lshlrev_b32_e32 v36, 16, v93
	v_and_b32_e32 v37, 0xffff0000, v93
	v_lshlrev_b32_e32 v38, 16, v94
	v_and_b32_e32 v39, 0xffff0000, v94
	v_lshlrev_b32_e32 v52, 16, v95
	v_and_b32_e32 v53, 0xffff0000, v95
	v_mul_f32_e32 v249, v34, v34
	v_fmac_f32_e32 v249, v35, v35
	v_fmac_f32_e32 v249, v36, v36
	v_fmac_f32_e32 v249, v37, v37
	v_fmac_f32_e32 v249, v38, v38
	v_fmac_f32_e32 v249, v39, v39
	v_fmac_f32_e32 v249, v52, v52
	v_fmac_f32_e32 v249, v53, v53
	s_waitcnt vmcnt(15)
	v_lshlrev_b32_e32 v34, 16, v96
	v_and_b32_e32 v35, 0xffff0000, v96
	v_lshlrev_b32_e32 v36, 16, v97
	v_and_b32_e32 v37, 0xffff0000, v97
	v_lshlrev_b32_e32 v38, 16, v98
	v_and_b32_e32 v39, 0xffff0000, v98
	v_lshlrev_b32_e32 v52, 16, v99
	v_and_b32_e32 v53, 0xffff0000, v99
	v_mul_f32_e32 v250, v34, v34
	v_fmac_f32_e32 v250, v35, v35
	v_fmac_f32_e32 v250, v36, v36
	v_fmac_f32_e32 v250, v37, v37
	v_fmac_f32_e32 v250, v38, v38
	v_fmac_f32_e32 v250, v39, v39
	v_fmac_f32_e32 v250, v52, v52
	v_fmac_f32_e32 v250, v53, v53
	s_waitcnt vmcnt(14)
	v_lshlrev_b32_e32 v34, 16, v100
	v_and_b32_e32 v35, 0xffff0000, v100
	v_lshlrev_b32_e32 v36, 16, v101
	v_and_b32_e32 v37, 0xffff0000, v101
	v_lshlrev_b32_e32 v38, 16, v102
	v_and_b32_e32 v39, 0xffff0000, v102
	v_lshlrev_b32_e32 v52, 16, v103
	v_and_b32_e32 v53, 0xffff0000, v103
	v_mul_f32_e32 v251, v34, v34
	v_fmac_f32_e32 v251, v35, v35
	v_fmac_f32_e32 v251, v36, v36
	v_fmac_f32_e32 v251, v37, v37
	v_fmac_f32_e32 v251, v38, v38
	v_fmac_f32_e32 v251, v39, v39
	v_fmac_f32_e32 v251, v52, v52
	v_fmac_f32_e32 v251, v53, v53
	s_waitcnt vmcnt(13)
	v_lshlrev_b32_e32 v34, 16, v44
	v_and_b32_e32 v35, 0xffff0000, v44
	v_lshlrev_b32_e32 v36, 16, v45
	v_and_b32_e32 v37, 0xffff0000, v45
	v_lshlrev_b32_e32 v38, 16, v46
	v_and_b32_e32 v39, 0xffff0000, v46
	v_lshlrev_b32_e32 v52, 16, v47
	v_and_b32_e32 v53, 0xffff0000, v47
	v_mul_f32_e32 v252, v34, v34
	v_fmac_f32_e32 v252, v35, v35
	v_fmac_f32_e32 v252, v36, v36
	v_fmac_f32_e32 v252, v37, v37
	v_fmac_f32_e32 v252, v38, v38
	v_fmac_f32_e32 v252, v39, v39
	v_fmac_f32_e32 v252, v52, v52
	v_fmac_f32_e32 v252, v53, v53
	s_waitcnt vmcnt(12)
	v_lshlrev_b32_e32 v34, 16, v48
	v_and_b32_e32 v35, 0xffff0000, v48
	v_lshlrev_b32_e32 v36, 16, v49
	v_and_b32_e32 v37, 0xffff0000, v49
	v_lshlrev_b32_e32 v38, 16, v50
	v_and_b32_e32 v39, 0xffff0000, v50
	v_lshlrev_b32_e32 v52, 16, v51
	v_and_b32_e32 v53, 0xffff0000, v51
	v_mul_f32_e32 v253, v34, v34
	v_fmac_f32_e32 v253, v35, v35
	v_fmac_f32_e32 v253, v36, v36
	v_fmac_f32_e32 v253, v37, v37
	v_fmac_f32_e32 v253, v38, v38
	v_fmac_f32_e32 v253, v39, v39
	v_fmac_f32_e32 v253, v52, v52
	v_fmac_f32_e32 v253, v53, v53
	s_waitcnt vmcnt(11)
	v_lshlrev_b32_e32 v34, 16, v4
	v_and_b32_e32 v35, 0xffff0000, v4
	v_lshlrev_b32_e32 v36, 16, v5
	v_and_b32_e32 v37, 0xffff0000, v5
	v_lshlrev_b32_e32 v38, 16, v6
	v_and_b32_e32 v39, 0xffff0000, v6
	v_lshlrev_b32_e32 v52, 16, v7
	v_and_b32_e32 v53, 0xffff0000, v7
	v_mul_f32_e32 v254, v34, v34
	v_fmac_f32_e32 v254, v35, v35
	v_fmac_f32_e32 v254, v36, v36
	v_fmac_f32_e32 v254, v37, v37
	v_fmac_f32_e32 v254, v38, v38
	v_fmac_f32_e32 v254, v39, v39
	v_fmac_f32_e32 v254, v52, v52
	v_fmac_f32_e32 v254, v53, v53
	s_waitcnt vmcnt(10)
	v_lshlrev_b32_e32 v34, 16, v8
	v_and_b32_e32 v35, 0xffff0000, v8
	v_lshlrev_b32_e32 v36, 16, v9
	v_and_b32_e32 v37, 0xffff0000, v9
	v_lshlrev_b32_e32 v38, 16, v10
	v_and_b32_e32 v39, 0xffff0000, v10
	v_lshlrev_b32_e32 v52, 16, v11
	v_and_b32_e32 v53, 0xffff0000, v11
	v_mul_f32_e32 v255, v34, v34
	v_fmac_f32_e32 v255, v35, v35
	v_fmac_f32_e32 v255, v36, v36
	v_fmac_f32_e32 v255, v37, v37
	v_fmac_f32_e32 v255, v38, v38
	v_fmac_f32_e32 v255, v39, v39
	v_fmac_f32_e32 v255, v52, v52
	v_fmac_f32_e32 v255, v53, v53
	v_add_f32_dpp v248, v248, v248 quad_perm:[1,0,3,2] row_mask:0xf bank_mask:0xf bound_ctrl:1
	v_add_f32_dpp v249, v249, v249 quad_perm:[1,0,3,2] row_mask:0xf bank_mask:0xf bound_ctrl:1
	v_add_f32_dpp v250, v250, v250 quad_perm:[1,0,3,2] row_mask:0xf bank_mask:0xf bound_ctrl:1
	v_add_f32_dpp v251, v251, v251 quad_perm:[1,0,3,2] row_mask:0xf bank_mask:0xf bound_ctrl:1
	v_add_f32_dpp v252, v252, v252 quad_perm:[1,0,3,2] row_mask:0xf bank_mask:0xf bound_ctrl:1
	v_add_f32_dpp v253, v253, v253 quad_perm:[1,0,3,2] row_mask:0xf bank_mask:0xf bound_ctrl:1
	v_add_f32_dpp v254, v254, v254 quad_perm:[1,0,3,2] row_mask:0xf bank_mask:0xf bound_ctrl:1
	v_add_f32_dpp v255, v255, v255 quad_perm:[1,0,3,2] row_mask:0xf bank_mask:0xf bound_ctrl:1
	v_add_f32_dpp v248, v248, v248 quad_perm:[2,3,0,1] row_mask:0xf bank_mask:0xf bound_ctrl:1
	v_add_f32_dpp v249, v249, v249 quad_perm:[2,3,0,1] row_mask:0xf bank_mask:0xf bound_ctrl:1
	v_add_f32_dpp v250, v250, v250 quad_perm:[2,3,0,1] row_mask:0xf bank_mask:0xf bound_ctrl:1
	v_add_f32_dpp v251, v251, v251 quad_perm:[2,3,0,1] row_mask:0xf bank_mask:0xf bound_ctrl:1
	v_add_f32_dpp v252, v252, v252 quad_perm:[2,3,0,1] row_mask:0xf bank_mask:0xf bound_ctrl:1
	v_add_f32_dpp v253, v253, v253 quad_perm:[2,3,0,1] row_mask:0xf bank_mask:0xf bound_ctrl:1
	v_add_f32_dpp v254, v254, v254 quad_perm:[2,3,0,1] row_mask:0xf bank_mask:0xf bound_ctrl:1
; __device__ __forceinline__ float bflo(unsigned u) { return __uint_as_float(u << 16); }
; __device__ __forceinline__ float bfhi(unsigned u) { return __uint_as_float(u & 0xffff0000u); }
; DI float bflo(unsigned u) { return __uint_as_float(u << 16); }
; DI float bfhi(unsigned u) { return __uint_as_float(u & 0xffff0000u); }
; DI unsigned pk2(float lo, float hi) { f32x2_t v = {lo, hi}; bf16x2_t b = __builtin_convertvector(v, bf16x2_t); return __builtin_bit_cast(unsigned, b); }
; DI void fox_prep_unit(const Params& P, int n, unsigned char* lds, int tid) {
;     ...
;         const float rstd = rsqrtf(ss * (1.f / 64.f) + EPS) * sc;
; #pragma unroll
;         for (int i = 0; i < 8; ++i) { const f32x4 w0 = *(const f32x4*)(nw + 8 * i), w1 = *(const f32x4*)(nw + 8 * i + 4); u32x4 o;
;             o.x = pk2(bflo(raw[i].x) * rstd * w0.x, bfhi(raw[i].x) * rstd * w0.y); o.y = pk2(bflo(raw[i].y) * rstd * w0.z, bfhi(raw[i].y) * rstd * w0.w);
;             o.z = pk2(bflo(raw[i].z) * rstd * w1.x, bfhi(raw[i].z) * rstd * w1.y); o.w = pk2(bflo(raw[i].w) * rstd * w1.z, bfhi(raw[i].w) * rstd * w1.w);
;             *(u32x4*)(ptr + 8 * i) = o; }
	v_add_f32_dpp v255, v255, v255 quad_perm:[2,3,0,1] row_mask:0xf bank_mask:0xf bound_ctrl:1
	v_add_f32_dpp v248, v248, v248 row_half_mirror row_mask:0xf bank_mask:0xf bound_ctrl:1
	v_add_f32_dpp v249, v249, v249 row_half_mirror row_mask:0xf bank_mask:0xf bound_ctrl:1
	v_add_f32_dpp v250, v250, v250 row_half_mirror row_mask:0xf bank_mask:0xf bound_ctrl:1
	v_add_f32_dpp v251, v251, v251 row_half_mirror row_mask:0xf bank_mask:0xf bound_ctrl:1
	v_add_f32_dpp v252, v252, v252 row_half_mirror row_mask:0xf bank_mask:0xf bound_ctrl:1
	v_add_f32_dpp v253, v253, v253 row_half_mirror row_mask:0xf bank_mask:0xf bound_ctrl:1
	v_add_f32_dpp v254, v254, v254 row_half_mirror row_mask:0xf bank_mask:0xf bound_ctrl:1
	v_add_f32_dpp v255, v255, v255 row_half_mirror row_mask:0xf bank_mask:0xf bound_ctrl:1
	v_mov_b32_e32 v12, 0x358637bd
	v_fmamk_f32 v248, v248, 0x3c800000, v12
	v_fmamk_f32 v249, v249, 0x3c800000, v12
	v_fmamk_f32 v250, v250, 0x3c800000, v12
	v_fmamk_f32 v251, v251, 0x3c800000, v12
	v_fmamk_f32 v252, v252, 0x3c800000, v12
	v_fmamk_f32 v253, v253, 0x3c800000, v12
	v_fmamk_f32 v254, v254, 0x3c800000, v12
	v_fmamk_f32 v255, v255, 0x3c800000, v12
	v_rsq_f32_e32 v248, v248
	v_rsq_f32_e32 v249, v249
	v_rsq_f32_e32 v250, v250
	v_rsq_f32_e32 v251, v251
	v_rsq_f32_e32 v252, v252
	v_rsq_f32_e32 v253, v253
	v_rsq_f32_e32 v254, v254
	v_rsq_f32_e32 v255, v255
	s_nop 0
	s_waitcnt vmcnt(6)
	v_lshlrev_b32_e32 v34, 16, v88
	v_and_b32_e32 v35, 0xffff0000, v88
	v_lshlrev_b32_e32 v36, 16, v89
	v_and_b32_e32 v37, 0xffff0000, v89
	v_lshlrev_b32_e32 v38, 16, v90
	v_and_b32_e32 v39, 0xffff0000, v90
	v_lshlrev_b32_e32 v52, 16, v91
	v_and_b32_e32 v53, 0xffff0000, v91
	v_pk_mul_f32 v[34:35], v[248:249], v[34:35] op_sel_hi:[0,1]
	v_pk_mul_f32 v[36:37], v[248:249], v[36:37] op_sel_hi:[0,1]
	v_pk_mul_f32 v[38:39], v[248:249], v[38:39] op_sel_hi:[0,1]
	v_pk_mul_f32 v[52:53], v[248:249], v[52:53] op_sel_hi:[0,1]
	v_pk_mul_f32 v[34:35], v[110:111], v[34:35]
	v_pk_mul_f32 v[36:37], v[112:113], v[36:37]
	v_pk_mul_f32 v[38:39], v[114:115], v[38:39]
	v_pk_mul_f32 v[52:53], v[116:117], v[52:53]
	v_cvt_pk_bf16_f32 v88, v34, v35
	v_cvt_pk_bf16_f32 v89, v36, v37
	v_cvt_pk_bf16_f32 v90, v38, v39
	v_cvt_pk_bf16_f32 v91, v52, v53
	global_store_dwordx4 v2, v[88:91], s[46:47]
	s_add_u32 s46, s46, 0x2000
	s_addc_u32 s47, s47, 0
	v_lshlrev_b32_e32 v34, 16, v92
	v_and_b32_e32 v35, 0xffff0000, v92
	v_lshlrev_b32_e32 v36, 16, v93
	v_and_b32_e32 v37, 0xffff0000, v93
	v_lshlrev_b32_e32 v38, 16, v94
	v_and_b32_e32 v39, 0xffff0000, v94
	v_lshlrev_b32_e32 v52, 16, v95
	v_and_b32_e32 v53, 0xffff0000, v95
	v_pk_mul_f32 v[34:35], v[248:249], v[34:35] op_sel:[1,0] op_sel_hi:[1,1]
	v_pk_mul_f32 v[36:37], v[248:249], v[36:37] op_sel:[1,0] op_sel_hi:[1,1]
	v_pk_mul_f32 v[38:39], v[248:249], v[38:39] op_sel:[1,0] op_sel_hi:[1,1]
	v_pk_mul_f32 v[52:53], v[248:249], v[52:53] op_sel:[1,0] op_sel_hi:[1,1]
	v_pk_mul_f32 v[34:35], v[110:111], v[34:35]
	v_pk_mul_f32 v[36:37], v[112:113], v[36:37]
	v_pk_mul_f32 v[38:39], v[114:115], v[38:39]
	v_pk_mul_f32 v[52:53], v[116:117], v[52:53]
	v_cvt_pk_bf16_f32 v92, v34, v35
	v_cvt_pk_bf16_f32 v93, v36, v37
	v_cvt_pk_bf16_f32 v94, v38, v39
	v_cvt_pk_bf16_f32 v95, v52, v53
	global_store_dwordx4 v2, v[92:95], s[46:47]
	s_add_u32 s46, s46, 0x2000
	s_addc_u32 s47, s47, 0
	v_lshlrev_b32_e32 v34, 16, v96
	v_and_b32_e32 v35, 0xffff0000, v96
	v_lshlrev_b32_e32 v36, 16, v97
	v_and_b32_e32 v37, 0xffff0000, v97
	v_lshlrev_b32_e32 v38, 16, v98
	v_and_b32_e32 v39, 0xffff0000, v98
	v_lshlrev_b32_e32 v52, 16, v99
	v_and_b32_e32 v53, 0xffff0000, v99
	v_pk_mul_f32 v[34:35], v[250:251], v[34:35] op_sel_hi:[0,1]
	v_pk_mul_f32 v[36:37], v[250:251], v[36:37] op_sel_hi:[0,1]
	v_pk_mul_f32 v[38:39], v[250:251], v[38:39] op_sel_hi:[0,1]
	v_pk_mul_f32 v[52:53], v[250:251], v[52:53] op_sel_hi:[0,1]
	v_pk_mul_f32 v[34:35], v[110:111], v[34:35]
	v_pk_mul_f32 v[36:37], v[112:113], v[36:37]
	v_pk_mul_f32 v[38:39], v[114:115], v[38:39]
	v_pk_mul_f32 v[52:53], v[116:117], v[52:53]
	v_cvt_pk_bf16_f32 v96, v34, v35
	v_cvt_pk_bf16_f32 v97, v36, v37
	v_cvt_pk_bf16_f32 v98, v38, v39
	v_cvt_pk_bf16_f32 v99, v52, v53
	global_store_dwordx4 v2, v[96:99], s[46:47]
	s_add_u32 s46, s46, 0x2000
	s_addc_u32 s47, s47, 0
	v_lshlrev_b32_e32 v34, 16, v100
	v_and_b32_e32 v35, 0xffff0000, v100
	v_lshlrev_b32_e32 v36, 16, v101
	v_and_b32_e32 v37, 0xffff0000, v101
	v_lshlrev_b32_e32 v38, 16, v102
	v_and_b32_e32 v39, 0xffff0000, v102
	v_lshlrev_b32_e32 v52, 16, v103
	v_and_b32_e32 v53, 0xffff0000, v103
	v_pk_mul_f32 v[34:35], v[250:251], v[34:35] op_sel:[1,0] op_sel_hi:[1,1]
	v_pk_mul_f32 v[36:37], v[250:251], v[36:37] op_sel:[1,0] op_sel_hi:[1,1]
	v_pk_mul_f32 v[38:39], v[250:251], v[38:39] op_sel:[1,0] op_sel_hi:[1,1]
	v_pk_mul_f32 v[52:53], v[250:251], v[52:53] op_sel:[1,0] op_sel_hi:[1,1]
	v_pk_mul_f32 v[34:35], v[110:111], v[34:35]
	v_pk_mul_f32 v[36:37], v[112:113], v[36:37]
	v_pk_mul_f32 v[38:39], v[114:115], v[38:39]
	v_pk_mul_f32 v[52:53], v[116:117], v[52:53]
	v_cvt_pk_bf16_f32 v100, v34, v35
	v_cvt_pk_bf16_f32 v101, v36, v37
	v_cvt_pk_bf16_f32 v102, v38, v39
	v_cvt_pk_bf16_f32 v103, v52, v53
	global_store_dwordx4 v2, v[100:103], s[46:47]
	s_add_u32 s46, s46, 0x2000
	s_addc_u32 s47, s47, 0
	v_lshlrev_b32_e32 v34, 16, v44
	v_and_b32_e32 v35, 0xffff0000, v44
	v_lshlrev_b32_e32 v36, 16, v45
	v_and_b32_e32 v37, 0xffff0000, v45
	v_lshlrev_b32_e32 v38, 16, v46
	v_and_b32_e32 v39, 0xffff0000, v46
	v_lshlrev_b32_e32 v52, 16, v47
	v_and_b32_e32 v53, 0xffff0000, v47
	v_pk_mul_f32 v[34:35], v[252:253], v[34:35] op_sel_hi:[0,1]
	v_pk_mul_f32 v[36:37], v[252:253], v[36:37] op_sel_hi:[0,1]
	v_pk_mul_f32 v[38:39], v[252:253], v[38:39] op_sel_hi:[0,1]
; __device__ __forceinline__ float bflo(unsigned u) { return __uint_as_float(u << 16); }
; __device__ __forceinline__ float bfhi(unsigned u) { return __uint_as_float(u & 0xffff0000u); }
; DI float bflo(unsigned u) { return __uint_as_float(u << 16); }
; DI float bfhi(unsigned u) { return __uint_as_float(u & 0xffff0000u); }
; DI unsigned pk2(float lo, float hi) { f32x2_t v = {lo, hi}; bf16x2_t b = __builtin_convertvector(v, bf16x2_t); return __builtin_bit_cast(unsigned, b); }
; DI void fox_prep_unit(const Params& P, int n, unsigned char* lds, int tid) {
;     ...
;         for (int i = 0; i < 8; ++i) { const f32x4 w0 = *(const f32x4*)(nw + 8 * i), w1 = *(const f32x4*)(nw + 8 * i + 4); u32x4 o;
;             o.x = pk2(bflo(raw[i].x) * rstd * w0.x, bfhi(raw[i].x) * rstd * w0.y); o.y = pk2(bflo(raw[i].y) * rstd * w0.z, bfhi(raw[i].y) * rstd * w0.w);
;             o.z = pk2(bflo(raw[i].z) * rstd * w1.x, bfhi(raw[i].z) * rstd * w1.y); o.w = pk2(bflo(raw[i].w) * rstd * w1.z, bfhi(raw[i].w) * rstd * w1.w);
;             *(u32x4*)(ptr + 8 * i) = o; }
	v_pk_mul_f32 v[52:53], v[252:253], v[52:53] op_sel_hi:[0,1]
	v_pk_mul_f32 v[34:35], v[110:111], v[34:35]
	v_pk_mul_f32 v[36:37], v[112:113], v[36:37]
	v_pk_mul_f32 v[38:39], v[114:115], v[38:39]
	v_pk_mul_f32 v[52:53], v[116:117], v[52:53]
	v_cvt_pk_bf16_f32 v44, v34, v35
	v_cvt_pk_bf16_f32 v45, v36, v37
	v_cvt_pk_bf16_f32 v46, v38, v39
	v_cvt_pk_bf16_f32 v47, v52, v53
	global_store_dwordx4 v2, v[44:47], s[46:47]
	s_add_u32 s46, s46, 0x2000
	s_addc_u32 s47, s47, 0
	v_lshlrev_b32_e32 v34, 16, v48
	v_and_b32_e32 v35, 0xffff0000, v48
	v_lshlrev_b32_e32 v36, 16, v49
	v_and_b32_e32 v37, 0xffff0000, v49
	v_lshlrev_b32_e32 v38, 16, v50
	v_and_b32_e32 v39, 0xffff0000, v50
	v_lshlrev_b32_e32 v52, 16, v51
	v_and_b32_e32 v53, 0xffff0000, v51
	v_pk_mul_f32 v[34:35], v[252:253], v[34:35] op_sel:[1,0] op_sel_hi:[1,1]
	v_pk_mul_f32 v[36:37], v[252:253], v[36:37] op_sel:[1,0] op_sel_hi:[1,1]
	v_pk_mul_f32 v[38:39], v[252:253], v[38:39] op_sel:[1,0] op_sel_hi:[1,1]
	v_pk_mul_f32 v[52:53], v[252:253], v[52:53] op_sel:[1,0] op_sel_hi:[1,1]
	v_pk_mul_f32 v[34:35], v[110:111], v[34:35]
	v_pk_mul_f32 v[36:37], v[112:113], v[36:37]
	v_pk_mul_f32 v[38:39], v[114:115], v[38:39]
	v_pk_mul_f32 v[52:53], v[116:117], v[52:53]
	v_cvt_pk_bf16_f32 v48, v34, v35
	v_cvt_pk_bf16_f32 v49, v36, v37
	v_cvt_pk_bf16_f32 v50, v38, v39
	v_cvt_pk_bf16_f32 v51, v52, v53
	global_store_dwordx4 v2, v[48:51], s[46:47]
	s_add_u32 s46, s46, 0x2000
	s_addc_u32 s47, s47, 0
	v_lshlrev_b32_e32 v34, 16, v4
	v_and_b32_e32 v35, 0xffff0000, v4
	v_lshlrev_b32_e32 v36, 16, v5
	v_and_b32_e32 v37, 0xffff0000, v5
	v_lshlrev_b32_e32 v38, 16, v6
	v_and_b32_e32 v39, 0xffff0000, v6
	v_lshlrev_b32_e32 v52, 16, v7
	v_and_b32_e32 v53, 0xffff0000, v7
	v_pk_mul_f32 v[34:35], v[254:255], v[34:35] op_sel_hi:[0,1]
	v_pk_mul_f32 v[36:37], v[254:255], v[36:37] op_sel_hi:[0,1]
	v_pk_mul_f32 v[38:39], v[254:255], v[38:39] op_sel_hi:[0,1]
	v_pk_mul_f32 v[52:53], v[254:255], v[52:53] op_sel_hi:[0,1]
	v_pk_mul_f32 v[34:35], v[110:111], v[34:35]
	v_pk_mul_f32 v[36:37], v[112:113], v[36:37]
	v_pk_mul_f32 v[38:39], v[114:115], v[38:39]
	v_pk_mul_f32 v[52:53], v[116:117], v[52:53]
	v_cvt_pk_bf16_f32 v4, v34, v35
	v_cvt_pk_bf16_f32 v5, v36, v37
	v_cvt_pk_bf16_f32 v6, v38, v39
	v_cvt_pk_bf16_f32 v7, v52, v53
	global_store_dwordx4 v2, v[4:7], s[46:47]
	s_add_u32 s46, s46, 0x2000
	s_addc_u32 s47, s47, 0
	v_lshlrev_b32_e32 v34, 16, v8
	v_and_b32_e32 v35, 0xffff0000, v8
	v_lshlrev_b32_e32 v36, 16, v9
	v_and_b32_e32 v37, 0xffff0000, v9
	v_lshlrev_b32_e32 v38, 16, v10
	v_and_b32_e32 v39, 0xffff0000, v10
	v_lshlrev_b32_e32 v52, 16, v11
	v_and_b32_e32 v53, 0xffff0000, v11
	v_pk_mul_f32 v[34:35], v[254:255], v[34:35] op_sel:[1,0] op_sel_hi:[1,1]
	v_pk_mul_f32 v[36:37], v[254:255], v[36:37] op_sel:[1,0] op_sel_hi:[1,1]
	v_pk_mul_f32 v[38:39], v[254:255], v[38:39] op_sel:[1,0] op_sel_hi:[1,1]
	v_pk_mul_f32 v[52:53], v[254:255], v[52:53] op_sel:[1,0] op_sel_hi:[1,1]
	v_pk_mul_f32 v[34:35], v[110:111], v[34:35]
	v_pk_mul_f32 v[36:37], v[112:113], v[36:37]
	v_pk_mul_f32 v[38:39], v[114:115], v[38:39]
	v_pk_mul_f32 v[52:53], v[116:117], v[52:53]
	v_cvt_pk_bf16_f32 v8, v34, v35
	v_cvt_pk_bf16_f32 v9, v36, v37
	v_cvt_pk_bf16_f32 v10, v38, v39
	v_cvt_pk_bf16_f32 v11, v52, v53
	global_store_dwordx4 v2, v[8:11], s[46:47]
	s_add_u32 s46, s46, 0x2000
	s_addc_u32 s47, s47, 0
	s_waitcnt vmcnt(30)
; DI float softplusf(float v) { return v > 20.f ? v : __logf(1.0f + __expf(v)); }
; #define LDSFENCE() asm volatile("s_waitcnt lgkmcnt(0)" ::: "memory")
; DI void fox_prep_unit(const Params& P, int n, unsigned char* lds, int tid) {
;     ...
;     { bf16_t* tile = (bf16_t*)(lds + h * 9216);
; #pragma unroll
;       for (int i = 0; i < 8; ++i) { const u32x4 r = *(const u32x4*)(FV + 8 * i);
;           tile[(8 * i + 0) * 72 + t] = (bf16_t)(r.x & 0xffffu); tile[(8 * i + 1) * 72 + t] = (bf16_t)(r.x >> 16);
;           tile[(8 * i + 2) * 72 + t] = (bf16_t)(r.y & 0xffffu); tile[(8 * i + 3) * 72 + t] = (bf16_t)(r.y >> 16);
;           tile[(8 * i + 4) * 72 + t] = (bf16_t)(r.z & 0xffffu); tile[(8 * i + 5) * 72 + t] = (bf16_t)(r.z >> 16);
;           tile[(8 * i + 6) * 72 + t] = (bf16_t)(r.w & 0xffffu); tile[(8 * i + 7) * 72 + t] = (bf16_t)(r.w >> 16); }
;       LDSFENCE();
;       bf16_t* VT = (bf16_t*)(ws + WS_VT) + (size_t)(h * 64) * SEQ + (size_t)n * 64;
; #pragma unroll
;       for (int k = 0; k < 8; ++k) { const int idx = t + 64 * k, d = idx >> 3, c = idx & 7;
;           *(u32x4*)(VT + (size_t)d * SEQ + 8 * c) = *(const u32x4*)(tile + d * 72 + 8 * c); }
;       LDSFENCE(); }
;     { const float f = ((const float*)(ws + WS_SMALL))[(size_t)tok * 32 + 16 + h] + P.in[8][h];
;       float v = -softplusf(-f) * 1.4426950408889634f;
;       v = wave_incl_scan(v);
;       ((float*)(ws + WS_CL))[(size_t)h * SEQ + tok] = v;
;       if (t == 63) ((float*)(ws + WS_CT))[h * 256 + n] = v; }
	s_nop 0
	ds_write_b16 v104, v30
	ds_write_b16_d16_hi v104, v30 offset:144
	ds_write_b16 v104, v31 offset:288
	ds_write_b16_d16_hi v104, v31 offset:432
	ds_write_b16 v104, v32 offset:576
	ds_write_b16_d16_hi v104, v32 offset:720
	ds_write_b16 v104, v33 offset:864
	ds_write_b16_d16_hi v104, v33 offset:1008
	ds_write_b16 v104, v40 offset:1152
	ds_write_b16_d16_hi v104, v40 offset:1296
	ds_write_b16 v104, v41 offset:1440
	ds_write_b16_d16_hi v104, v41 offset:1584
	ds_write_b16 v104, v42 offset:1728
	ds_write_b16_d16_hi v104, v42 offset:1872
	ds_write_b16 v104, v43 offset:2016
	ds_write_b16_d16_hi v104, v43 offset:2160
	ds_write_b16 v104, v54 offset:2304
	ds_write_b16_d16_hi v104, v54 offset:2448
	ds_write_b16 v104, v55 offset:2592
	ds_write_b16_d16_hi v104, v55 offset:2736
	ds_write_b16 v104, v56 offset:2880
	ds_write_b16_d16_hi v104, v56 offset:3024
	ds_write_b16 v104, v57 offset:3168
	ds_write_b16_d16_hi v104, v57 offset:3312
	ds_write_b16 v104, v58 offset:3456
	ds_write_b16_d16_hi v104, v58 offset:3600
	ds_write_b16 v104, v59 offset:3744
	ds_write_b16_d16_hi v104, v59 offset:3888
	ds_write_b16 v104, v60 offset:4032
	ds_write_b16_d16_hi v104, v60 offset:4176
	ds_write_b16 v104, v61 offset:4320
	ds_write_b16_d16_hi v104, v61 offset:4464
	ds_write_b16 v104, v62 offset:4608
	ds_write_b16_d16_hi v104, v62 offset:4752
	ds_write_b16 v104, v63 offset:4896
	ds_write_b16_d16_hi v104, v63 offset:5040
	ds_write_b16 v104, v64 offset:5184
	ds_write_b16_d16_hi v104, v64 offset:5328
	ds_write_b16 v104, v65 offset:5472
	ds_write_b16_d16_hi v104, v65 offset:5616
	ds_write_b16 v104, v66 offset:5760
	ds_write_b16_d16_hi v104, v66 offset:5904
	ds_write_b16 v104, v67 offset:6048
	ds_write_b16_d16_hi v104, v67 offset:6192
	ds_write_b16 v104, v68 offset:6336
	ds_write_b16_d16_hi v104, v68 offset:6480
	ds_write_b16 v104, v69 offset:6624
	ds_write_b16_d16_hi v104, v69 offset:6768
	ds_write_b16 v104, v70 offset:6912
	ds_write_b16_d16_hi v104, v70 offset:7056
	ds_write_b16 v104, v71 offset:7200
	ds_write_b16_d16_hi v104, v71 offset:7344
	ds_write_b16 v104, v72 offset:7488
	ds_write_b16_d16_hi v104, v72 offset:7632
	ds_write_b16 v104, v73 offset:7776
	ds_write_b16_d16_hi v104, v73 offset:7920
	ds_write_b16 v104, v74 offset:8064
	ds_write_b16_d16_hi v104, v74 offset:8208
	ds_write_b16 v104, v75 offset:8352
	ds_write_b16_d16_hi v104, v75 offset:8496
	ds_write_b16 v104, v76 offset:8640
	ds_write_b16_d16_hi v104, v76 offset:8784
	ds_write_b16 v104, v77 offset:8928
	ds_write_b16_d16_hi v104, v77 offset:9072
	v_add_co_u32_e32 v50, vcc, s22, v28
	v_lshlrev_b64 v[88:89], 7, v[26:27]
	s_nop 0
	s_nop 1
	v_addc_co_u32_e32 v51, vcc, 0, v29, vcc
	v_add_co_u32_e32 v52, vcc, s23, v28
	v_lshl_add_u64 v[88:89], v[20:21], 0, v[88:89]
	s_nop 0
	s_nop 1
	v_addc_co_u32_e32 v53, vcc, 0, v29, vcc
	s_waitcnt lgkmcnt(0)
	ds_read_b128 v[2:5], v107
	ds_read_b128 v[6:9], v107 offset:1152
	ds_read_b128 v[10:13], v107 offset:2304
	ds_read_b128 v[30:33], v107 offset:3456
	ds_read_b128 v[34:37], v107 offset:4608
	ds_read_b128 v[38:41], v107 offset:5760
	ds_read_b128 v[42:45], v107 offset:6912
	ds_read_b128 v[46:49], v107 offset:8064
	s_waitcnt lgkmcnt(7)
	global_store_dwordx4 v[28:29], v[2:5], off
	s_waitcnt lgkmcnt(6)
	global_store_dwordx4 v[78:79], v[6:9], off
	s_waitcnt lgkmcnt(5)
	global_store_dwordx4 v[80:81], v[10:13], off
	s_waitcnt lgkmcnt(4)
	global_store_dwordx4 v[82:83], v[30:33], off
	s_waitcnt lgkmcnt(3)
	global_store_dwordx4 v[84:85], v[34:37], off
	s_waitcnt lgkmcnt(2)
	global_store_dwordx4 v[86:87], v[38:41], off
	s_waitcnt lgkmcnt(1)
	global_store_dwordx4 v[50:51], v[42:45], off
	s_waitcnt lgkmcnt(0)
	global_store_dwordx4 v[52:53], v[46:49], off
	s_waitcnt lgkmcnt(0)
	global_load_dword v2, v[88:89], off
	global_load_dword v3, v[22:23], off
	v_mov_b32_e32 v4, 0
	v_mov_b32_e32 v6, 0
	s_waitcnt vmcnt(0)
	v_add_f32_e32 v2, v2, v3
	v_mul_f32_e32 v3, 0xbfb8aa3b, v2
	v_exp_f32_e32 v3, v3
	s_nop 0
	v_add_f32_e32 v3, 1.0, v3
	v_cmp_gt_f32_e32 vcc, s3, v3
	s_nop 1
	v_cndmask_b32_e64 v5, 0, 32, vcc
	v_ldexp_f32 v3, v3, v5
	v_log_f32_e32 v3, v3
	v_cndmask_b32_e32 v7, 0, v108, vcc
	v_mov_b32_e32 v5, 0
	v_mul_f32_e32 v8, 0x3f317217, v3
	v_fma_f32 v8, v3, s25, -v8
	v_fmac_f32_e32 v8, 0x3377d1cf, v3
	v_fmac_f32_e32 v8, 0x3f317217, v3
	v_cmp_lt_f32_e64 vcc, |v3|, s26
	s_nop 1
	v_cndmask_b32_e32 v3, v3, v8, vcc
	v_sub_f32_e32 v3, v3, v7
	v_cmp_gt_f32_e32 vcc, s24, v2
	s_nop 1
	v_cndmask_b32_e64 v2, v3, -v2, vcc
	v_mul_f32_e32 v3, 0xbfb8aa3b, v2
	s_nop 1
	v_mov_b32_dpp v4, v3 row_shr:1 row_mask:0xf bank_mask:0xf
	v_fmac_f32_e32 v4, 0xbfb8aa3b, v2
	s_nop 1
	v_add_f32_dpp v2, v4, v4 row_shr:2 row_mask:0xf bank_mask:0xf bound_ctrl:1
	s_nop 1
	v_add_f32_dpp v2, v2, v2 row_shr:4 row_mask:0xf bank_mask:0xf bound_ctrl:1
	s_nop 1
	v_add_f32_dpp v2, v2, v2 row_shr:8 row_mask:0xf bank_mask:0xf bound_ctrl:1
	s_nop 1
	v_mov_b32_dpp v5, v2 row_bcast:15 row_mask:0xa bank_mask:0xf
	v_add_f32_e32 v2, v2, v5
	v_lshl_add_u64 v[4:5], v[26:27], 2, v[24:25]
	s_nop 0
	v_mov_b32_dpp v6, v2 row_bcast:31 row_mask:0xc bank_mask:0xf
	v_add_f32_e32 v2, v2, v6
	global_store_dword v[4:5], v2, off
	s_and_saveexec_b64 s[14:15], s[8:9]
	s_cbranch_execz .LBB0_590
	v_add_u32_e32 v4, s27, v105
	v_ashrrev_i32_e32 v5, 31, v4
	v_readlane_b32 s30, v239, 3
	v_readlane_b32 s31, v239, 4
	s_nop 0
	v_lshl_add_u64 v[4:5], v[4:5], 2, s[30:31]
	global_store_dword v[4:5], v2, off
	s_branch .LBB0_590

; __device__ __forceinline__ unsigned cvt_pk_bf16(float lo, float hi) { unsigned r; asm volatile("v_cvt_pk_bf16_f32 %0, %1, %2" : "=v"(r) : "v"(lo), "v"(hi)); return r; }
; __device__ __forceinline__ float bflo(unsigned u) { return __uint_as_float(u << 16); }
; __device__ __forceinline__ float bfhi(unsigned u) { return __uint_as_float(u & 0xffff0000u); }
; __device__ __forceinline__ float sigm(float v) { return __builtin_amdgcn_rcpf(1.0f + __expf(-v)); }
; DI float bflo(unsigned u) { return __uint_as_float(u << 16); }
; DI float bfhi(unsigned u) { return __uint_as_float(u & 0xffff0000u); }
;     __device__ __forceinline__ void operator()(const f32x4 (&acc)[2][2][4][2], const Unit& u, int wr, int wc, int fr, int fq) const {
;     ...
;         for (int bj = 0; bj < 2; ++bj) {
;             const f32x4 b0 = *(const f32x4*)(gb + col0 + bj * HALF), b1 = *(const f32x4*)(gb + col0 + bj * HALF + 4);
; #pragma unroll
;             for (int ai = 0; ai < 2; ++ai)
; #pragma unroll
;                 for (int m = 0; m < 4; ++m) { const size_t row = (size_t)(row0 + ai * HALF + m * 16);
;                     const u32x4 g = *(const u32x4*)(gbase + row * 512 + gcol0 + bj * HALF);
;                     const f32x4 v0 = acc[ai][bj][m][0], v1 = acc[ai][bj][m][1];
;                     float r0 = v0[0] * sigm(bflo(g.x) + b0[0]), r1 = v0[1] * sigm(bfhi(g.x) + b0[1]), r2 = v0[2] * sigm(bflo(g.y) + b0[2]), r3 = v0[3] * sigm(bfhi(g.y) + b0[3]);
;                     float r4 = v1[0] * sigm(bflo(g.z) + b1[0]), r5 = v1[1] * sigm(bfhi(g.z) + b1[1]), r6 = v1[2] * sigm(bflo(g.w) + b1[2]), r7 = v1[3] * sigm(bfhi(g.w) + b1[3]);
;                     bf16_t* op = Mo + row * 1024 + col0 + bj * HALF;
;                     if (accum) { const u32x4 p = *(const u32x4*)op; r0 += bflo(p.x); r1 += bfhi(p.x); r2 += bflo(p.y); r3 += bfhi(p.y); r4 += bflo(p.z); r5 += bfhi(p.z); r6 += bflo(p.w); r7 += bfhi(p.w); }
;                     u32x4 w; w.x = cvt_pk_bf16(r0, r1); w.y = cvt_pk_bf16(r2, r3); w.z = cvt_pk_bf16(r4, r5); w.w = cvt_pk_bf16(r6, r7);
;                     *(u32x4*)op = w; }
.LBB0_880:
	s_lshr_b32 s2, s44, 31
	s_add_i32 s2, s44, s2
	s_ashr_i32 s24, s2, 1
	s_ashr_i32 s25, s24, 31
	s_lshl_b64 s[26:27], s[24:25], 24
	s_add_u32 s26, s36, s26
	s_addc_u32 s27, s37, s27
	v_lshl_or_b32 v154, s44, 8, v172
	s_lshl_b32 s2, s24, 9
	v_lshl_add_u32 v168, s22, 8, v1
	v_subrev_u32_e32 v114, s2, v154
	v_ashrrev_i32_e32 v115, 31, v114
	v_ashrrev_i32_e32 v169, 31, v168
	v_lshl_add_u64 v[170:171], v[114:115], 1, s[26:27]
	v_lshlrev_b64 v[114:115], 10, v[168:169]
	v_lshl_add_u64 v[158:159], v[170:171], 0, v[114:115]
	v_ashrrev_i32_e32 v155, 31, v154
	global_load_dwordx4 v[176:179], v[158:159], off
	v_lshl_add_u64 v[160:161], v[154:155], 2, s[78:79]
	global_load_dwordx4 v[118:121], v[160:161], off
	global_load_dwordx4 v[114:117], v[160:161], off offset:16
	v_lshlrev_b64 v[156:157], 11, v[168:169]
	v_or_b32_e32 v180, 16, v168
	v_lshlrev_b64 v[166:167], 1, v[154:155]
	v_ashrrev_i32_e32 v181, 31, v180
	v_lshl_add_u64 v[154:155], s[10:11], 0, v[156:157]
	v_lshlrev_b64 v[156:157], 10, v[180:181]
	v_lshl_add_u64 v[154:155], v[154:155], 0, v[166:167]
	v_lshl_add_u64 v[156:157], v[170:171], 0, v[156:157]
	s_andn2_b64 vcc, exec, s[6:7]
	s_mov_b64 s[6:7], -1
	v_mov_b32_e32 v250, v158
	v_mov_b32_e32 v251, v159
	s_mov_b64 s[98:99], 0x4000
	v_lshl_add_u64 v[248:249], v[250:251], 0, s[98:99]
	global_load_dwordx4 v[204:207], v[248:249], off
	s_mov_b64 s[98:99], 0x8000
	v_lshl_add_u64 v[248:249], v[250:251], 0, s[98:99]
	global_load_dwordx4 v[208:211], v[248:249], off
	s_mov_b64 s[98:99], 0xc000
	v_lshl_add_u64 v[248:249], v[250:251], 0, s[98:99]
	global_load_dwordx4 v[212:215], v[248:249], off
	s_mov_b64 s[98:99], 0x20000
	v_lshl_add_u64 v[248:249], v[250:251], 0, s[98:99]
	global_load_dwordx4 v[216:219], v[248:249], off
	s_mov_b64 s[98:99], 0x24000
	v_lshl_add_u64 v[248:249], v[250:251], 0, s[98:99]
	global_load_dwordx4 v[220:223], v[248:249], off
	s_mov_b64 s[98:99], 0x28000
	v_lshl_add_u64 v[248:249], v[250:251], 0, s[98:99]
	global_load_dwordx4 v[224:227], v[248:249], off
	global_load_dwordx4 v[240:243], v[160:161], off offset:512
	global_load_dwordx4 v[244:247], v[160:161], off offset:528
	s_waitcnt vmcnt(8)
	v_lshlrev_b32_e32 v184, 16, v179
	v_and_b32_e32 v179, 0xffff0000, v179
	v_lshlrev_b32_e32 v169, 16, v176
	v_and_b32_e32 v176, 0xffff0000, v176
	v_lshlrev_b32_e32 v182, 16, v177
	v_and_b32_e32 v177, 0xffff0000, v177
	v_lshlrev_b32_e32 v183, 16, v178
	v_and_b32_e32 v178, 0xffff0000, v178
	v_add_f32_e32 v179, v117, v179
	v_add_f32_e32 v169, v118, v169
	v_add_f32_e32 v176, v119, v176
	v_add_f32_e32 v182, v120, v182
	v_add_f32_e32 v177, v121, v177
	v_add_f32_e32 v183, v114, v183
	v_add_f32_e32 v178, v115, v178
	v_add_f32_e32 v184, v116, v184
	v_mul_f32_e32 v179, 0xbfb8aa3b, v179
	v_mul_f32_e32 v169, 0xbfb8aa3b, v169
	v_mul_f32_e32 v176, 0xbfb8aa3b, v176
	v_mul_f32_e32 v182, 0xbfb8aa3b, v182
	v_mul_f32_e32 v177, 0xbfb8aa3b, v177
	v_mul_f32_e32 v183, 0xbfb8aa3b, v183
	v_mul_f32_e32 v178, 0xbfb8aa3b, v178
	v_mul_f32_e32 v184, 0xbfb8aa3b, v184
	v_exp_f32_e32 v179, v179
	v_exp_f32_e32 v169, v169
	v_exp_f32_e32 v176, v176
	v_exp_f32_e32 v182, v182
	v_exp_f32_e32 v177, v177
	v_exp_f32_e32 v183, v183
	v_exp_f32_e32 v178, v178
	v_exp_f32_e32 v184, v184
	v_add_f32_e32 v179, 1.0, v179
	v_add_f32_e32 v169, 1.0, v169
	v_add_f32_e32 v176, 1.0, v176
	v_add_f32_e32 v182, 1.0, v182
	v_add_f32_e32 v177, 1.0, v177
	v_add_f32_e32 v183, 1.0, v183
	v_add_f32_e32 v178, 1.0, v178
	v_add_f32_e32 v184, 1.0, v184
	v_rcp_f32_e32 v179, v179
	v_rcp_f32_e32 v169, v169
	v_rcp_f32_e32 v176, v176
	v_rcp_f32_e32 v182, v182
	v_rcp_f32_e32 v177, v177
	v_rcp_f32_e32 v183, v183
	v_rcp_f32_e32 v178, v178
	v_rcp_f32_e32 v184, v184
	v_mul_f32_e32 v133, v133, v179
	v_mul_f32_e32 v134, v134, v169
	v_mul_f32_e32 v135, v135, v176
	v_mul_f32_e32 v136, v136, v182
	v_mul_f32_e32 v137, v137, v177
	v_mul_f32_e32 v169, v130, v183
	v_mul_f32_e32 v176, v131, v178
	v_mul_f32_e32 v177, v132, v184
	v_cvt_pk_bf16_f32 v130, v134, v135
	v_cvt_pk_bf16_f32 v131, v136, v137
	v_cvt_pk_bf16_f32 v132, v169, v176
	v_cvt_pk_bf16_f32 v133, v177, v133
	global_store_dwordx4 v[154:155], v[130:133], off
	s_nop 0
	v_or_b32_e32 v176, 32, v168
	v_lshlrev_b64 v[130:131], 11, v[180:181]
	v_ashrrev_i32_e32 v177, 31, v176
	v_lshl_add_u64 v[130:131], s[10:11], 0, v[130:131]
	v_lshlrev_b64 v[132:133], 10, v[176:177]
	v_lshl_add_u64 v[130:131], v[130:131], 0, v[166:167]
	v_lshl_add_u64 v[132:133], v[170:171], 0, v[132:133]
	s_waitcnt vmcnt(8)
; __device__ __forceinline__ unsigned cvt_pk_bf16(float lo, float hi) { unsigned r; asm volatile("v_cvt_pk_bf16_f32 %0, %1, %2" : "=v"(r) : "v"(lo), "v"(hi)); return r; }
; __device__ __forceinline__ float bflo(unsigned u) { return __uint_as_float(u << 16); }
; __device__ __forceinline__ float bfhi(unsigned u) { return __uint_as_float(u & 0xffff0000u); }
; __device__ __forceinline__ float sigm(float v) { return __builtin_amdgcn_rcpf(1.0f + __expf(-v)); }
; DI float bflo(unsigned u) { return __uint_as_float(u << 16); }
; DI float bfhi(unsigned u) { return __uint_as_float(u & 0xffff0000u); }
;     __device__ __forceinline__ void operator()(const f32x4 (&acc)[2][2][4][2], const Unit& u, int wr, int wc, int fr, int fq) const {
;     ...
;                 for (int m = 0; m < 4; ++m) { const size_t row = (size_t)(row0 + ai * HALF + m * 16);
;                     const u32x4 g = *(const u32x4*)(gbase + row * 512 + gcol0 + bj * HALF);
;                     const f32x4 v0 = acc[ai][bj][m][0], v1 = acc[ai][bj][m][1];
;                     float r0 = v0[0] * sigm(bflo(g.x) + b0[0]), r1 = v0[1] * sigm(bfhi(g.x) + b0[1]), r2 = v0[2] * sigm(bflo(g.y) + b0[2]), r3 = v0[3] * sigm(bfhi(g.y) + b0[3]);
;                     float r4 = v1[0] * sigm(bflo(g.z) + b1[0]), r5 = v1[1] * sigm(bfhi(g.z) + b1[1]), r6 = v1[2] * sigm(bflo(g.w) + b1[2]), r7 = v1[3] * sigm(bfhi(g.w) + b1[3]);
;                     bf16_t* op = Mo + row * 1024 + col0 + bj * HALF;
;                     if (accum) { const u32x4 p = *(const u32x4*)op; r0 += bflo(p.x); r1 += bfhi(p.x); r2 += bflo(p.y); r3 += bfhi(p.y); r4 += bflo(p.z); r5 += bfhi(p.z); r6 += bflo(p.w); r7 += bfhi(p.w); }
;                     u32x4 w; w.x = cvt_pk_bf16(r0, r1); w.y = cvt_pk_bf16(r2, r3); w.z = cvt_pk_bf16(r4, r5); w.w = cvt_pk_bf16(r6, r7);
;                     *(u32x4*)op = w; }
	v_lshlrev_b32_e32 v180, 16, v207
	v_and_b32_e32 v137, 0xffff0000, v207
	v_lshlrev_b32_e32 v169, 16, v204
	v_and_b32_e32 v134, 0xffff0000, v204
	v_lshlrev_b32_e32 v178, 16, v205
	v_and_b32_e32 v135, 0xffff0000, v205
	v_lshlrev_b32_e32 v179, 16, v206
	v_and_b32_e32 v136, 0xffff0000, v206
	s_mov_b64 s[98:99], 0x2c000
	v_lshl_add_u64 v[248:249], v[250:251], 0, s[98:99]
	global_load_dwordx4 v[204:207], v[248:249], off
	v_add_f32_e32 v137, v117, v137
	v_add_f32_e32 v169, v118, v169
	v_add_f32_e32 v134, v119, v134
	v_add_f32_e32 v178, v120, v178
	v_add_f32_e32 v135, v121, v135
	v_add_f32_e32 v179, v114, v179
	v_add_f32_e32 v136, v115, v136
	v_add_f32_e32 v180, v116, v180
	v_mul_f32_e32 v137, 0xbfb8aa3b, v137
	v_mul_f32_e32 v169, 0xbfb8aa3b, v169
	v_mul_f32_e32 v134, 0xbfb8aa3b, v134
	v_mul_f32_e32 v178, 0xbfb8aa3b, v178
	v_mul_f32_e32 v135, 0xbfb8aa3b, v135
	v_mul_f32_e32 v179, 0xbfb8aa3b, v179
	v_mul_f32_e32 v136, 0xbfb8aa3b, v136
	v_mul_f32_e32 v180, 0xbfb8aa3b, v180
	v_exp_f32_e32 v137, v137
	v_exp_f32_e32 v169, v169
	v_exp_f32_e32 v134, v134
	v_exp_f32_e32 v178, v178
	v_exp_f32_e32 v135, v135
	v_exp_f32_e32 v179, v179
	v_exp_f32_e32 v136, v136
	v_exp_f32_e32 v180, v180
	v_add_f32_e32 v137, 1.0, v137
	v_add_f32_e32 v169, 1.0, v169
	v_add_f32_e32 v134, 1.0, v134
	v_add_f32_e32 v178, 1.0, v178
	v_add_f32_e32 v135, 1.0, v135
	v_add_f32_e32 v179, 1.0, v179
	v_add_f32_e32 v136, 1.0, v136
	v_add_f32_e32 v180, 1.0, v180
	v_rcp_f32_e32 v137, v137
	v_rcp_f32_e32 v169, v169
	v_rcp_f32_e32 v134, v134
	v_rcp_f32_e32 v178, v178
	v_rcp_f32_e32 v135, v135
	v_rcp_f32_e32 v179, v179
	v_rcp_f32_e32 v136, v136
	v_rcp_f32_e32 v180, v180
	v_mul_f32_e32 v125, v125, v137
	v_mul_f32_e32 v126, v126, v169
	v_mul_f32_e32 v127, v127, v134
	v_mul_f32_e32 v128, v128, v178
	v_mul_f32_e32 v129, v129, v135
	v_mul_f32_e32 v134, v122, v179
	v_mul_f32_e32 v135, v123, v136
	v_mul_f32_e32 v136, v124, v180
	v_cvt_pk_bf16_f32 v122, v126, v127
	v_cvt_pk_bf16_f32 v123, v128, v129
	v_cvt_pk_bf16_f32 v124, v134, v135
	v_cvt_pk_bf16_f32 v125, v136, v125
	global_store_dwordx4 v[130:131], v[122:125], off
	s_nop 0
	v_or_b32_e32 v134, 48, v168
	v_lshlrev_b64 v[122:123], 11, v[176:177]
	v_ashrrev_i32_e32 v135, 31, v134
	v_lshl_add_u64 v[122:123], s[10:11], 0, v[122:123]
	v_lshlrev_b64 v[124:125], 10, v[134:135]
	v_lshl_add_u64 v[122:123], v[122:123], 0, v[166:167]
	v_lshl_add_u64 v[124:125], v[170:171], 0, v[124:125]
	s_waitcnt vmcnt(9)
	v_lshlrev_b32_e32 v176, 16, v211
	v_and_b32_e32 v129, 0xffff0000, v211
	v_lshlrev_b32_e32 v136, 16, v208
	v_and_b32_e32 v126, 0xffff0000, v208
	v_lshlrev_b32_e32 v137, 16, v209
	v_and_b32_e32 v127, 0xffff0000, v209
	v_lshlrev_b32_e32 v169, 16, v210
	v_and_b32_e32 v128, 0xffff0000, v210
	global_load_dwordx4 v[208:211], v[250:251], off offset:256
	v_add_f32_e32 v129, v117, v129
	v_add_f32_e32 v136, v118, v136
	v_add_f32_e32 v126, v119, v126
	v_add_f32_e32 v137, v120, v137
	v_add_f32_e32 v127, v121, v127
	v_add_f32_e32 v169, v114, v169
	v_add_f32_e32 v128, v115, v128
	v_add_f32_e32 v176, v116, v176
	v_mul_f32_e32 v129, 0xbfb8aa3b, v129
	v_mul_f32_e32 v136, 0xbfb8aa3b, v136
	v_mul_f32_e32 v126, 0xbfb8aa3b, v126
	v_mul_f32_e32 v137, 0xbfb8aa3b, v137
	v_mul_f32_e32 v127, 0xbfb8aa3b, v127
	v_mul_f32_e32 v169, 0xbfb8aa3b, v169
	v_mul_f32_e32 v128, 0xbfb8aa3b, v128
	v_mul_f32_e32 v176, 0xbfb8aa3b, v176
	v_exp_f32_e32 v129, v129
	v_exp_f32_e32 v136, v136
	v_exp_f32_e32 v126, v126
	v_exp_f32_e32 v137, v137
	v_exp_f32_e32 v127, v127
	v_exp_f32_e32 v169, v169
	v_exp_f32_e32 v128, v128
	v_exp_f32_e32 v176, v176
	v_add_f32_e32 v129, 1.0, v129
	v_add_f32_e32 v136, 1.0, v136
	v_add_f32_e32 v126, 1.0, v126
	v_add_f32_e32 v137, 1.0, v137
	v_add_f32_e32 v127, 1.0, v127
	v_add_f32_e32 v169, 1.0, v169
	v_add_f32_e32 v128, 1.0, v128
	v_add_f32_e32 v176, 1.0, v176
	v_rcp_f32_e32 v129, v129
	v_rcp_f32_e32 v136, v136
	v_rcp_f32_e32 v126, v126
	v_rcp_f32_e32 v137, v137
	v_rcp_f32_e32 v127, v127
	v_rcp_f32_e32 v169, v169
	v_rcp_f32_e32 v128, v128
	v_rcp_f32_e32 v176, v176
	v_mul_f32_e32 v109, v109, v129
	v_mul_f32_e32 v110, v110, v136
	v_mul_f32_e32 v111, v111, v126
	v_mul_f32_e32 v112, v112, v137
	v_mul_f32_e32 v113, v113, v127
	v_mul_f32_e32 v126, v106, v169
	v_mul_f32_e32 v127, v107, v128
	v_mul_f32_e32 v128, v108, v176
	v_cvt_pk_bf16_f32 v106, v110, v111
	v_cvt_pk_bf16_f32 v107, v112, v113
	v_cvt_pk_bf16_f32 v108, v126, v127
	v_cvt_pk_bf16_f32 v109, v128, v109
	global_store_dwordx4 v[122:123], v[106:109], off
	s_nop 0
	v_add_u32_e32 v126, 0x80, v168
	v_lshlrev_b64 v[106:107], 11, v[134:135]
	v_ashrrev_i32_e32 v127, 31, v126
	v_lshl_add_u64 v[106:107], s[10:11], 0, v[106:107]
	v_lshlrev_b64 v[108:109], 10, v[126:127]
	v_lshl_add_u64 v[106:107], v[106:107], 0, v[166:167]
	v_lshl_add_u64 v[108:109], v[170:171], 0, v[108:109]
	s_waitcnt vmcnt(10)
; __device__ __forceinline__ unsigned cvt_pk_bf16(float lo, float hi) { unsigned r; asm volatile("v_cvt_pk_bf16_f32 %0, %1, %2" : "=v"(r) : "v"(lo), "v"(hi)); return r; }
; __device__ __forceinline__ float bflo(unsigned u) { return __uint_as_float(u << 16); }
; __device__ __forceinline__ float bfhi(unsigned u) { return __uint_as_float(u & 0xffff0000u); }
; __device__ __forceinline__ float sigm(float v) { return __builtin_amdgcn_rcpf(1.0f + __expf(-v)); }
; DI float bflo(unsigned u) { return __uint_as_float(u << 16); }
; DI float bfhi(unsigned u) { return __uint_as_float(u & 0xffff0000u); }
;     __device__ __forceinline__ void operator()(const f32x4 (&acc)[2][2][4][2], const Unit& u, int wr, int wc, int fr, int fq) const {
;     ...
;                 for (int m = 0; m < 4; ++m) { const size_t row = (size_t)(row0 + ai * HALF + m * 16);
;                     const u32x4 g = *(const u32x4*)(gbase + row * 512 + gcol0 + bj * HALF);
;                     const f32x4 v0 = acc[ai][bj][m][0], v1 = acc[ai][bj][m][1];
;                     float r0 = v0[0] * sigm(bflo(g.x) + b0[0]), r1 = v0[1] * sigm(bfhi(g.x) + b0[1]), r2 = v0[2] * sigm(bflo(g.y) + b0[2]), r3 = v0[3] * sigm(bfhi(g.y) + b0[3]);
;                     float r4 = v1[0] * sigm(bflo(g.z) + b1[0]), r5 = v1[1] * sigm(bfhi(g.z) + b1[1]), r6 = v1[2] * sigm(bflo(g.w) + b1[2]), r7 = v1[3] * sigm(bfhi(g.w) + b1[3]);
;                     bf16_t* op = Mo + row * 1024 + col0 + bj * HALF;
;                     if (accum) { const u32x4 p = *(const u32x4*)op; r0 += bflo(p.x); r1 += bfhi(p.x); r2 += bflo(p.y); r3 += bfhi(p.y); r4 += bflo(p.z); r5 += bfhi(p.z); r6 += bflo(p.w); r7 += bfhi(p.w); }
;                     u32x4 w; w.x = cvt_pk_bf16(r0, r1); w.y = cvt_pk_bf16(r2, r3); w.z = cvt_pk_bf16(r4, r5); w.w = cvt_pk_bf16(r6, r7);
;                     *(u32x4*)op = w; }
	v_lshlrev_b32_e32 v135, 16, v215
	v_and_b32_e32 v113, 0xffff0000, v215
	v_lshlrev_b32_e32 v128, 16, v212
	v_and_b32_e32 v110, 0xffff0000, v212
	v_lshlrev_b32_e32 v129, 16, v213
	v_and_b32_e32 v111, 0xffff0000, v213
	v_lshlrev_b32_e32 v134, 16, v214
	v_and_b32_e32 v112, 0xffff0000, v214
	s_mov_b64 s[98:99], 0x4000
	v_lshl_add_u64 v[248:249], v[250:251], 0, s[98:99]
	global_load_dwordx4 v[212:215], v[248:249], off offset:256
	v_add_f32_e32 v113, v117, v113
	v_add_f32_e32 v128, v118, v128
	v_add_f32_e32 v110, v119, v110
	v_add_f32_e32 v129, v120, v129
	v_add_f32_e32 v111, v121, v111
	v_add_f32_e32 v134, v114, v134
	v_add_f32_e32 v112, v115, v112
	v_add_f32_e32 v135, v116, v135
	v_mul_f32_e32 v113, 0xbfb8aa3b, v113
	v_mul_f32_e32 v128, 0xbfb8aa3b, v128
	v_mul_f32_e32 v110, 0xbfb8aa3b, v110
	v_mul_f32_e32 v129, 0xbfb8aa3b, v129
	v_mul_f32_e32 v111, 0xbfb8aa3b, v111
	v_mul_f32_e32 v134, 0xbfb8aa3b, v134
	v_mul_f32_e32 v112, 0xbfb8aa3b, v112
	v_mul_f32_e32 v135, 0xbfb8aa3b, v135
	v_exp_f32_e32 v113, v113
	v_exp_f32_e32 v128, v128
	v_exp_f32_e32 v110, v110
	v_exp_f32_e32 v129, v129
	v_exp_f32_e32 v111, v111
	v_exp_f32_e32 v134, v134
	v_exp_f32_e32 v112, v112
	v_exp_f32_e32 v135, v135
	v_add_f32_e32 v113, 1.0, v113
	v_add_f32_e32 v128, 1.0, v128
	v_add_f32_e32 v110, 1.0, v110
	v_add_f32_e32 v129, 1.0, v129
	v_add_f32_e32 v111, 1.0, v111
	v_add_f32_e32 v134, 1.0, v134
	v_add_f32_e32 v112, 1.0, v112
	v_add_f32_e32 v135, 1.0, v135
	v_rcp_f32_e32 v113, v113
	v_rcp_f32_e32 v128, v128
	v_rcp_f32_e32 v110, v110
	v_rcp_f32_e32 v129, v129
	v_rcp_f32_e32 v111, v111
	v_rcp_f32_e32 v134, v134
	v_rcp_f32_e32 v112, v112
	v_rcp_f32_e32 v135, v135
	v_mul_f32_e32 v101, v101, v113
	v_mul_f32_e32 v102, v102, v128
	v_mul_f32_e32 v103, v103, v110
	v_mul_f32_e32 v104, v104, v129
	v_mul_f32_e32 v105, v105, v111
	v_mul_f32_e32 v110, v98, v134
	v_mul_f32_e32 v111, v99, v112
	v_mul_f32_e32 v112, v100, v135
	v_cvt_pk_bf16_f32 v98, v102, v103
	v_cvt_pk_bf16_f32 v99, v104, v105
	v_cvt_pk_bf16_f32 v100, v110, v111
	v_cvt_pk_bf16_f32 v101, v112, v101
	global_store_dwordx4 v[106:107], v[98:101], off
	s_nop 0
	v_add_u32_e32 v110, 0x90, v168
	v_lshlrev_b64 v[98:99], 11, v[126:127]
	v_ashrrev_i32_e32 v111, 31, v110
	v_lshl_add_u64 v[98:99], s[10:11], 0, v[98:99]
	v_lshlrev_b64 v[100:101], 10, v[110:111]
	v_lshl_add_u64 v[98:99], v[98:99], 0, v[166:167]
	v_lshl_add_u64 v[100:101], v[170:171], 0, v[100:101]
	s_waitcnt vmcnt(11)
	v_lshlrev_b32_e32 v127, 16, v219
	v_and_b32_e32 v105, 0xffff0000, v219
	v_lshlrev_b32_e32 v112, 16, v216
	v_and_b32_e32 v102, 0xffff0000, v216
	v_lshlrev_b32_e32 v113, 16, v217
	v_and_b32_e32 v103, 0xffff0000, v217
	v_lshlrev_b32_e32 v126, 16, v218
	v_and_b32_e32 v104, 0xffff0000, v218
	s_mov_b64 s[98:99], 0x8000
	v_lshl_add_u64 v[248:249], v[250:251], 0, s[98:99]
	global_load_dwordx4 v[216:219], v[248:249], off offset:256
	v_add_f32_e32 v105, v117, v105
	v_add_f32_e32 v112, v118, v112
	v_add_f32_e32 v102, v119, v102
	v_add_f32_e32 v113, v120, v113
	v_add_f32_e32 v103, v121, v103
	v_add_f32_e32 v126, v114, v126
	v_add_f32_e32 v104, v115, v104
	v_add_f32_e32 v127, v116, v127
	v_mul_f32_e32 v105, 0xbfb8aa3b, v105
	v_mul_f32_e32 v112, 0xbfb8aa3b, v112
	v_mul_f32_e32 v102, 0xbfb8aa3b, v102
	v_mul_f32_e32 v113, 0xbfb8aa3b, v113
	v_mul_f32_e32 v103, 0xbfb8aa3b, v103
	v_mul_f32_e32 v126, 0xbfb8aa3b, v126
	v_mul_f32_e32 v104, 0xbfb8aa3b, v104
	v_mul_f32_e32 v127, 0xbfb8aa3b, v127
	v_exp_f32_e32 v105, v105
	v_exp_f32_e32 v112, v112
	v_exp_f32_e32 v102, v102
	v_exp_f32_e32 v113, v113
	v_exp_f32_e32 v103, v103
	v_exp_f32_e32 v126, v126
	v_exp_f32_e32 v104, v104
	v_exp_f32_e32 v127, v127
	v_add_f32_e32 v105, 1.0, v105
	v_add_f32_e32 v112, 1.0, v112
	v_add_f32_e32 v102, 1.0, v102
	v_add_f32_e32 v113, 1.0, v113
	v_add_f32_e32 v103, 1.0, v103
	v_add_f32_e32 v126, 1.0, v126
	v_add_f32_e32 v104, 1.0, v104
	v_add_f32_e32 v127, 1.0, v127
	v_rcp_f32_e32 v105, v105
	v_rcp_f32_e32 v112, v112
	v_rcp_f32_e32 v102, v102
	v_rcp_f32_e32 v113, v113
	v_rcp_f32_e32 v103, v103
	v_rcp_f32_e32 v126, v126
	v_rcp_f32_e32 v104, v104
	v_rcp_f32_e32 v127, v127
	v_mul_f32_e32 v93, v93, v105
	v_mul_f32_e32 v94, v94, v112
	v_mul_f32_e32 v95, v95, v102
	v_mul_f32_e32 v96, v96, v113
	v_mul_f32_e32 v97, v97, v103
	v_mul_f32_e32 v102, v90, v126
	v_mul_f32_e32 v103, v91, v104
	v_mul_f32_e32 v104, v92, v127
	v_cvt_pk_bf16_f32 v90, v94, v95
	v_cvt_pk_bf16_f32 v91, v96, v97
	v_cvt_pk_bf16_f32 v92, v102, v103
	v_cvt_pk_bf16_f32 v93, v104, v93
	global_store_dwordx4 v[98:99], v[90:93], off
	s_nop 0
	v_add_u32_e32 v102, 0xa0, v168
	v_lshlrev_b64 v[90:91], 11, v[110:111]
	v_ashrrev_i32_e32 v103, 31, v102
	v_lshl_add_u64 v[90:91], s[10:11], 0, v[90:91]
	v_lshlrev_b64 v[92:93], 10, v[102:103]
	v_lshl_add_u64 v[90:91], v[90:91], 0, v[166:167]
	v_lshl_add_u64 v[92:93], v[170:171], 0, v[92:93]
	s_waitcnt vmcnt(12)
; __device__ __forceinline__ unsigned cvt_pk_bf16(float lo, float hi) { unsigned r; asm volatile("v_cvt_pk_bf16_f32 %0, %1, %2" : "=v"(r) : "v"(lo), "v"(hi)); return r; }
; __device__ __forceinline__ float bflo(unsigned u) { return __uint_as_float(u << 16); }
; __device__ __forceinline__ float bfhi(unsigned u) { return __uint_as_float(u & 0xffff0000u); }
; __device__ __forceinline__ float sigm(float v) { return __builtin_amdgcn_rcpf(1.0f + __expf(-v)); }
; DI float bflo(unsigned u) { return __uint_as_float(u << 16); }
; DI float bfhi(unsigned u) { return __uint_as_float(u & 0xffff0000u); }
;     __device__ __forceinline__ void operator()(const f32x4 (&acc)[2][2][4][2], const Unit& u, int wr, int wc, int fr, int fq) const {
;     ...
;                 for (int m = 0; m < 4; ++m) { const size_t row = (size_t)(row0 + ai * HALF + m * 16);
;                     const u32x4 g = *(const u32x4*)(gbase + row * 512 + gcol0 + bj * HALF);
;                     const f32x4 v0 = acc[ai][bj][m][0], v1 = acc[ai][bj][m][1];
;                     float r0 = v0[0] * sigm(bflo(g.x) + b0[0]), r1 = v0[1] * sigm(bfhi(g.x) + b0[1]), r2 = v0[2] * sigm(bflo(g.y) + b0[2]), r3 = v0[3] * sigm(bfhi(g.y) + b0[3]);
;                     float r4 = v1[0] * sigm(bflo(g.z) + b1[0]), r5 = v1[1] * sigm(bfhi(g.z) + b1[1]), r6 = v1[2] * sigm(bflo(g.w) + b1[2]), r7 = v1[3] * sigm(bfhi(g.w) + b1[3]);
;                     bf16_t* op = Mo + row * 1024 + col0 + bj * HALF;
;                     if (accum) { const u32x4 p = *(const u32x4*)op; r0 += bflo(p.x); r1 += bfhi(p.x); r2 += bflo(p.y); r3 += bfhi(p.y); r4 += bflo(p.z); r5 += bfhi(p.z); r6 += bflo(p.w); r7 += bfhi(p.w); }
;                     u32x4 w; w.x = cvt_pk_bf16(r0, r1); w.y = cvt_pk_bf16(r2, r3); w.z = cvt_pk_bf16(r4, r5); w.w = cvt_pk_bf16(r6, r7);
;                     *(u32x4*)op = w; }
	v_lshlrev_b32_e32 v111, 16, v223
	v_and_b32_e32 v97, 0xffff0000, v223
	v_lshlrev_b32_e32 v104, 16, v220
	v_and_b32_e32 v94, 0xffff0000, v220
	v_lshlrev_b32_e32 v105, 16, v221
	v_and_b32_e32 v95, 0xffff0000, v221
	v_lshlrev_b32_e32 v110, 16, v222
	v_and_b32_e32 v96, 0xffff0000, v222
	s_mov_b64 s[98:99], 0xc000
	v_lshl_add_u64 v[248:249], v[250:251], 0, s[98:99]
	global_load_dwordx4 v[220:223], v[248:249], off offset:256
	v_add_f32_e32 v97, v117, v97
	v_add_f32_e32 v104, v118, v104
	v_add_f32_e32 v94, v119, v94
	v_add_f32_e32 v105, v120, v105
	v_add_f32_e32 v95, v121, v95
	v_add_f32_e32 v110, v114, v110
	v_add_f32_e32 v96, v115, v96
	v_add_f32_e32 v111, v116, v111
	v_mul_f32_e32 v97, 0xbfb8aa3b, v97
	v_mul_f32_e32 v104, 0xbfb8aa3b, v104
	v_mul_f32_e32 v94, 0xbfb8aa3b, v94
	v_mul_f32_e32 v105, 0xbfb8aa3b, v105
	v_mul_f32_e32 v95, 0xbfb8aa3b, v95
	v_mul_f32_e32 v110, 0xbfb8aa3b, v110
	v_mul_f32_e32 v96, 0xbfb8aa3b, v96
	v_mul_f32_e32 v111, 0xbfb8aa3b, v111
	v_exp_f32_e32 v97, v97
	v_exp_f32_e32 v104, v104
	v_exp_f32_e32 v94, v94
	v_exp_f32_e32 v105, v105
	v_exp_f32_e32 v95, v95
	v_exp_f32_e32 v110, v110
	v_exp_f32_e32 v96, v96
	v_exp_f32_e32 v111, v111
	v_add_f32_e32 v97, 1.0, v97
	v_add_f32_e32 v104, 1.0, v104
	v_add_f32_e32 v94, 1.0, v94
	v_add_f32_e32 v105, 1.0, v105
	v_add_f32_e32 v95, 1.0, v95
	v_add_f32_e32 v110, 1.0, v110
	v_add_f32_e32 v96, 1.0, v96
	v_add_f32_e32 v111, 1.0, v111
	v_rcp_f32_e32 v97, v97
	v_rcp_f32_e32 v104, v104
	v_rcp_f32_e32 v94, v94
	v_rcp_f32_e32 v105, v105
	v_rcp_f32_e32 v95, v95
	v_rcp_f32_e32 v110, v110
	v_rcp_f32_e32 v96, v96
	v_rcp_f32_e32 v111, v111
	v_mul_f32_e32 v85, v85, v97
	v_mul_f32_e32 v86, v86, v104
	v_mul_f32_e32 v87, v87, v94
	v_mul_f32_e32 v88, v88, v105
	v_mul_f32_e32 v89, v89, v95
	v_mul_f32_e32 v94, v82, v110
	v_mul_f32_e32 v95, v83, v96
	v_mul_f32_e32 v96, v84, v111
	v_cvt_pk_bf16_f32 v82, v86, v87
	v_cvt_pk_bf16_f32 v83, v88, v89
	v_cvt_pk_bf16_f32 v84, v94, v95
	v_cvt_pk_bf16_f32 v85, v96, v85
	global_store_dwordx4 v[90:91], v[82:85], off
	s_nop 0
	v_add_u32_e32 v94, 0xb0, v168
	v_lshlrev_b64 v[82:83], 11, v[102:103]
	v_ashrrev_i32_e32 v95, 31, v94
	v_lshl_add_u64 v[82:83], s[10:11], 0, v[82:83]
	v_lshlrev_b64 v[84:85], 10, v[94:95]
	v_lshl_add_u64 v[82:83], v[82:83], 0, v[166:167]
	v_lshl_add_u64 v[84:85], v[170:171], 0, v[84:85]
	s_waitcnt vmcnt(13)
	v_lshlrev_b32_e32 v103, 16, v227
	v_and_b32_e32 v89, 0xffff0000, v227
	v_lshlrev_b32_e32 v96, 16, v224
	v_and_b32_e32 v86, 0xffff0000, v224
	v_lshlrev_b32_e32 v97, 16, v225
	v_and_b32_e32 v87, 0xffff0000, v225
	v_lshlrev_b32_e32 v102, 16, v226
	v_and_b32_e32 v88, 0xffff0000, v226
	s_mov_b64 s[98:99], 0x20000
	v_lshl_add_u64 v[248:249], v[250:251], 0, s[98:99]
	global_load_dwordx4 v[224:227], v[248:249], off offset:256
	v_add_f32_e32 v89, v117, v89
	v_add_f32_e32 v96, v118, v96
	v_add_f32_e32 v86, v119, v86
	v_add_f32_e32 v97, v120, v97
	v_add_f32_e32 v87, v121, v87
	v_add_f32_e32 v102, v114, v102
	v_add_f32_e32 v88, v115, v88
	v_add_f32_e32 v103, v116, v103
	v_mul_f32_e32 v89, 0xbfb8aa3b, v89
	v_mul_f32_e32 v96, 0xbfb8aa3b, v96
	v_mul_f32_e32 v86, 0xbfb8aa3b, v86
	v_mul_f32_e32 v97, 0xbfb8aa3b, v97
	v_mul_f32_e32 v87, 0xbfb8aa3b, v87
	v_mul_f32_e32 v102, 0xbfb8aa3b, v102
	v_mul_f32_e32 v88, 0xbfb8aa3b, v88
	v_mul_f32_e32 v103, 0xbfb8aa3b, v103
	v_exp_f32_e32 v89, v89
	v_exp_f32_e32 v96, v96
	v_exp_f32_e32 v86, v86
	v_exp_f32_e32 v97, v97
	v_exp_f32_e32 v87, v87
	v_exp_f32_e32 v102, v102
	v_exp_f32_e32 v88, v88
	v_exp_f32_e32 v103, v103
	v_add_f32_e32 v89, 1.0, v89
	v_add_f32_e32 v96, 1.0, v96
	v_add_f32_e32 v86, 1.0, v86
	v_add_f32_e32 v97, 1.0, v97
	v_add_f32_e32 v87, 1.0, v87
	v_add_f32_e32 v102, 1.0, v102
	v_add_f32_e32 v88, 1.0, v88
	v_add_f32_e32 v103, 1.0, v103
	v_rcp_f32_e32 v89, v89
	v_rcp_f32_e32 v96, v96
	v_rcp_f32_e32 v86, v86
	v_rcp_f32_e32 v97, v97
	v_rcp_f32_e32 v87, v87
	v_rcp_f32_e32 v102, v102
	v_rcp_f32_e32 v88, v88
	v_rcp_f32_e32 v103, v103
	v_mul_f32_e32 v77, v77, v89
	v_mul_f32_e32 v78, v78, v96
	v_mul_f32_e32 v79, v79, v86
	v_mul_f32_e32 v80, v80, v97
	v_mul_f32_e32 v81, v81, v87
	v_mul_f32_e32 v86, v74, v102
	v_mul_f32_e32 v87, v75, v88
	v_mul_f32_e32 v88, v76, v103
	v_cvt_pk_bf16_f32 v74, v78, v79
	v_cvt_pk_bf16_f32 v75, v80, v81
	v_cvt_pk_bf16_f32 v76, v86, v87
	v_cvt_pk_bf16_f32 v77, v88, v77
	global_store_dwordx4 v[82:83], v[74:77], off
	s_nop 0
	s_waitcnt vmcnt(11)
	v_lshlrev_b32_e32 v87, 16, v207
	v_and_b32_e32 v79, 0xffff0000, v207
	v_lshlrev_b32_e32 v80, 16, v204
	v_and_b32_e32 v76, 0xffff0000, v204
	v_lshlrev_b32_e32 v81, 16, v205
	v_and_b32_e32 v77, 0xffff0000, v205
	v_lshlrev_b32_e32 v86, 16, v206
	v_and_b32_e32 v78, 0xffff0000, v206
	s_mov_b64 s[98:99], 0x24000
	v_lshl_add_u64 v[248:249], v[250:251], 0, s[98:99]
	global_load_dwordx4 v[204:207], v[248:249], off offset:256
	v_add_f32_e32 v79, v117, v79
	v_add_f32_e32 v80, v118, v80
	v_add_f32_e32 v76, v119, v76
	v_add_f32_e32 v81, v120, v81
	v_add_f32_e32 v77, v121, v77
	v_add_f32_e32 v86, v114, v86
	v_add_f32_e32 v78, v115, v78
	v_add_f32_e32 v87, v116, v87
	v_mul_f32_e32 v79, 0xbfb8aa3b, v79
	v_mul_f32_e32 v80, 0xbfb8aa3b, v80
	v_mul_f32_e32 v76, 0xbfb8aa3b, v76
	v_mul_f32_e32 v81, 0xbfb8aa3b, v81
	v_mul_f32_e32 v77, 0xbfb8aa3b, v77
	v_mul_f32_e32 v86, 0xbfb8aa3b, v86
	v_mul_f32_e32 v78, 0xbfb8aa3b, v78
	v_mul_f32_e32 v87, 0xbfb8aa3b, v87
	v_exp_f32_e32 v79, v79
	v_exp_f32_e32 v80, v80
	v_exp_f32_e32 v76, v76
	v_exp_f32_e32 v81, v81
	v_exp_f32_e32 v77, v77
	v_exp_f32_e32 v86, v86
	v_exp_f32_e32 v78, v78
	v_exp_f32_e32 v87, v87
	v_add_f32_e32 v79, 1.0, v79
	v_add_f32_e32 v80, 1.0, v80
	v_add_f32_e32 v76, 1.0, v76
	v_add_f32_e32 v81, 1.0, v81
	v_add_f32_e32 v77, 1.0, v77
	v_add_f32_e32 v86, 1.0, v86
	v_add_f32_e32 v78, 1.0, v78
	v_add_f32_e32 v87, 1.0, v87
	v_rcp_f32_e32 v79, v79
	v_rcp_f32_e32 v80, v80
	v_rcp_f32_e32 v76, v76
	v_rcp_f32_e32 v81, v81
	v_rcp_f32_e32 v77, v77
	v_rcp_f32_e32 v86, v86
	v_rcp_f32_e32 v78, v78
	v_rcp_f32_e32 v87, v87
	v_lshlrev_b64 v[74:75], 11, v[94:95]
	v_lshl_add_u64 v[74:75], s[10:11], 0, v[74:75]
	v_lshl_add_u64 v[74:75], v[74:75], 0, v[166:167]
	v_mul_f32_e32 v69, v69, v79
	v_mul_f32_e32 v70, v70, v80
	v_mul_f32_e32 v71, v71, v76
	v_mul_f32_e32 v72, v72, v81
	v_mul_f32_e32 v73, v73, v77
	v_mul_f32_e32 v76, v66, v86
	v_mul_f32_e32 v77, v67, v78
	v_mul_f32_e32 v78, v68, v87
	v_cvt_pk_bf16_f32 v66, v70, v71
	v_cvt_pk_bf16_f32 v67, v72, v73
	v_cvt_pk_bf16_f32 v68, v76, v77
	v_cvt_pk_bf16_f32 v69, v78, v69
	global_store_dwordx4 v[74:75], v[66:69], off
	s_nop 0
	v_mov_b32_e32 v70, v240
	v_mov_b32_e32 v71, v241
	v_mov_b32_e32 v72, v242
	v_mov_b32_e32 v73, v243
	s_nop 0
	v_mov_b32_e32 v66, v244
	v_mov_b32_e32 v67, v245
	v_mov_b32_e32 v68, v246
	v_mov_b32_e32 v69, v247
	s_waitcnt vmcnt(11)
; __device__ __forceinline__ unsigned cvt_pk_bf16(float lo, float hi) { unsigned r; asm volatile("v_cvt_pk_bf16_f32 %0, %1, %2" : "=v"(r) : "v"(lo), "v"(hi)); return r; }
; __device__ __forceinline__ float bflo(unsigned u) { return __uint_as_float(u << 16); }
; __device__ __forceinline__ float bfhi(unsigned u) { return __uint_as_float(u & 0xffff0000u); }
; __device__ __forceinline__ float sigm(float v) { return __builtin_amdgcn_rcpf(1.0f + __expf(-v)); }
; DI float bflo(unsigned u) { return __uint_as_float(u << 16); }
; DI float bfhi(unsigned u) { return __uint_as_float(u & 0xffff0000u); }
;     __device__ __forceinline__ void operator()(const f32x4 (&acc)[2][2][4][2], const Unit& u, int wr, int wc, int fr, int fq) const {
;     ...
;                 for (int m = 0; m < 4; ++m) { const size_t row = (size_t)(row0 + ai * HALF + m * 16);
;                     const u32x4 g = *(const u32x4*)(gbase + row * 512 + gcol0 + bj * HALF);
;                     const f32x4 v0 = acc[ai][bj][m][0], v1 = acc[ai][bj][m][1];
;                     float r0 = v0[0] * sigm(bflo(g.x) + b0[0]), r1 = v0[1] * sigm(bfhi(g.x) + b0[1]), r2 = v0[2] * sigm(bflo(g.y) + b0[2]), r3 = v0[3] * sigm(bfhi(g.y) + b0[3]);
;                     float r4 = v1[0] * sigm(bflo(g.z) + b1[0]), r5 = v1[1] * sigm(bfhi(g.z) + b1[1]), r6 = v1[2] * sigm(bflo(g.w) + b1[2]), r7 = v1[3] * sigm(bfhi(g.w) + b1[3]);
;                     bf16_t* op = Mo + row * 1024 + col0 + bj * HALF;
;                     if (accum) { const u32x4 p = *(const u32x4*)op; r0 += bflo(p.x); r1 += bfhi(p.x); r2 += bflo(p.y); r3 += bfhi(p.y); r4 += bflo(p.z); r5 += bfhi(p.z); r6 += bflo(p.w); r7 += bfhi(p.w); }
;                     u32x4 w; w.x = cvt_pk_bf16(r0, r1); w.y = cvt_pk_bf16(r2, r3); w.z = cvt_pk_bf16(r4, r5); w.w = cvt_pk_bf16(r6, r7);
;                     *(u32x4*)op = w; }
	v_lshlrev_b32_e32 v87, 16, v211
	v_and_b32_e32 v79, 0xffff0000, v211
	v_lshlrev_b32_e32 v80, 16, v208
	v_and_b32_e32 v76, 0xffff0000, v208
	v_lshlrev_b32_e32 v81, 16, v209
	v_and_b32_e32 v77, 0xffff0000, v209
	v_lshlrev_b32_e32 v86, 16, v210
	v_and_b32_e32 v78, 0xffff0000, v210
	s_mov_b64 s[98:99], 0x28000
	v_lshl_add_u64 v[248:249], v[250:251], 0, s[98:99]
	global_load_dwordx4 v[208:211], v[248:249], off offset:256
	s_nop 0
	v_add_f32_e32 v79, v69, v79
	v_add_f32_e32 v80, v70, v80
	v_add_f32_e32 v76, v71, v76
	v_add_f32_e32 v81, v72, v81
	v_add_f32_e32 v77, v73, v77
	v_add_f32_e32 v86, v66, v86
	v_add_f32_e32 v78, v67, v78
	v_add_f32_e32 v87, v68, v87
	v_mul_f32_e32 v79, 0xbfb8aa3b, v79
	v_mul_f32_e32 v80, 0xbfb8aa3b, v80
	v_mul_f32_e32 v76, 0xbfb8aa3b, v76
	v_mul_f32_e32 v81, 0xbfb8aa3b, v81
	v_mul_f32_e32 v77, 0xbfb8aa3b, v77
	v_mul_f32_e32 v86, 0xbfb8aa3b, v86
	v_mul_f32_e32 v78, 0xbfb8aa3b, v78
	v_mul_f32_e32 v87, 0xbfb8aa3b, v87
	v_exp_f32_e32 v79, v79
	v_exp_f32_e32 v80, v80
	v_exp_f32_e32 v76, v76
	v_exp_f32_e32 v81, v81
	v_exp_f32_e32 v77, v77
	v_exp_f32_e32 v86, v86
	v_exp_f32_e32 v78, v78
	v_exp_f32_e32 v87, v87
	v_add_f32_e32 v79, 1.0, v79
	v_add_f32_e32 v80, 1.0, v80
	v_add_f32_e32 v76, 1.0, v76
	v_add_f32_e32 v81, 1.0, v81
	v_add_f32_e32 v77, 1.0, v77
	v_add_f32_e32 v86, 1.0, v86
	v_add_f32_e32 v78, 1.0, v78
	v_add_f32_e32 v87, 1.0, v87
	v_rcp_f32_e32 v79, v79
	v_rcp_f32_e32 v80, v80
	v_rcp_f32_e32 v76, v76
	v_rcp_f32_e32 v81, v81
	v_rcp_f32_e32 v77, v77
	v_rcp_f32_e32 v86, v86
	v_rcp_f32_e32 v78, v78
	v_rcp_f32_e32 v87, v87
	v_mul_f32_e32 v61, v61, v79
	v_mul_f32_e32 v62, v62, v80
	v_mul_f32_e32 v63, v63, v76
	v_mul_f32_e32 v64, v64, v81
	v_mul_f32_e32 v65, v65, v77
	v_mul_f32_e32 v76, v58, v86
	v_mul_f32_e32 v77, v59, v78
	v_mul_f32_e32 v78, v60, v87
	v_cvt_pk_bf16_f32 v58, v62, v63
	v_cvt_pk_bf16_f32 v59, v64, v65
	v_cvt_pk_bf16_f32 v60, v76, v77
	v_cvt_pk_bf16_f32 v61, v78, v61
	global_store_dwordx4 v[154:155], v[58:61], off offset:256
	s_nop 0
	s_waitcnt vmcnt(11)
	v_lshlrev_b32_e32 v65, 16, v215
	v_and_b32_e32 v61, 0xffff0000, v215
	v_lshlrev_b32_e32 v62, 16, v212
	v_and_b32_e32 v58, 0xffff0000, v212
	v_lshlrev_b32_e32 v63, 16, v213
	v_and_b32_e32 v59, 0xffff0000, v213
	v_lshlrev_b32_e32 v64, 16, v214
	v_and_b32_e32 v60, 0xffff0000, v214
	s_mov_b64 s[98:99], 0x2c000
	v_lshl_add_u64 v[248:249], v[250:251], 0, s[98:99]
	global_load_dwordx4 v[212:215], v[248:249], off offset:256
	v_add_f32_e32 v61, v69, v61
	v_add_f32_e32 v62, v70, v62
	v_add_f32_e32 v58, v71, v58
	v_add_f32_e32 v63, v72, v63
	v_add_f32_e32 v59, v73, v59
	v_add_f32_e32 v64, v66, v64
	v_add_f32_e32 v60, v67, v60
	v_add_f32_e32 v65, v68, v65
	v_mul_f32_e32 v61, 0xbfb8aa3b, v61
	v_mul_f32_e32 v62, 0xbfb8aa3b, v62
	v_mul_f32_e32 v58, 0xbfb8aa3b, v58
	v_mul_f32_e32 v63, 0xbfb8aa3b, v63
	v_mul_f32_e32 v59, 0xbfb8aa3b, v59
	v_mul_f32_e32 v64, 0xbfb8aa3b, v64
	v_mul_f32_e32 v60, 0xbfb8aa3b, v60
	v_mul_f32_e32 v65, 0xbfb8aa3b, v65
	v_exp_f32_e32 v61, v61
	v_exp_f32_e32 v62, v62
	v_exp_f32_e32 v58, v58
	v_exp_f32_e32 v63, v63
	v_exp_f32_e32 v59, v59
	v_exp_f32_e32 v64, v64
	v_exp_f32_e32 v60, v60
	v_exp_f32_e32 v65, v65
	v_add_f32_e32 v61, 1.0, v61
	v_add_f32_e32 v62, 1.0, v62
	v_add_f32_e32 v58, 1.0, v58
	v_add_f32_e32 v63, 1.0, v63
	v_add_f32_e32 v59, 1.0, v59
	v_add_f32_e32 v64, 1.0, v64
	v_add_f32_e32 v60, 1.0, v60
	v_add_f32_e32 v65, 1.0, v65
	v_rcp_f32_e32 v61, v61
	v_rcp_f32_e32 v62, v62
	v_rcp_f32_e32 v58, v58
	v_rcp_f32_e32 v63, v63
	v_rcp_f32_e32 v59, v59
	v_rcp_f32_e32 v64, v64
	v_rcp_f32_e32 v60, v60
	v_rcp_f32_e32 v65, v65
	v_mul_f32_e32 v53, v53, v61
	v_mul_f32_e32 v54, v54, v62
	v_mul_f32_e32 v55, v55, v58
	v_mul_f32_e32 v56, v56, v63
	v_mul_f32_e32 v57, v57, v59
	v_mul_f32_e32 v58, v50, v64
	v_mul_f32_e32 v59, v51, v60
	v_mul_f32_e32 v60, v52, v65
	v_cvt_pk_bf16_f32 v50, v54, v55
	v_cvt_pk_bf16_f32 v51, v56, v57
	v_cvt_pk_bf16_f32 v52, v58, v59
	v_cvt_pk_bf16_f32 v53, v60, v53
	global_store_dwordx4 v[130:131], v[50:53], off offset:256
	s_nop 0
	s_waitcnt vmcnt(11)
	v_lshlrev_b32_e32 v57, 16, v219
	v_and_b32_e32 v53, 0xffff0000, v219
	v_lshlrev_b32_e32 v54, 16, v216
	v_and_b32_e32 v50, 0xffff0000, v216
	v_lshlrev_b32_e32 v55, 16, v217
	v_and_b32_e32 v51, 0xffff0000, v217
	v_lshlrev_b32_e32 v56, 16, v218
	v_and_b32_e32 v52, 0xffff0000, v218
	v_add_f32_e32 v53, v69, v53
	v_add_f32_e32 v54, v70, v54
	v_add_f32_e32 v50, v71, v50
	v_add_f32_e32 v55, v72, v55
	v_add_f32_e32 v51, v73, v51
	v_add_f32_e32 v56, v66, v56
	v_add_f32_e32 v52, v67, v52
	v_add_f32_e32 v57, v68, v57
	v_mul_f32_e32 v53, 0xbfb8aa3b, v53
	v_mul_f32_e32 v54, 0xbfb8aa3b, v54
	v_mul_f32_e32 v50, 0xbfb8aa3b, v50
	v_mul_f32_e32 v55, 0xbfb8aa3b, v55
	v_mul_f32_e32 v51, 0xbfb8aa3b, v51
	v_mul_f32_e32 v56, 0xbfb8aa3b, v56
	v_mul_f32_e32 v52, 0xbfb8aa3b, v52
	v_mul_f32_e32 v57, 0xbfb8aa3b, v57
	v_exp_f32_e32 v53, v53
	v_exp_f32_e32 v54, v54
	v_exp_f32_e32 v50, v50
	v_exp_f32_e32 v55, v55
	v_exp_f32_e32 v51, v51
	v_exp_f32_e32 v56, v56
	v_exp_f32_e32 v52, v52
	v_exp_f32_e32 v57, v57
	v_add_f32_e32 v53, 1.0, v53
	v_add_f32_e32 v54, 1.0, v54
	v_add_f32_e32 v50, 1.0, v50
	v_add_f32_e32 v55, 1.0, v55
	v_add_f32_e32 v51, 1.0, v51
	v_add_f32_e32 v56, 1.0, v56
	v_add_f32_e32 v52, 1.0, v52
	v_add_f32_e32 v57, 1.0, v57
	v_rcp_f32_e32 v53, v53
	v_rcp_f32_e32 v54, v54
	v_rcp_f32_e32 v50, v50
	v_rcp_f32_e32 v55, v55
	v_rcp_f32_e32 v51, v51
	v_rcp_f32_e32 v56, v56
	v_rcp_f32_e32 v52, v52
	v_rcp_f32_e32 v57, v57
	v_mul_f32_e32 v45, v45, v53
	v_mul_f32_e32 v46, v46, v54
	v_mul_f32_e32 v47, v47, v50
	v_mul_f32_e32 v48, v48, v55
	v_mul_f32_e32 v49, v49, v51
	v_mul_f32_e32 v50, v42, v56
	v_mul_f32_e32 v51, v43, v52
	v_mul_f32_e32 v52, v44, v57
	v_cvt_pk_bf16_f32 v42, v46, v47
	v_cvt_pk_bf16_f32 v43, v48, v49
	v_cvt_pk_bf16_f32 v44, v50, v51
	v_cvt_pk_bf16_f32 v45, v52, v45
	global_store_dwordx4 v[122:123], v[42:45], off offset:256
	s_nop 0
	s_waitcnt vmcnt(10)
; __device__ __forceinline__ unsigned cvt_pk_bf16(float lo, float hi) { unsigned r; asm volatile("v_cvt_pk_bf16_f32 %0, %1, %2" : "=v"(r) : "v"(lo), "v"(hi)); return r; }
; __device__ __forceinline__ float bflo(unsigned u) { return __uint_as_float(u << 16); }
; __device__ __forceinline__ float bfhi(unsigned u) { return __uint_as_float(u & 0xffff0000u); }
; __device__ __forceinline__ float sigm(float v) { return __builtin_amdgcn_rcpf(1.0f + __expf(-v)); }
; DI float bflo(unsigned u) { return __uint_as_float(u << 16); }
; DI float bfhi(unsigned u) { return __uint_as_float(u & 0xffff0000u); }
;     __device__ __forceinline__ void operator()(const f32x4 (&acc)[2][2][4][2], const Unit& u, int wr, int wc, int fr, int fq) const {
;     ...
;                 for (int m = 0; m < 4; ++m) { const size_t row = (size_t)(row0 + ai * HALF + m * 16);
;                     const u32x4 g = *(const u32x4*)(gbase + row * 512 + gcol0 + bj * HALF);
;                     const f32x4 v0 = acc[ai][bj][m][0], v1 = acc[ai][bj][m][1];
;                     float r0 = v0[0] * sigm(bflo(g.x) + b0[0]), r1 = v0[1] * sigm(bfhi(g.x) + b0[1]), r2 = v0[2] * sigm(bflo(g.y) + b0[2]), r3 = v0[3] * sigm(bfhi(g.y) + b0[3]);
;                     float r4 = v1[0] * sigm(bflo(g.z) + b1[0]), r5 = v1[1] * sigm(bfhi(g.z) + b1[1]), r6 = v1[2] * sigm(bflo(g.w) + b1[2]), r7 = v1[3] * sigm(bfhi(g.w) + b1[3]);
;                     bf16_t* op = Mo + row * 1024 + col0 + bj * HALF;
;                     if (accum) { const u32x4 p = *(const u32x4*)op; r0 += bflo(p.x); r1 += bfhi(p.x); r2 += bflo(p.y); r3 += bfhi(p.y); r4 += bflo(p.z); r5 += bfhi(p.z); r6 += bflo(p.w); r7 += bfhi(p.w); }
;                     u32x4 w; w.x = cvt_pk_bf16(r0, r1); w.y = cvt_pk_bf16(r2, r3); w.z = cvt_pk_bf16(r4, r5); w.w = cvt_pk_bf16(r6, r7);
;                     *(u32x4*)op = w; }
	v_lshlrev_b32_e32 v49, 16, v223
	v_and_b32_e32 v45, 0xffff0000, v223
	v_lshlrev_b32_e32 v46, 16, v220
	v_and_b32_e32 v42, 0xffff0000, v220
	v_lshlrev_b32_e32 v47, 16, v221
	v_and_b32_e32 v43, 0xffff0000, v221
	v_lshlrev_b32_e32 v48, 16, v222
	v_and_b32_e32 v44, 0xffff0000, v222
	v_add_f32_e32 v45, v69, v45
	v_add_f32_e32 v46, v70, v46
	v_add_f32_e32 v42, v71, v42
	v_add_f32_e32 v47, v72, v47
	v_add_f32_e32 v43, v73, v43
	v_add_f32_e32 v48, v66, v48
	v_add_f32_e32 v44, v67, v44
	v_add_f32_e32 v49, v68, v49
	v_mul_f32_e32 v45, 0xbfb8aa3b, v45
	v_mul_f32_e32 v46, 0xbfb8aa3b, v46
	v_mul_f32_e32 v42, 0xbfb8aa3b, v42
	v_mul_f32_e32 v47, 0xbfb8aa3b, v47
	v_mul_f32_e32 v43, 0xbfb8aa3b, v43
	v_mul_f32_e32 v48, 0xbfb8aa3b, v48
	v_mul_f32_e32 v44, 0xbfb8aa3b, v44
	v_mul_f32_e32 v49, 0xbfb8aa3b, v49
	v_exp_f32_e32 v45, v45
	v_exp_f32_e32 v46, v46
	v_exp_f32_e32 v42, v42
	v_exp_f32_e32 v47, v47
	v_exp_f32_e32 v43, v43
	v_exp_f32_e32 v48, v48
	v_exp_f32_e32 v44, v44
	v_exp_f32_e32 v49, v49
	v_add_f32_e32 v45, 1.0, v45
	v_add_f32_e32 v46, 1.0, v46
	v_add_f32_e32 v42, 1.0, v42
	v_add_f32_e32 v47, 1.0, v47
	v_add_f32_e32 v43, 1.0, v43
	v_add_f32_e32 v48, 1.0, v48
	v_add_f32_e32 v44, 1.0, v44
	v_add_f32_e32 v49, 1.0, v49
	v_rcp_f32_e32 v45, v45
	v_rcp_f32_e32 v46, v46
	v_rcp_f32_e32 v42, v42
	v_rcp_f32_e32 v47, v47
	v_rcp_f32_e32 v43, v43
	v_rcp_f32_e32 v48, v48
	v_rcp_f32_e32 v44, v44
	v_rcp_f32_e32 v49, v49
	v_mul_f32_e32 v37, v37, v45
	v_mul_f32_e32 v38, v38, v46
	v_mul_f32_e32 v39, v39, v42
	v_mul_f32_e32 v40, v40, v47
	v_mul_f32_e32 v41, v41, v43
	v_mul_f32_e32 v42, v34, v48
	v_mul_f32_e32 v43, v35, v44
	v_mul_f32_e32 v44, v36, v49
	v_cvt_pk_bf16_f32 v34, v38, v39
	v_cvt_pk_bf16_f32 v35, v40, v41
	v_cvt_pk_bf16_f32 v36, v42, v43
	v_cvt_pk_bf16_f32 v37, v44, v37
	global_store_dwordx4 v[106:107], v[34:37], off offset:256
	s_nop 0
	s_waitcnt vmcnt(9)
	v_lshlrev_b32_e32 v41, 16, v227
	v_and_b32_e32 v37, 0xffff0000, v227
	v_lshlrev_b32_e32 v38, 16, v224
	v_and_b32_e32 v34, 0xffff0000, v224
	v_lshlrev_b32_e32 v39, 16, v225
	v_and_b32_e32 v35, 0xffff0000, v225
	v_lshlrev_b32_e32 v40, 16, v226
	v_and_b32_e32 v36, 0xffff0000, v226
	v_add_f32_e32 v37, v69, v37
	v_add_f32_e32 v38, v70, v38
	v_add_f32_e32 v34, v71, v34
	v_add_f32_e32 v39, v72, v39
	v_add_f32_e32 v35, v73, v35
	v_add_f32_e32 v40, v66, v40
	v_add_f32_e32 v36, v67, v36
	v_add_f32_e32 v41, v68, v41
	v_mul_f32_e32 v37, 0xbfb8aa3b, v37
	v_mul_f32_e32 v38, 0xbfb8aa3b, v38
	v_mul_f32_e32 v34, 0xbfb8aa3b, v34
	v_mul_f32_e32 v39, 0xbfb8aa3b, v39
	v_mul_f32_e32 v35, 0xbfb8aa3b, v35
	v_mul_f32_e32 v40, 0xbfb8aa3b, v40
	v_mul_f32_e32 v36, 0xbfb8aa3b, v36
	v_mul_f32_e32 v41, 0xbfb8aa3b, v41
	v_exp_f32_e32 v37, v37
	v_exp_f32_e32 v38, v38
	v_exp_f32_e32 v34, v34
	v_exp_f32_e32 v39, v39
	v_exp_f32_e32 v35, v35
	v_exp_f32_e32 v40, v40
	v_exp_f32_e32 v36, v36
	v_exp_f32_e32 v41, v41
	v_add_f32_e32 v37, 1.0, v37
	v_add_f32_e32 v38, 1.0, v38
	v_add_f32_e32 v34, 1.0, v34
	v_add_f32_e32 v39, 1.0, v39
	v_add_f32_e32 v35, 1.0, v35
	v_add_f32_e32 v40, 1.0, v40
	v_add_f32_e32 v36, 1.0, v36
	v_add_f32_e32 v41, 1.0, v41
	v_rcp_f32_e32 v37, v37
	v_rcp_f32_e32 v38, v38
	v_rcp_f32_e32 v34, v34
	v_rcp_f32_e32 v39, v39
	v_rcp_f32_e32 v35, v35
	v_rcp_f32_e32 v40, v40
	v_rcp_f32_e32 v36, v36
	v_rcp_f32_e32 v41, v41
	v_mul_f32_e32 v29, v29, v37
	v_mul_f32_e32 v30, v30, v38
	v_mul_f32_e32 v31, v31, v34
	v_mul_f32_e32 v32, v32, v39
	v_mul_f32_e32 v33, v33, v35
	v_mul_f32_e32 v34, v26, v40
	v_mul_f32_e32 v35, v27, v36
	v_mul_f32_e32 v36, v28, v41
	v_cvt_pk_bf16_f32 v26, v30, v31
	v_cvt_pk_bf16_f32 v27, v32, v33
	v_cvt_pk_bf16_f32 v28, v34, v35
	v_cvt_pk_bf16_f32 v29, v36, v29
	global_store_dwordx4 v[98:99], v[26:29], off offset:256
	s_nop 0
	s_waitcnt vmcnt(8)
	v_lshlrev_b32_e32 v33, 16, v207
	v_and_b32_e32 v29, 0xffff0000, v207
	v_lshlrev_b32_e32 v30, 16, v204
	v_and_b32_e32 v26, 0xffff0000, v204
	v_lshlrev_b32_e32 v31, 16, v205
	v_and_b32_e32 v27, 0xffff0000, v205
	v_lshlrev_b32_e32 v32, 16, v206
	v_and_b32_e32 v28, 0xffff0000, v206
	v_add_f32_e32 v29, v69, v29
	v_add_f32_e32 v30, v70, v30
	v_add_f32_e32 v26, v71, v26
	v_add_f32_e32 v31, v72, v31
	v_add_f32_e32 v27, v73, v27
	v_add_f32_e32 v32, v66, v32
	v_add_f32_e32 v28, v67, v28
	v_add_f32_e32 v33, v68, v33
	v_mul_f32_e32 v29, 0xbfb8aa3b, v29
	v_mul_f32_e32 v30, 0xbfb8aa3b, v30
	v_mul_f32_e32 v26, 0xbfb8aa3b, v26
	v_mul_f32_e32 v31, 0xbfb8aa3b, v31
	v_mul_f32_e32 v27, 0xbfb8aa3b, v27
	v_mul_f32_e32 v32, 0xbfb8aa3b, v32
	v_mul_f32_e32 v28, 0xbfb8aa3b, v28
	v_mul_f32_e32 v33, 0xbfb8aa3b, v33
	v_exp_f32_e32 v29, v29
	v_exp_f32_e32 v30, v30
	v_exp_f32_e32 v26, v26
	v_exp_f32_e32 v31, v31
	v_exp_f32_e32 v27, v27
	v_exp_f32_e32 v32, v32
	v_exp_f32_e32 v28, v28
	v_exp_f32_e32 v33, v33
	v_add_f32_e32 v29, 1.0, v29
	v_add_f32_e32 v30, 1.0, v30
	v_add_f32_e32 v26, 1.0, v26
	v_add_f32_e32 v31, 1.0, v31
	v_add_f32_e32 v27, 1.0, v27
	v_add_f32_e32 v32, 1.0, v32
	v_add_f32_e32 v28, 1.0, v28
	v_add_f32_e32 v33, 1.0, v33
	v_rcp_f32_e32 v29, v29
	v_rcp_f32_e32 v30, v30
	v_rcp_f32_e32 v26, v26
	v_rcp_f32_e32 v31, v31
	v_rcp_f32_e32 v27, v27
	v_rcp_f32_e32 v32, v32
	v_rcp_f32_e32 v28, v28
	v_rcp_f32_e32 v33, v33
	v_mul_f32_e32 v21, v21, v29
	v_mul_f32_e32 v22, v22, v30
	v_mul_f32_e32 v23, v23, v26
	v_mul_f32_e32 v24, v24, v31
	v_mul_f32_e32 v25, v25, v27
	v_mul_f32_e32 v26, v18, v32
	v_mul_f32_e32 v27, v19, v28
	v_mul_f32_e32 v28, v20, v33
	v_cvt_pk_bf16_f32 v18, v22, v23
	v_cvt_pk_bf16_f32 v19, v24, v25
	v_cvt_pk_bf16_f32 v20, v26, v27
	v_cvt_pk_bf16_f32 v21, v28, v21
	global_store_dwordx4 v[90:91], v[18:21], off offset:256
	s_nop 0
	s_waitcnt vmcnt(7)
; __device__ __forceinline__ unsigned cvt_pk_bf16(float lo, float hi) { unsigned r; asm volatile("v_cvt_pk_bf16_f32 %0, %1, %2" : "=v"(r) : "v"(lo), "v"(hi)); return r; }
; __device__ __forceinline__ float bflo(unsigned u) { return __uint_as_float(u << 16); }
; __device__ __forceinline__ float bfhi(unsigned u) { return __uint_as_float(u & 0xffff0000u); }
; __device__ __forceinline__ float sigm(float v) { return __builtin_amdgcn_rcpf(1.0f + __expf(-v)); }
; DI float bflo(unsigned u) { return __uint_as_float(u << 16); }
; DI float bfhi(unsigned u) { return __uint_as_float(u & 0xffff0000u); }
;     __device__ __forceinline__ void operator()(const f32x4 (&acc)[2][2][4][2], const Unit& u, int wr, int wc, int fr, int fq) const {
;     ...
;                 for (int m = 0; m < 4; ++m) { const size_t row = (size_t)(row0 + ai * HALF + m * 16);
;                     const u32x4 g = *(const u32x4*)(gbase + row * 512 + gcol0 + bj * HALF);
;                     const f32x4 v0 = acc[ai][bj][m][0], v1 = acc[ai][bj][m][1];
;                     float r0 = v0[0] * sigm(bflo(g.x) + b0[0]), r1 = v0[1] * sigm(bfhi(g.x) + b0[1]), r2 = v0[2] * sigm(bflo(g.y) + b0[2]), r3 = v0[3] * sigm(bfhi(g.y) + b0[3]);
;                     float r4 = v1[0] * sigm(bflo(g.z) + b1[0]), r5 = v1[1] * sigm(bfhi(g.z) + b1[1]), r6 = v1[2] * sigm(bflo(g.w) + b1[2]), r7 = v1[3] * sigm(bfhi(g.w) + b1[3]);
;                     bf16_t* op = Mo + row * 1024 + col0 + bj * HALF;
;                     if (accum) { const u32x4 p = *(const u32x4*)op; r0 += bflo(p.x); r1 += bfhi(p.x); r2 += bflo(p.y); r3 += bfhi(p.y); r4 += bflo(p.z); r5 += bfhi(p.z); r6 += bflo(p.w); r7 += bfhi(p.w); }
;                     u32x4 w; w.x = cvt_pk_bf16(r0, r1); w.y = cvt_pk_bf16(r2, r3); w.z = cvt_pk_bf16(r4, r5); w.w = cvt_pk_bf16(r6, r7);
;                     *(u32x4*)op = w; }
	v_lshlrev_b32_e32 v25, 16, v211
	v_and_b32_e32 v21, 0xffff0000, v211
	v_lshlrev_b32_e32 v22, 16, v208
	v_and_b32_e32 v18, 0xffff0000, v208
	v_lshlrev_b32_e32 v23, 16, v209
	v_and_b32_e32 v19, 0xffff0000, v209
	v_lshlrev_b32_e32 v24, 16, v210
	v_and_b32_e32 v20, 0xffff0000, v210
	v_add_f32_e32 v21, v69, v21
	v_add_f32_e32 v22, v70, v22
	v_add_f32_e32 v18, v71, v18
	v_add_f32_e32 v23, v72, v23
	v_add_f32_e32 v19, v73, v19
	v_add_f32_e32 v24, v66, v24
	v_add_f32_e32 v20, v67, v20
	v_add_f32_e32 v25, v68, v25
	v_mul_f32_e32 v21, 0xbfb8aa3b, v21
	v_mul_f32_e32 v22, 0xbfb8aa3b, v22
	v_mul_f32_e32 v18, 0xbfb8aa3b, v18
	v_mul_f32_e32 v23, 0xbfb8aa3b, v23
	v_mul_f32_e32 v19, 0xbfb8aa3b, v19
	v_mul_f32_e32 v24, 0xbfb8aa3b, v24
	v_mul_f32_e32 v20, 0xbfb8aa3b, v20
	v_mul_f32_e32 v25, 0xbfb8aa3b, v25
	v_exp_f32_e32 v21, v21
	v_exp_f32_e32 v22, v22
	v_exp_f32_e32 v18, v18
	v_exp_f32_e32 v23, v23
	v_exp_f32_e32 v19, v19
	v_exp_f32_e32 v24, v24
	v_exp_f32_e32 v20, v20
	v_exp_f32_e32 v25, v25
	v_add_f32_e32 v21, 1.0, v21
	v_add_f32_e32 v22, 1.0, v22
	v_add_f32_e32 v18, 1.0, v18
	v_add_f32_e32 v23, 1.0, v23
	v_add_f32_e32 v19, 1.0, v19
	v_add_f32_e32 v24, 1.0, v24
	v_add_f32_e32 v20, 1.0, v20
	v_add_f32_e32 v25, 1.0, v25
	v_rcp_f32_e32 v21, v21
	v_rcp_f32_e32 v22, v22
	v_rcp_f32_e32 v18, v18
	v_rcp_f32_e32 v23, v23
	v_rcp_f32_e32 v19, v19
	v_rcp_f32_e32 v24, v24
	v_rcp_f32_e32 v20, v20
	v_rcp_f32_e32 v25, v25
	v_mul_f32_e32 v13, v13, v21
	v_mul_f32_e32 v14, v14, v22
	v_mul_f32_e32 v15, v15, v18
	v_mul_f32_e32 v16, v16, v23
	v_mul_f32_e32 v17, v17, v19
	v_mul_f32_e32 v18, v10, v24
	v_mul_f32_e32 v19, v11, v20
	v_mul_f32_e32 v20, v12, v25
	v_cvt_pk_bf16_f32 v10, v14, v15
	v_cvt_pk_bf16_f32 v11, v16, v17
	v_cvt_pk_bf16_f32 v12, v18, v19
	v_cvt_pk_bf16_f32 v13, v20, v13
	global_store_dwordx4 v[82:83], v[10:13], off offset:256
	s_nop 0
	s_waitcnt vmcnt(6)
	v_lshlrev_b32_e32 v17, 16, v215
	v_and_b32_e32 v13, 0xffff0000, v215
	v_lshlrev_b32_e32 v14, 16, v212
	v_and_b32_e32 v10, 0xffff0000, v212
	v_lshlrev_b32_e32 v15, 16, v213
	v_and_b32_e32 v11, 0xffff0000, v213
	v_lshlrev_b32_e32 v16, 16, v214
	v_and_b32_e32 v12, 0xffff0000, v214
	v_add_f32_e32 v13, v69, v13
	v_add_f32_e32 v14, v70, v14
	v_add_f32_e32 v10, v71, v10
	v_add_f32_e32 v15, v72, v15
	v_add_f32_e32 v11, v73, v11
	v_add_f32_e32 v16, v66, v16
	v_add_f32_e32 v12, v67, v12
	v_add_f32_e32 v17, v68, v17
	v_mul_f32_e32 v13, 0xbfb8aa3b, v13
	v_mul_f32_e32 v14, 0xbfb8aa3b, v14
	v_mul_f32_e32 v10, 0xbfb8aa3b, v10
	v_mul_f32_e32 v15, 0xbfb8aa3b, v15
	v_mul_f32_e32 v11, 0xbfb8aa3b, v11
	v_mul_f32_e32 v16, 0xbfb8aa3b, v16
	v_mul_f32_e32 v12, 0xbfb8aa3b, v12
	v_mul_f32_e32 v17, 0xbfb8aa3b, v17
	v_exp_f32_e32 v13, v13
	v_exp_f32_e32 v14, v14
	v_exp_f32_e32 v10, v10
	v_exp_f32_e32 v15, v15
	v_exp_f32_e32 v11, v11
	v_exp_f32_e32 v16, v16
	v_exp_f32_e32 v12, v12
	v_exp_f32_e32 v17, v17
	v_add_f32_e32 v13, 1.0, v13
	v_add_f32_e32 v14, 1.0, v14
	v_add_f32_e32 v10, 1.0, v10
	v_add_f32_e32 v15, 1.0, v15
	v_add_f32_e32 v11, 1.0, v11
	v_add_f32_e32 v16, 1.0, v16
	v_add_f32_e32 v12, 1.0, v12
	v_add_f32_e32 v17, 1.0, v17
	v_rcp_f32_e32 v13, v13
	v_rcp_f32_e32 v14, v14
	v_rcp_f32_e32 v10, v10
	v_rcp_f32_e32 v15, v15
	v_rcp_f32_e32 v11, v11
	v_rcp_f32_e32 v16, v16
	v_rcp_f32_e32 v12, v12
	v_rcp_f32_e32 v17, v17
	v_mul_f32_e32 v5, v5, v13
	v_mul_f32_e32 v6, v6, v14
	v_mul_f32_e32 v7, v7, v10
	v_mul_f32_e32 v8, v8, v15
	v_mul_f32_e32 v9, v9, v11
	v_mul_f32_e32 v10, v2, v16
	v_mul_f32_e32 v11, v3, v12
	v_mul_f32_e32 v12, v4, v17
	v_cvt_pk_bf16_f32 v2, v6, v7
	v_cvt_pk_bf16_f32 v3, v8, v9
	v_cvt_pk_bf16_f32 v4, v10, v11
	v_cvt_pk_bf16_f32 v5, v12, v5
	global_store_dwordx4 v[74:75], v[2:5], off offset:256
	s_cbranch_vccnz .LBB0_869
	s_andn2_b64 vcc, exec, s[0:1]
	s_cbranch_vccnz .LBB0_868
	s_barrier
	s_branch .LBB0_868

; __device__ __forceinline__ unsigned cvt_pk_bf16(float lo, float hi) { unsigned r; asm volatile("v_cvt_pk_bf16_f32 %0, %1, %2" : "=v"(r) : "v"(lo), "v"(hi)); return r; }
; __device__ __forceinline__ float bflo(unsigned u) { return __uint_as_float(u << 16); }
; __device__ __forceinline__ float bfhi(unsigned u) { return __uint_as_float(u & 0xffff0000u); }
; __device__ __forceinline__ float sigm(float v) { return __builtin_amdgcn_rcpf(1.0f + __expf(-v)); }
; DI float bflo(unsigned u) { return __uint_as_float(u << 16); }
; DI float bfhi(unsigned u) { return __uint_as_float(u & 0xffff0000u); }
;     __device__ __forceinline__ void operator()(const f32x4 (&acc)[2][2][4][2], const Unit& u, int wr, int wc, int fr, int fq) const {
;     ...
;         for (int bj = 0; bj < 2; ++bj) {
;             const f32x4 b0 = *(const f32x4*)(gb + col0 + bj * HALF), b1 = *(const f32x4*)(gb + col0 + bj * HALF + 4);
; #pragma unroll
;             for (int ai = 0; ai < 2; ++ai)
; #pragma unroll
;                 for (int m = 0; m < 4; ++m) { const size_t row = (size_t)(row0 + ai * HALF + m * 16);
;                     const u32x4 g = *(const u32x4*)(gbase + row * 512 + gcol0 + bj * HALF);
;                     const f32x4 v0 = acc[ai][bj][m][0], v1 = acc[ai][bj][m][1];
;                     float r0 = v0[0] * sigm(bflo(g.x) + b0[0]), r1 = v0[1] * sigm(bfhi(g.x) + b0[1]), r2 = v0[2] * sigm(bflo(g.y) + b0[2]), r3 = v0[3] * sigm(bfhi(g.y) + b0[3]);
;                     float r4 = v1[0] * sigm(bflo(g.z) + b1[0]), r5 = v1[1] * sigm(bfhi(g.z) + b1[1]), r6 = v1[2] * sigm(bflo(g.w) + b1[2]), r7 = v1[3] * sigm(bfhi(g.w) + b1[3]);
;                     bf16_t* op = Mo + row * 1024 + col0 + bj * HALF;
;                     if (accum) { const u32x4 p = *(const u32x4*)op; r0 += bflo(p.x); r1 += bfhi(p.x); r2 += bflo(p.y); r3 += bfhi(p.y); r4 += bflo(p.z); r5 += bfhi(p.z); r6 += bflo(p.w); r7 += bfhi(p.w); }
;                     u32x4 w; w.x = cvt_pk_bf16(r0, r1); w.y = cvt_pk_bf16(r2, r3); w.z = cvt_pk_bf16(r4, r5); w.w = cvt_pk_bf16(r6, r7);
;                     *(u32x4*)op = w; }
.LBB0_904:
	s_lshr_b32 s2, s48, 31
	s_add_i32 s2, s48, s2
	s_ashr_i32 s26, s2, 1
	s_ashr_i32 s27, s26, 31
	s_lshl_b64 s[28:29], s[26:27], 24
	s_add_u32 s28, s40, s28
	s_addc_u32 s29, s41, s29
	v_lshl_or_b32 v114, s48, 8, v172
	s_lshl_b32 s2, s26, 9
	v_lshl_add_u32 v168, s24, 8, v1
	v_subrev_u32_e32 v116, s2, v114
	v_ashrrev_i32_e32 v117, 31, v116
	v_ashrrev_i32_e32 v169, 31, v168
	v_lshl_add_u64 v[170:171], v[116:117], 1, s[28:29]
	v_lshlrev_b64 v[116:117], 10, v[168:169]
	v_lshl_add_u64 v[158:159], v[170:171], 0, v[116:117]
	v_ashrrev_i32_e32 v115, 31, v114
	v_lshlrev_b64 v[116:117], 11, v[168:169]
	v_lshl_add_u64 v[116:117], s[10:11], 0, v[116:117]
	v_lshlrev_b64 v[166:167], 1, v[114:115]
	global_load_dwordx4 v[176:179], v[158:159], off
	v_lshl_add_u64 v[154:155], v[116:117], 0, v[166:167]
	v_lshl_add_u64 v[160:161], v[114:115], 2, s[4:5]
	global_load_dwordx4 v[180:183], v[154:155], off
	global_load_dwordx4 v[118:121], v[160:161], off
	global_load_dwordx4 v[114:117], v[160:161], off offset:16
	v_or_b32_e32 v184, 16, v168
	v_ashrrev_i32_e32 v185, 31, v184
	v_lshlrev_b64 v[156:157], 10, v[184:185]
	v_lshl_add_u64 v[156:157], v[170:171], 0, v[156:157]
	s_andn2_b64 vcc, exec, s[6:7]
	s_mov_b64 s[6:7], -1
	v_mov_b32_e32 v250, v158
	v_mov_b32_e32 v251, v159
	v_mov_b32_e32 v252, v154
	v_mov_b32_e32 v253, v155
	s_mov_b64 s[98:99], 0x4000
	v_lshl_add_u64 v[248:249], v[250:251], 0, s[98:99]
	global_load_dwordx4 v[204:207], v[248:249], off
	s_mov_b64 s[98:99], 0x8000
	v_lshl_add_u64 v[248:249], v[252:253], 0, s[98:99]
	global_load_dwordx4 v[216:219], v[248:249], off
	s_mov_b64 s[98:99], 0x8000
	v_lshl_add_u64 v[248:249], v[250:251], 0, s[98:99]
	global_load_dwordx4 v[208:211], v[248:249], off
	s_mov_b64 s[98:99], 0x10000
	v_lshl_add_u64 v[248:249], v[252:253], 0, s[98:99]
	global_load_dwordx4 v[220:223], v[248:249], off
	s_mov_b64 s[98:99], 0xc000
	v_lshl_add_u64 v[248:249], v[250:251], 0, s[98:99]
	global_load_dwordx4 v[212:215], v[248:249], off
	s_mov_b64 s[98:99], 0x18000
	v_lshl_add_u64 v[248:249], v[252:253], 0, s[98:99]
	global_load_dwordx4 v[224:227], v[248:249], off
	global_load_dwordx4 v[240:243], v[160:161], off offset:512
	global_load_dwordx4 v[244:247], v[160:161], off offset:528
	s_waitcnt vmcnt(8)
	v_lshlrev_b32_e32 v169, 16, v176
	v_and_b32_e32 v176, 0xffff0000, v176
	v_lshlrev_b32_e32 v186, 16, v177
	v_and_b32_e32 v177, 0xffff0000, v177
	v_lshlrev_b32_e32 v187, 16, v178
	v_and_b32_e32 v178, 0xffff0000, v178
	v_lshlrev_b32_e32 v188, 16, v179
	v_and_b32_e32 v179, 0xffff0000, v179
	v_add_f32_e32 v169, v118, v169
	v_add_f32_e32 v176, v119, v176
	v_add_f32_e32 v186, v120, v186
	v_add_f32_e32 v177, v121, v177
	v_add_f32_e32 v187, v114, v187
	v_add_f32_e32 v178, v115, v178
	v_add_f32_e32 v188, v116, v188
	v_add_f32_e32 v179, v117, v179
	v_mul_f32_e32 v169, 0xbfb8aa3b, v169
	v_mul_f32_e32 v176, 0xbfb8aa3b, v176
	v_mul_f32_e32 v186, 0xbfb8aa3b, v186
	v_mul_f32_e32 v177, 0xbfb8aa3b, v177
	v_mul_f32_e32 v187, 0xbfb8aa3b, v187
	v_mul_f32_e32 v178, 0xbfb8aa3b, v178
	v_mul_f32_e32 v188, 0xbfb8aa3b, v188
	v_mul_f32_e32 v179, 0xbfb8aa3b, v179
	v_exp_f32_e32 v169, v169
	v_exp_f32_e32 v176, v176
	v_exp_f32_e32 v186, v186
	v_exp_f32_e32 v177, v177
	v_exp_f32_e32 v187, v187
	v_exp_f32_e32 v178, v178
	v_exp_f32_e32 v188, v188
	v_exp_f32_e32 v179, v179
	v_add_f32_e32 v169, 1.0, v169
	v_add_f32_e32 v176, 1.0, v176
	v_add_f32_e32 v186, 1.0, v186
	v_add_f32_e32 v177, 1.0, v177
	v_add_f32_e32 v187, 1.0, v187
	v_add_f32_e32 v178, 1.0, v178
	v_add_f32_e32 v188, 1.0, v188
	v_add_f32_e32 v179, 1.0, v179
	v_rcp_f32_e32 v169, v169
	v_rcp_f32_e32 v176, v176
	v_rcp_f32_e32 v186, v186
	v_rcp_f32_e32 v177, v177
	v_rcp_f32_e32 v187, v187
	v_rcp_f32_e32 v178, v178
	v_rcp_f32_e32 v188, v188
	v_rcp_f32_e32 v179, v179
	v_lshlrev_b32_e32 v189, 16, v180
	v_and_b32_e32 v180, 0xffff0000, v180
	v_lshlrev_b32_e32 v190, 16, v181
	v_and_b32_e32 v181, 0xffff0000, v181
	v_lshlrev_b32_e32 v191, 16, v182
	v_and_b32_e32 v182, 0xffff0000, v182
	v_lshlrev_b32_e32 v192, 16, v183
	v_and_b32_e32 v183, 0xffff0000, v183
	v_fmac_f32_e32 v189, v134, v169
	v_fmac_f32_e32 v180, v135, v176
	v_fmac_f32_e32 v190, v136, v186
	v_fmac_f32_e32 v181, v137, v177
	v_fmac_f32_e32 v191, v130, v187
	v_fmac_f32_e32 v182, v131, v178
	v_fmac_f32_e32 v192, v132, v188
	v_fmac_f32_e32 v183, v133, v179
	v_cvt_pk_bf16_f32 v130, v189, v180
	v_cvt_pk_bf16_f32 v131, v190, v181
	v_cvt_pk_bf16_f32 v132, v191, v182
	v_cvt_pk_bf16_f32 v133, v192, v183
	global_store_dwordx4 v[154:155], v[130:133], off
	s_nop 0
	v_or_b32_e32 v180, 32, v168
	v_lshlrev_b64 v[130:131], 11, v[184:185]
	v_lshl_add_u64 v[130:131], s[10:11], 0, v[130:131]
	v_lshl_add_u64 v[130:131], v[130:131], 0, v[166:167]
	s_nop 0
	v_ashrrev_i32_e32 v181, 31, v180
	v_lshlrev_b64 v[132:133], 10, v[180:181]
	v_lshl_add_u64 v[132:133], v[170:171], 0, v[132:133]
	s_waitcnt vmcnt(8)
; __device__ __forceinline__ unsigned cvt_pk_bf16(float lo, float hi) { unsigned r; asm volatile("v_cvt_pk_bf16_f32 %0, %1, %2" : "=v"(r) : "v"(lo), "v"(hi)); return r; }
; __device__ __forceinline__ float bflo(unsigned u) { return __uint_as_float(u << 16); }
; __device__ __forceinline__ float bfhi(unsigned u) { return __uint_as_float(u & 0xffff0000u); }
; __device__ __forceinline__ float sigm(float v) { return __builtin_amdgcn_rcpf(1.0f + __expf(-v)); }
; DI float bflo(unsigned u) { return __uint_as_float(u << 16); }
; DI float bfhi(unsigned u) { return __uint_as_float(u & 0xffff0000u); }
;     __device__ __forceinline__ void operator()(const f32x4 (&acc)[2][2][4][2], const Unit& u, int wr, int wc, int fr, int fq) const {
;     ...
;                 for (int m = 0; m < 4; ++m) { const size_t row = (size_t)(row0 + ai * HALF + m * 16);
;                     const u32x4 g = *(const u32x4*)(gbase + row * 512 + gcol0 + bj * HALF);
;                     const f32x4 v0 = acc[ai][bj][m][0], v1 = acc[ai][bj][m][1];
;                     float r0 = v0[0] * sigm(bflo(g.x) + b0[0]), r1 = v0[1] * sigm(bfhi(g.x) + b0[1]), r2 = v0[2] * sigm(bflo(g.y) + b0[2]), r3 = v0[3] * sigm(bfhi(g.y) + b0[3]);
;                     float r4 = v1[0] * sigm(bflo(g.z) + b1[0]), r5 = v1[1] * sigm(bfhi(g.z) + b1[1]), r6 = v1[2] * sigm(bflo(g.w) + b1[2]), r7 = v1[3] * sigm(bfhi(g.w) + b1[3]);
;                     bf16_t* op = Mo + row * 1024 + col0 + bj * HALF;
;                     if (accum) { const u32x4 p = *(const u32x4*)op; r0 += bflo(p.x); r1 += bfhi(p.x); r2 += bflo(p.y); r3 += bfhi(p.y); r4 += bflo(p.z); r5 += bfhi(p.z); r6 += bflo(p.w); r7 += bfhi(p.w); }
;                     u32x4 w; w.x = cvt_pk_bf16(r0, r1); w.y = cvt_pk_bf16(r2, r3); w.z = cvt_pk_bf16(r4, r5); w.w = cvt_pk_bf16(r6, r7);
;                     *(u32x4*)op = w; }
	v_lshlrev_b32_e32 v169, 16, v204
	v_and_b32_e32 v134, 0xffff0000, v204
	v_lshlrev_b32_e32 v182, 16, v205
	v_and_b32_e32 v135, 0xffff0000, v205
	v_lshlrev_b32_e32 v183, 16, v206
	v_and_b32_e32 v136, 0xffff0000, v206
	v_lshlrev_b32_e32 v184, 16, v207
	v_and_b32_e32 v137, 0xffff0000, v207
	s_mov_b64 s[98:99], 0x20000
	v_lshl_add_u64 v[248:249], v[250:251], 0, s[98:99]
	global_load_dwordx4 v[204:207], v[248:249], off
	v_add_f32_e32 v169, v118, v169
	v_add_f32_e32 v134, v119, v134
	v_add_f32_e32 v182, v120, v182
	v_add_f32_e32 v135, v121, v135
	v_add_f32_e32 v183, v114, v183
	v_add_f32_e32 v136, v115, v136
	v_add_f32_e32 v184, v116, v184
	v_add_f32_e32 v137, v117, v137
	v_mul_f32_e32 v169, 0xbfb8aa3b, v169
	v_mul_f32_e32 v134, 0xbfb8aa3b, v134
	v_mul_f32_e32 v182, 0xbfb8aa3b, v182
	v_mul_f32_e32 v135, 0xbfb8aa3b, v135
	v_mul_f32_e32 v183, 0xbfb8aa3b, v183
	v_mul_f32_e32 v136, 0xbfb8aa3b, v136
	v_mul_f32_e32 v184, 0xbfb8aa3b, v184
	v_mul_f32_e32 v137, 0xbfb8aa3b, v137
	v_exp_f32_e32 v169, v169
	v_exp_f32_e32 v134, v134
	v_exp_f32_e32 v182, v182
	v_exp_f32_e32 v135, v135
	v_exp_f32_e32 v183, v183
	v_exp_f32_e32 v136, v136
	v_exp_f32_e32 v184, v184
	v_exp_f32_e32 v137, v137
	v_add_f32_e32 v169, 1.0, v169
	v_add_f32_e32 v134, 1.0, v134
	v_add_f32_e32 v182, 1.0, v182
	v_add_f32_e32 v135, 1.0, v135
	v_add_f32_e32 v183, 1.0, v183
	v_add_f32_e32 v136, 1.0, v136
	v_add_f32_e32 v184, 1.0, v184
	v_add_f32_e32 v137, 1.0, v137
	v_rcp_f32_e32 v169, v169
	v_rcp_f32_e32 v134, v134
	v_rcp_f32_e32 v182, v182
	v_rcp_f32_e32 v135, v135
	v_rcp_f32_e32 v183, v183
	v_rcp_f32_e32 v136, v136
	v_rcp_f32_e32 v184, v184
	v_rcp_f32_e32 v137, v137
	s_waitcnt vmcnt(8)
	v_lshlrev_b32_e32 v185, 16, v216
	v_and_b32_e32 v176, 0xffff0000, v216
	v_lshlrev_b32_e32 v186, 16, v217
	v_and_b32_e32 v177, 0xffff0000, v217
	v_lshlrev_b32_e32 v187, 16, v218
	v_and_b32_e32 v178, 0xffff0000, v218
	v_lshlrev_b32_e32 v188, 16, v219
	v_and_b32_e32 v179, 0xffff0000, v219
	s_mov_b64 s[98:99], 0x40000
	v_lshl_add_u64 v[248:249], v[252:253], 0, s[98:99]
	global_load_dwordx4 v[216:219], v[248:249], off
	v_fmac_f32_e32 v185, v126, v169
	v_fmac_f32_e32 v176, v127, v134
	v_fmac_f32_e32 v186, v128, v182
	v_fmac_f32_e32 v177, v129, v135
	v_fmac_f32_e32 v187, v122, v183
	v_fmac_f32_e32 v178, v123, v136
	v_fmac_f32_e32 v188, v124, v184
	v_fmac_f32_e32 v179, v125, v137
	v_cvt_pk_bf16_f32 v122, v185, v176
	v_cvt_pk_bf16_f32 v123, v186, v177
	v_cvt_pk_bf16_f32 v124, v187, v178
	v_cvt_pk_bf16_f32 v125, v188, v179
	global_store_dwordx4 v[130:131], v[122:125], off
	s_nop 0
	v_or_b32_e32 v176, 48, v168
	v_lshlrev_b64 v[122:123], 11, v[180:181]
	v_lshl_add_u64 v[122:123], s[10:11], 0, v[122:123]
	v_lshl_add_u64 v[122:123], v[122:123], 0, v[166:167]
	s_nop 0
	v_ashrrev_i32_e32 v177, 31, v176
	v_lshlrev_b64 v[124:125], 10, v[176:177]
	v_lshl_add_u64 v[124:125], v[170:171], 0, v[124:125]
	s_waitcnt vmcnt(9)
	v_lshlrev_b32_e32 v169, 16, v208
	v_and_b32_e32 v126, 0xffff0000, v208
	v_lshlrev_b32_e32 v178, 16, v209
	v_and_b32_e32 v127, 0xffff0000, v209
	v_lshlrev_b32_e32 v179, 16, v210
	v_and_b32_e32 v128, 0xffff0000, v210
	v_lshlrev_b32_e32 v180, 16, v211
	v_and_b32_e32 v129, 0xffff0000, v211
	s_mov_b64 s[98:99], 0x24000
	v_lshl_add_u64 v[248:249], v[250:251], 0, s[98:99]
	global_load_dwordx4 v[208:211], v[248:249], off
	v_add_f32_e32 v169, v118, v169
	v_add_f32_e32 v126, v119, v126
	v_add_f32_e32 v178, v120, v178
	v_add_f32_e32 v127, v121, v127
	v_add_f32_e32 v179, v114, v179
	v_add_f32_e32 v128, v115, v128
	v_add_f32_e32 v180, v116, v180
	v_add_f32_e32 v129, v117, v129
	v_mul_f32_e32 v169, 0xbfb8aa3b, v169
	v_mul_f32_e32 v126, 0xbfb8aa3b, v126
	v_mul_f32_e32 v178, 0xbfb8aa3b, v178
	v_mul_f32_e32 v127, 0xbfb8aa3b, v127
	v_mul_f32_e32 v179, 0xbfb8aa3b, v179
	v_mul_f32_e32 v128, 0xbfb8aa3b, v128
	v_mul_f32_e32 v180, 0xbfb8aa3b, v180
	v_mul_f32_e32 v129, 0xbfb8aa3b, v129
	v_exp_f32_e32 v169, v169
	v_exp_f32_e32 v126, v126
	v_exp_f32_e32 v178, v178
	v_exp_f32_e32 v127, v127
	v_exp_f32_e32 v179, v179
	v_exp_f32_e32 v128, v128
	v_exp_f32_e32 v180, v180
	v_exp_f32_e32 v129, v129
	v_add_f32_e32 v169, 1.0, v169
	v_add_f32_e32 v126, 1.0, v126
	v_add_f32_e32 v178, 1.0, v178
	v_add_f32_e32 v127, 1.0, v127
	v_add_f32_e32 v179, 1.0, v179
	v_add_f32_e32 v128, 1.0, v128
	v_add_f32_e32 v180, 1.0, v180
	v_add_f32_e32 v129, 1.0, v129
	v_rcp_f32_e32 v169, v169
	v_rcp_f32_e32 v126, v126
	v_rcp_f32_e32 v178, v178
	v_rcp_f32_e32 v127, v127
	v_rcp_f32_e32 v179, v179
	v_rcp_f32_e32 v128, v128
	v_rcp_f32_e32 v180, v180
	v_rcp_f32_e32 v129, v129
	s_waitcnt vmcnt(9)
	v_lshlrev_b32_e32 v181, 16, v220
	v_and_b32_e32 v134, 0xffff0000, v220
	v_lshlrev_b32_e32 v182, 16, v221
	v_and_b32_e32 v135, 0xffff0000, v221
	v_lshlrev_b32_e32 v183, 16, v222
	v_and_b32_e32 v136, 0xffff0000, v222
	v_lshlrev_b32_e32 v184, 16, v223
	v_and_b32_e32 v137, 0xffff0000, v223
	s_mov_b64 s[98:99], 0x48000
	v_lshl_add_u64 v[248:249], v[252:253], 0, s[98:99]
	global_load_dwordx4 v[220:223], v[248:249], off
	v_fmac_f32_e32 v181, v110, v169
	v_fmac_f32_e32 v134, v111, v126
	v_fmac_f32_e32 v182, v112, v178
	v_fmac_f32_e32 v135, v113, v127
	v_fmac_f32_e32 v183, v106, v179
	v_fmac_f32_e32 v136, v107, v128
	v_fmac_f32_e32 v184, v108, v180
	v_fmac_f32_e32 v137, v109, v129
	v_cvt_pk_bf16_f32 v106, v181, v134
	v_cvt_pk_bf16_f32 v107, v182, v135
	v_cvt_pk_bf16_f32 v108, v183, v136
	v_cvt_pk_bf16_f32 v109, v184, v137
	global_store_dwordx4 v[122:123], v[106:109], off
	s_nop 0
	v_add_u32_e32 v134, 0x80, v168
	v_lshlrev_b64 v[106:107], 11, v[176:177]
	v_lshl_add_u64 v[106:107], s[10:11], 0, v[106:107]
	v_lshl_add_u64 v[106:107], v[106:107], 0, v[166:167]
	s_nop 0
	v_ashrrev_i32_e32 v135, 31, v134
	v_lshlrev_b64 v[108:109], 10, v[134:135]
	v_lshl_add_u64 v[108:109], v[170:171], 0, v[108:109]
	s_waitcnt vmcnt(10)
; __device__ __forceinline__ unsigned cvt_pk_bf16(float lo, float hi) { unsigned r; asm volatile("v_cvt_pk_bf16_f32 %0, %1, %2" : "=v"(r) : "v"(lo), "v"(hi)); return r; }
; __device__ __forceinline__ float bflo(unsigned u) { return __uint_as_float(u << 16); }
; __device__ __forceinline__ float bfhi(unsigned u) { return __uint_as_float(u & 0xffff0000u); }
; __device__ __forceinline__ float sigm(float v) { return __builtin_amdgcn_rcpf(1.0f + __expf(-v)); }
; DI float bflo(unsigned u) { return __uint_as_float(u << 16); }
; DI float bfhi(unsigned u) { return __uint_as_float(u & 0xffff0000u); }
;     __device__ __forceinline__ void operator()(const f32x4 (&acc)[2][2][4][2], const Unit& u, int wr, int wc, int fr, int fq) const {
;     ...
;                 for (int m = 0; m < 4; ++m) { const size_t row = (size_t)(row0 + ai * HALF + m * 16);
;                     const u32x4 g = *(const u32x4*)(gbase + row * 512 + gcol0 + bj * HALF);
;                     const f32x4 v0 = acc[ai][bj][m][0], v1 = acc[ai][bj][m][1];
;                     float r0 = v0[0] * sigm(bflo(g.x) + b0[0]), r1 = v0[1] * sigm(bfhi(g.x) + b0[1]), r2 = v0[2] * sigm(bflo(g.y) + b0[2]), r3 = v0[3] * sigm(bfhi(g.y) + b0[3]);
;                     float r4 = v1[0] * sigm(bflo(g.z) + b1[0]), r5 = v1[1] * sigm(bfhi(g.z) + b1[1]), r6 = v1[2] * sigm(bflo(g.w) + b1[2]), r7 = v1[3] * sigm(bfhi(g.w) + b1[3]);
;                     bf16_t* op = Mo + row * 1024 + col0 + bj * HALF;
;                     if (accum) { const u32x4 p = *(const u32x4*)op; r0 += bflo(p.x); r1 += bfhi(p.x); r2 += bflo(p.y); r3 += bfhi(p.y); r4 += bflo(p.z); r5 += bfhi(p.z); r6 += bflo(p.w); r7 += bfhi(p.w); }
;                     u32x4 w; w.x = cvt_pk_bf16(r0, r1); w.y = cvt_pk_bf16(r2, r3); w.z = cvt_pk_bf16(r4, r5); w.w = cvt_pk_bf16(r6, r7);
;                     *(u32x4*)op = w; }
	v_lshlrev_b32_e32 v136, 16, v212
	v_and_b32_e32 v110, 0xffff0000, v212
	v_lshlrev_b32_e32 v137, 16, v213
	v_and_b32_e32 v111, 0xffff0000, v213
	v_lshlrev_b32_e32 v169, 16, v214
	v_and_b32_e32 v112, 0xffff0000, v214
	v_lshlrev_b32_e32 v176, 16, v215
	v_and_b32_e32 v113, 0xffff0000, v215
	s_mov_b64 s[98:99], 0x28000
	v_lshl_add_u64 v[248:249], v[250:251], 0, s[98:99]
	global_load_dwordx4 v[212:215], v[248:249], off
	v_add_f32_e32 v136, v118, v136
	v_add_f32_e32 v110, v119, v110
	v_add_f32_e32 v137, v120, v137
	v_add_f32_e32 v111, v121, v111
	v_add_f32_e32 v169, v114, v169
	v_add_f32_e32 v112, v115, v112
	v_add_f32_e32 v176, v116, v176
	v_add_f32_e32 v113, v117, v113
	v_mul_f32_e32 v136, 0xbfb8aa3b, v136
	v_mul_f32_e32 v110, 0xbfb8aa3b, v110
	v_mul_f32_e32 v137, 0xbfb8aa3b, v137
	v_mul_f32_e32 v111, 0xbfb8aa3b, v111
	v_mul_f32_e32 v169, 0xbfb8aa3b, v169
	v_mul_f32_e32 v112, 0xbfb8aa3b, v112
	v_mul_f32_e32 v176, 0xbfb8aa3b, v176
	v_mul_f32_e32 v113, 0xbfb8aa3b, v113
	v_exp_f32_e32 v136, v136
	v_exp_f32_e32 v110, v110
	v_exp_f32_e32 v137, v137
	v_exp_f32_e32 v111, v111
	v_exp_f32_e32 v169, v169
	v_exp_f32_e32 v112, v112
	v_exp_f32_e32 v176, v176
	v_exp_f32_e32 v113, v113
	v_add_f32_e32 v136, 1.0, v136
	v_add_f32_e32 v110, 1.0, v110
	v_add_f32_e32 v137, 1.0, v137
	v_add_f32_e32 v111, 1.0, v111
	v_add_f32_e32 v169, 1.0, v169
	v_add_f32_e32 v112, 1.0, v112
	v_add_f32_e32 v176, 1.0, v176
	v_add_f32_e32 v113, 1.0, v113
	v_rcp_f32_e32 v136, v136
	v_rcp_f32_e32 v110, v110
	v_rcp_f32_e32 v137, v137
	v_rcp_f32_e32 v111, v111
	v_rcp_f32_e32 v169, v169
	v_rcp_f32_e32 v112, v112
	v_rcp_f32_e32 v176, v176
	v_rcp_f32_e32 v113, v113
	s_waitcnt vmcnt(10)
	v_lshlrev_b32_e32 v177, 16, v224
	v_and_b32_e32 v126, 0xffff0000, v224
	v_lshlrev_b32_e32 v178, 16, v225
	v_and_b32_e32 v127, 0xffff0000, v225
	v_lshlrev_b32_e32 v179, 16, v226
	v_and_b32_e32 v128, 0xffff0000, v226
	v_lshlrev_b32_e32 v180, 16, v227
	v_and_b32_e32 v129, 0xffff0000, v227
	s_mov_b64 s[98:99], 0x50000
	v_lshl_add_u64 v[248:249], v[252:253], 0, s[98:99]
	global_load_dwordx4 v[224:227], v[248:249], off
	v_fmac_f32_e32 v177, v102, v136
	v_fmac_f32_e32 v126, v103, v110
	v_fmac_f32_e32 v178, v104, v137
	v_fmac_f32_e32 v127, v105, v111
	v_fmac_f32_e32 v179, v98, v169
	v_fmac_f32_e32 v128, v99, v112
	v_fmac_f32_e32 v180, v100, v176
	v_fmac_f32_e32 v129, v101, v113
	v_cvt_pk_bf16_f32 v98, v177, v126
	v_cvt_pk_bf16_f32 v99, v178, v127
	v_cvt_pk_bf16_f32 v100, v179, v128
	v_cvt_pk_bf16_f32 v101, v180, v129
	global_store_dwordx4 v[106:107], v[98:101], off
	s_nop 0
	v_add_u32_e32 v126, 0x90, v168
	v_lshlrev_b64 v[98:99], 11, v[134:135]
	v_lshl_add_u64 v[98:99], s[10:11], 0, v[98:99]
	v_lshl_add_u64 v[98:99], v[98:99], 0, v[166:167]
	s_nop 0
	v_ashrrev_i32_e32 v127, 31, v126
	v_lshlrev_b64 v[100:101], 10, v[126:127]
	v_lshl_add_u64 v[100:101], v[170:171], 0, v[100:101]
	s_waitcnt vmcnt(8)
	v_lshlrev_b32_e32 v128, 16, v204
	v_and_b32_e32 v102, 0xffff0000, v204
	v_lshlrev_b32_e32 v129, 16, v205
	v_and_b32_e32 v103, 0xffff0000, v205
	v_lshlrev_b32_e32 v134, 16, v206
	v_and_b32_e32 v104, 0xffff0000, v206
	v_lshlrev_b32_e32 v135, 16, v207
	v_and_b32_e32 v105, 0xffff0000, v207
	s_mov_b64 s[98:99], 0x2c000
	v_lshl_add_u64 v[248:249], v[250:251], 0, s[98:99]
	global_load_dwordx4 v[204:207], v[248:249], off
	v_add_f32_e32 v128, v118, v128
	v_add_f32_e32 v102, v119, v102
	v_add_f32_e32 v129, v120, v129
	v_add_f32_e32 v103, v121, v103
	v_add_f32_e32 v134, v114, v134
	v_add_f32_e32 v104, v115, v104
	v_add_f32_e32 v135, v116, v135
	v_add_f32_e32 v105, v117, v105
	v_mul_f32_e32 v128, 0xbfb8aa3b, v128
	v_mul_f32_e32 v102, 0xbfb8aa3b, v102
	v_mul_f32_e32 v129, 0xbfb8aa3b, v129
	v_mul_f32_e32 v103, 0xbfb8aa3b, v103
	v_mul_f32_e32 v134, 0xbfb8aa3b, v134
	v_mul_f32_e32 v104, 0xbfb8aa3b, v104
	v_mul_f32_e32 v135, 0xbfb8aa3b, v135
	v_mul_f32_e32 v105, 0xbfb8aa3b, v105
	v_exp_f32_e32 v128, v128
	v_exp_f32_e32 v102, v102
	v_exp_f32_e32 v129, v129
	v_exp_f32_e32 v103, v103
	v_exp_f32_e32 v134, v134
	v_exp_f32_e32 v104, v104
	v_exp_f32_e32 v135, v135
	v_exp_f32_e32 v105, v105
	v_add_f32_e32 v128, 1.0, v128
	v_add_f32_e32 v102, 1.0, v102
	v_add_f32_e32 v129, 1.0, v129
	v_add_f32_e32 v103, 1.0, v103
	v_add_f32_e32 v134, 1.0, v134
	v_add_f32_e32 v104, 1.0, v104
	v_add_f32_e32 v135, 1.0, v135
	v_add_f32_e32 v105, 1.0, v105
	v_rcp_f32_e32 v128, v128
	v_rcp_f32_e32 v102, v102
	v_rcp_f32_e32 v129, v129
	v_rcp_f32_e32 v103, v103
	v_rcp_f32_e32 v134, v134
	v_rcp_f32_e32 v104, v104
	v_rcp_f32_e32 v135, v135
	v_rcp_f32_e32 v105, v105
	s_waitcnt vmcnt(8)
	v_lshlrev_b32_e32 v136, 16, v216
	v_and_b32_e32 v110, 0xffff0000, v216
	v_lshlrev_b32_e32 v137, 16, v217
	v_and_b32_e32 v111, 0xffff0000, v217
	v_lshlrev_b32_e32 v169, 16, v218
	v_and_b32_e32 v112, 0xffff0000, v218
	v_lshlrev_b32_e32 v176, 16, v219
	v_and_b32_e32 v113, 0xffff0000, v219
	s_mov_b64 s[98:99], 0x58000
	v_lshl_add_u64 v[248:249], v[252:253], 0, s[98:99]
	global_load_dwordx4 v[216:219], v[248:249], off
	v_fmac_f32_e32 v136, v94, v128
	v_fmac_f32_e32 v110, v95, v102
	v_fmac_f32_e32 v137, v96, v129
	v_fmac_f32_e32 v111, v97, v103
	v_fmac_f32_e32 v169, v90, v134
	v_fmac_f32_e32 v112, v91, v104
	v_fmac_f32_e32 v176, v92, v135
	v_fmac_f32_e32 v113, v93, v105
	v_cvt_pk_bf16_f32 v90, v136, v110
	v_cvt_pk_bf16_f32 v91, v137, v111
	v_cvt_pk_bf16_f32 v92, v169, v112
	v_cvt_pk_bf16_f32 v93, v176, v113
	global_store_dwordx4 v[98:99], v[90:93], off
	s_nop 0
	v_add_u32_e32 v110, 0xa0, v168
	v_lshlrev_b64 v[90:91], 11, v[126:127]
	v_lshl_add_u64 v[90:91], s[10:11], 0, v[90:91]
	v_lshl_add_u64 v[90:91], v[90:91], 0, v[166:167]
	s_nop 0
	v_ashrrev_i32_e32 v111, 31, v110
	v_lshlrev_b64 v[92:93], 10, v[110:111]
	v_lshl_add_u64 v[92:93], v[170:171], 0, v[92:93]
	s_waitcnt vmcnt(8)
; __device__ __forceinline__ unsigned cvt_pk_bf16(float lo, float hi) { unsigned r; asm volatile("v_cvt_pk_bf16_f32 %0, %1, %2" : "=v"(r) : "v"(lo), "v"(hi)); return r; }
; __device__ __forceinline__ float bflo(unsigned u) { return __uint_as_float(u << 16); }
; __device__ __forceinline__ float bfhi(unsigned u) { return __uint_as_float(u & 0xffff0000u); }
; __device__ __forceinline__ float sigm(float v) { return __builtin_amdgcn_rcpf(1.0f + __expf(-v)); }
; DI float bflo(unsigned u) { return __uint_as_float(u << 16); }
; DI float bfhi(unsigned u) { return __uint_as_float(u & 0xffff0000u); }
;     __device__ __forceinline__ void operator()(const f32x4 (&acc)[2][2][4][2], const Unit& u, int wr, int wc, int fr, int fq) const {
;     ...
;                 for (int m = 0; m < 4; ++m) { const size_t row = (size_t)(row0 + ai * HALF + m * 16);
;                     const u32x4 g = *(const u32x4*)(gbase + row * 512 + gcol0 + bj * HALF);
;                     const f32x4 v0 = acc[ai][bj][m][0], v1 = acc[ai][bj][m][1];
;                     float r0 = v0[0] * sigm(bflo(g.x) + b0[0]), r1 = v0[1] * sigm(bfhi(g.x) + b0[1]), r2 = v0[2] * sigm(bflo(g.y) + b0[2]), r3 = v0[3] * sigm(bfhi(g.y) + b0[3]);
;                     float r4 = v1[0] * sigm(bflo(g.z) + b1[0]), r5 = v1[1] * sigm(bfhi(g.z) + b1[1]), r6 = v1[2] * sigm(bflo(g.w) + b1[2]), r7 = v1[3] * sigm(bfhi(g.w) + b1[3]);
;                     bf16_t* op = Mo + row * 1024 + col0 + bj * HALF;
;                     if (accum) { const u32x4 p = *(const u32x4*)op; r0 += bflo(p.x); r1 += bfhi(p.x); r2 += bflo(p.y); r3 += bfhi(p.y); r4 += bflo(p.z); r5 += bfhi(p.z); r6 += bflo(p.w); r7 += bfhi(p.w); }
;                     u32x4 w; w.x = cvt_pk_bf16(r0, r1); w.y = cvt_pk_bf16(r2, r3); w.z = cvt_pk_bf16(r4, r5); w.w = cvt_pk_bf16(r6, r7);
;                     *(u32x4*)op = w; }
	v_lshlrev_b32_e32 v112, 16, v208
	v_and_b32_e32 v94, 0xffff0000, v208
	v_lshlrev_b32_e32 v113, 16, v209
	v_and_b32_e32 v95, 0xffff0000, v209
	v_lshlrev_b32_e32 v126, 16, v210
	v_and_b32_e32 v96, 0xffff0000, v210
	v_lshlrev_b32_e32 v127, 16, v211
	v_and_b32_e32 v97, 0xffff0000, v211
	global_load_dwordx4 v[208:211], v[250:251], off offset:256
	v_add_f32_e32 v112, v118, v112
	v_add_f32_e32 v94, v119, v94
	v_add_f32_e32 v113, v120, v113
	v_add_f32_e32 v95, v121, v95
	v_add_f32_e32 v126, v114, v126
	v_add_f32_e32 v96, v115, v96
	v_add_f32_e32 v127, v116, v127
	v_add_f32_e32 v97, v117, v97
	v_mul_f32_e32 v112, 0xbfb8aa3b, v112
	v_mul_f32_e32 v94, 0xbfb8aa3b, v94
	v_mul_f32_e32 v113, 0xbfb8aa3b, v113
	v_mul_f32_e32 v95, 0xbfb8aa3b, v95
	v_mul_f32_e32 v126, 0xbfb8aa3b, v126
	v_mul_f32_e32 v96, 0xbfb8aa3b, v96
	v_mul_f32_e32 v127, 0xbfb8aa3b, v127
	v_mul_f32_e32 v97, 0xbfb8aa3b, v97
	v_exp_f32_e32 v112, v112
	v_exp_f32_e32 v94, v94
	v_exp_f32_e32 v113, v113
	v_exp_f32_e32 v95, v95
	v_exp_f32_e32 v126, v126
	v_exp_f32_e32 v96, v96
	v_exp_f32_e32 v127, v127
	v_exp_f32_e32 v97, v97
	v_add_f32_e32 v112, 1.0, v112
	v_add_f32_e32 v94, 1.0, v94
	v_add_f32_e32 v113, 1.0, v113
	v_add_f32_e32 v95, 1.0, v95
	v_add_f32_e32 v126, 1.0, v126
	v_add_f32_e32 v96, 1.0, v96
	v_add_f32_e32 v127, 1.0, v127
	v_add_f32_e32 v97, 1.0, v97
	v_rcp_f32_e32 v112, v112
	v_rcp_f32_e32 v94, v94
	v_rcp_f32_e32 v113, v113
	v_rcp_f32_e32 v95, v95
	v_rcp_f32_e32 v126, v126
	v_rcp_f32_e32 v96, v96
	v_rcp_f32_e32 v127, v127
	v_rcp_f32_e32 v97, v97
	s_waitcnt vmcnt(8)
	v_lshlrev_b32_e32 v128, 16, v220
	v_and_b32_e32 v102, 0xffff0000, v220
	v_lshlrev_b32_e32 v129, 16, v221
	v_and_b32_e32 v103, 0xffff0000, v221
	v_lshlrev_b32_e32 v134, 16, v222
	v_and_b32_e32 v104, 0xffff0000, v222
	v_lshlrev_b32_e32 v135, 16, v223
	v_and_b32_e32 v105, 0xffff0000, v223
	global_load_dwordx4 v[220:223], v[252:253], off offset:256
	v_fmac_f32_e32 v128, v86, v112
	v_fmac_f32_e32 v102, v87, v94
	v_fmac_f32_e32 v129, v88, v113
	v_fmac_f32_e32 v103, v89, v95
	v_fmac_f32_e32 v134, v82, v126
	v_fmac_f32_e32 v104, v83, v96
	v_fmac_f32_e32 v135, v84, v127
	v_fmac_f32_e32 v105, v85, v97
	v_cvt_pk_bf16_f32 v82, v128, v102
	v_cvt_pk_bf16_f32 v83, v129, v103
	v_cvt_pk_bf16_f32 v84, v134, v104
	v_cvt_pk_bf16_f32 v85, v135, v105
	global_store_dwordx4 v[90:91], v[82:85], off
	s_nop 0
	v_add_u32_e32 v102, 0xb0, v168
	v_lshlrev_b64 v[82:83], 11, v[110:111]
	v_lshl_add_u64 v[82:83], s[10:11], 0, v[82:83]
	v_lshl_add_u64 v[82:83], v[82:83], 0, v[166:167]
	s_nop 0
	v_ashrrev_i32_e32 v103, 31, v102
	v_lshlrev_b64 v[84:85], 10, v[102:103]
	v_lshl_add_u64 v[84:85], v[170:171], 0, v[84:85]
	s_waitcnt vmcnt(8)
	v_lshlrev_b32_e32 v104, 16, v212
	v_and_b32_e32 v86, 0xffff0000, v212
	v_lshlrev_b32_e32 v105, 16, v213
	v_and_b32_e32 v87, 0xffff0000, v213
	v_lshlrev_b32_e32 v110, 16, v214
	v_and_b32_e32 v88, 0xffff0000, v214
	v_lshlrev_b32_e32 v111, 16, v215
	v_and_b32_e32 v89, 0xffff0000, v215
	s_mov_b64 s[98:99], 0x4000
	v_lshl_add_u64 v[248:249], v[250:251], 0, s[98:99]
	global_load_dwordx4 v[212:215], v[248:249], off offset:256
	v_add_f32_e32 v104, v118, v104
	v_add_f32_e32 v86, v119, v86
	v_add_f32_e32 v105, v120, v105
	v_add_f32_e32 v87, v121, v87
	v_add_f32_e32 v110, v114, v110
	v_add_f32_e32 v88, v115, v88
	v_add_f32_e32 v111, v116, v111
	v_add_f32_e32 v89, v117, v89
	v_mul_f32_e32 v104, 0xbfb8aa3b, v104
	v_mul_f32_e32 v86, 0xbfb8aa3b, v86
	v_mul_f32_e32 v105, 0xbfb8aa3b, v105
	v_mul_f32_e32 v87, 0xbfb8aa3b, v87
	v_mul_f32_e32 v110, 0xbfb8aa3b, v110
	v_mul_f32_e32 v88, 0xbfb8aa3b, v88
	v_mul_f32_e32 v111, 0xbfb8aa3b, v111
	v_mul_f32_e32 v89, 0xbfb8aa3b, v89
	v_exp_f32_e32 v104, v104
	v_exp_f32_e32 v86, v86
	v_exp_f32_e32 v105, v105
	v_exp_f32_e32 v87, v87
	v_exp_f32_e32 v110, v110
	v_exp_f32_e32 v88, v88
	v_exp_f32_e32 v111, v111
	v_exp_f32_e32 v89, v89
	v_add_f32_e32 v104, 1.0, v104
	v_add_f32_e32 v86, 1.0, v86
	v_add_f32_e32 v105, 1.0, v105
	v_add_f32_e32 v87, 1.0, v87
	v_add_f32_e32 v110, 1.0, v110
	v_add_f32_e32 v88, 1.0, v88
	v_add_f32_e32 v111, 1.0, v111
	v_add_f32_e32 v89, 1.0, v89
	v_rcp_f32_e32 v104, v104
	v_rcp_f32_e32 v86, v86
	v_rcp_f32_e32 v105, v105
	v_rcp_f32_e32 v87, v87
	v_rcp_f32_e32 v110, v110
	v_rcp_f32_e32 v88, v88
	v_rcp_f32_e32 v111, v111
	v_rcp_f32_e32 v89, v89
	s_waitcnt vmcnt(8)
	v_lshlrev_b32_e32 v112, 16, v224
	v_and_b32_e32 v94, 0xffff0000, v224
	v_lshlrev_b32_e32 v113, 16, v225
	v_and_b32_e32 v95, 0xffff0000, v225
	v_lshlrev_b32_e32 v126, 16, v226
	v_and_b32_e32 v96, 0xffff0000, v226
	v_lshlrev_b32_e32 v127, 16, v227
	v_and_b32_e32 v97, 0xffff0000, v227
	s_mov_b64 s[98:99], 0x8000
	v_lshl_add_u64 v[248:249], v[252:253], 0, s[98:99]
	global_load_dwordx4 v[224:227], v[248:249], off offset:256
	v_fmac_f32_e32 v112, v78, v104
	v_fmac_f32_e32 v94, v79, v86
	v_fmac_f32_e32 v113, v80, v105
	v_fmac_f32_e32 v95, v81, v87
	v_fmac_f32_e32 v126, v74, v110
	v_fmac_f32_e32 v96, v75, v88
	v_fmac_f32_e32 v127, v76, v111
	v_fmac_f32_e32 v97, v77, v89
	v_cvt_pk_bf16_f32 v74, v112, v94
	v_cvt_pk_bf16_f32 v75, v113, v95
	v_cvt_pk_bf16_f32 v76, v126, v96
	v_cvt_pk_bf16_f32 v77, v127, v97
	global_store_dwordx4 v[82:83], v[74:77], off
	s_nop 0
	s_nop 0
	v_lshlrev_b64 v[74:75], 11, v[102:103]
	v_lshl_add_u64 v[74:75], s[10:11], 0, v[74:75]
	v_lshl_add_u64 v[74:75], v[74:75], 0, v[166:167]
	s_nop 0
	s_waitcnt vmcnt(8)
; __device__ __forceinline__ unsigned cvt_pk_bf16(float lo, float hi) { unsigned r; asm volatile("v_cvt_pk_bf16_f32 %0, %1, %2" : "=v"(r) : "v"(lo), "v"(hi)); return r; }
; __device__ __forceinline__ float bflo(unsigned u) { return __uint_as_float(u << 16); }
; __device__ __forceinline__ float bfhi(unsigned u) { return __uint_as_float(u & 0xffff0000u); }
; __device__ __forceinline__ float sigm(float v) { return __builtin_amdgcn_rcpf(1.0f + __expf(-v)); }
; DI float bflo(unsigned u) { return __uint_as_float(u << 16); }
; DI float bfhi(unsigned u) { return __uint_as_float(u & 0xffff0000u); }
;     __device__ __forceinline__ void operator()(const f32x4 (&acc)[2][2][4][2], const Unit& u, int wr, int wc, int fr, int fq) const {
;     ...
;                 for (int m = 0; m < 4; ++m) { const size_t row = (size_t)(row0 + ai * HALF + m * 16);
;                     const u32x4 g = *(const u32x4*)(gbase + row * 512 + gcol0 + bj * HALF);
;                     const f32x4 v0 = acc[ai][bj][m][0], v1 = acc[ai][bj][m][1];
;                     float r0 = v0[0] * sigm(bflo(g.x) + b0[0]), r1 = v0[1] * sigm(bfhi(g.x) + b0[1]), r2 = v0[2] * sigm(bflo(g.y) + b0[2]), r3 = v0[3] * sigm(bfhi(g.y) + b0[3]);
;                     float r4 = v1[0] * sigm(bflo(g.z) + b1[0]), r5 = v1[1] * sigm(bfhi(g.z) + b1[1]), r6 = v1[2] * sigm(bflo(g.w) + b1[2]), r7 = v1[3] * sigm(bfhi(g.w) + b1[3]);
;                     bf16_t* op = Mo + row * 1024 + col0 + bj * HALF;
;                     if (accum) { const u32x4 p = *(const u32x4*)op; r0 += bflo(p.x); r1 += bfhi(p.x); r2 += bflo(p.y); r3 += bfhi(p.y); r4 += bflo(p.z); r5 += bfhi(p.z); r6 += bflo(p.w); r7 += bfhi(p.w); }
;                     u32x4 w; w.x = cvt_pk_bf16(r0, r1); w.y = cvt_pk_bf16(r2, r3); w.z = cvt_pk_bf16(r4, r5); w.w = cvt_pk_bf16(r6, r7);
;                     *(u32x4*)op = w; }
	v_lshlrev_b32_e32 v80, 16, v204
	v_and_b32_e32 v76, 0xffff0000, v204
	v_lshlrev_b32_e32 v81, 16, v205
	v_and_b32_e32 v77, 0xffff0000, v205
	v_lshlrev_b32_e32 v94, 16, v206
	v_and_b32_e32 v78, 0xffff0000, v206
	v_lshlrev_b32_e32 v95, 16, v207
	v_and_b32_e32 v79, 0xffff0000, v207
	s_mov_b64 s[98:99], 0x8000
	v_lshl_add_u64 v[248:249], v[250:251], 0, s[98:99]
	global_load_dwordx4 v[204:207], v[248:249], off offset:256
	v_add_f32_e32 v80, v118, v80
	v_add_f32_e32 v76, v119, v76
	v_add_f32_e32 v81, v120, v81
	v_add_f32_e32 v77, v121, v77
	v_add_f32_e32 v94, v114, v94
	v_add_f32_e32 v78, v115, v78
	v_add_f32_e32 v95, v116, v95
	v_add_f32_e32 v79, v117, v79
	v_mul_f32_e32 v80, 0xbfb8aa3b, v80
	v_mul_f32_e32 v76, 0xbfb8aa3b, v76
	v_mul_f32_e32 v81, 0xbfb8aa3b, v81
	v_mul_f32_e32 v77, 0xbfb8aa3b, v77
	v_mul_f32_e32 v94, 0xbfb8aa3b, v94
	v_mul_f32_e32 v78, 0xbfb8aa3b, v78
	v_mul_f32_e32 v95, 0xbfb8aa3b, v95
	v_mul_f32_e32 v79, 0xbfb8aa3b, v79
	v_exp_f32_e32 v80, v80
	v_exp_f32_e32 v76, v76
	v_exp_f32_e32 v81, v81
	v_exp_f32_e32 v77, v77
	v_exp_f32_e32 v94, v94
	v_exp_f32_e32 v78, v78
	v_exp_f32_e32 v95, v95
	v_exp_f32_e32 v79, v79
	v_add_f32_e32 v80, 1.0, v80
	v_add_f32_e32 v76, 1.0, v76
	v_add_f32_e32 v81, 1.0, v81
	v_add_f32_e32 v77, 1.0, v77
	v_add_f32_e32 v94, 1.0, v94
	v_add_f32_e32 v78, 1.0, v78
	v_add_f32_e32 v95, 1.0, v95
	v_add_f32_e32 v79, 1.0, v79
	v_rcp_f32_e32 v80, v80
	v_rcp_f32_e32 v76, v76
	v_rcp_f32_e32 v81, v81
	v_rcp_f32_e32 v77, v77
	v_rcp_f32_e32 v94, v94
	v_rcp_f32_e32 v78, v78
	v_rcp_f32_e32 v95, v95
	v_rcp_f32_e32 v79, v79
	s_waitcnt vmcnt(8)
	v_lshlrev_b32_e32 v96, 16, v216
	v_and_b32_e32 v86, 0xffff0000, v216
	v_lshlrev_b32_e32 v97, 16, v217
	v_and_b32_e32 v87, 0xffff0000, v217
	v_lshlrev_b32_e32 v102, 16, v218
	v_and_b32_e32 v88, 0xffff0000, v218
	v_lshlrev_b32_e32 v103, 16, v219
	v_and_b32_e32 v89, 0xffff0000, v219
	s_mov_b64 s[98:99], 0x10000
	v_lshl_add_u64 v[248:249], v[252:253], 0, s[98:99]
	global_load_dwordx4 v[216:219], v[248:249], off offset:256
	v_fmac_f32_e32 v96, v70, v80
	v_fmac_f32_e32 v86, v71, v76
	v_fmac_f32_e32 v97, v72, v81
	v_fmac_f32_e32 v87, v73, v77
	v_fmac_f32_e32 v102, v66, v94
	v_fmac_f32_e32 v88, v67, v78
	v_fmac_f32_e32 v103, v68, v95
	v_fmac_f32_e32 v89, v69, v79
	v_cvt_pk_bf16_f32 v66, v96, v86
	v_cvt_pk_bf16_f32 v67, v97, v87
	v_cvt_pk_bf16_f32 v68, v102, v88
	v_cvt_pk_bf16_f32 v69, v103, v89
	global_store_dwordx4 v[74:75], v[66:69], off
	s_nop 0
	s_nop 0
	v_mov_b32_e32 v70, v240
	v_mov_b32_e32 v71, v241
	v_mov_b32_e32 v72, v242
	v_mov_b32_e32 v73, v243
	s_nop 0
	v_mov_b32_e32 v66, v244
	v_mov_b32_e32 v67, v245
	v_mov_b32_e32 v68, v246
	v_mov_b32_e32 v69, v247
	s_waitcnt vmcnt(8)
	v_lshlrev_b32_e32 v80, 16, v208
	v_and_b32_e32 v76, 0xffff0000, v208
	v_lshlrev_b32_e32 v81, 16, v209
	v_and_b32_e32 v77, 0xffff0000, v209
	v_lshlrev_b32_e32 v94, 16, v210
	v_and_b32_e32 v78, 0xffff0000, v210
	v_lshlrev_b32_e32 v95, 16, v211
	v_and_b32_e32 v79, 0xffff0000, v211
	s_mov_b64 s[98:99], 0xc000
	v_lshl_add_u64 v[248:249], v[250:251], 0, s[98:99]
	global_load_dwordx4 v[208:211], v[248:249], off offset:256
	s_nop 0
	v_add_f32_e32 v80, v70, v80
	v_add_f32_e32 v76, v71, v76
	v_add_f32_e32 v81, v72, v81
	v_add_f32_e32 v77, v73, v77
	s_waitcnt vmcnt(8)
	v_add_f32_e32 v94, v66, v94
	v_add_f32_e32 v78, v67, v78
	v_add_f32_e32 v95, v68, v95
	v_add_f32_e32 v79, v69, v79
	v_mul_f32_e32 v80, 0xbfb8aa3b, v80
	v_mul_f32_e32 v76, 0xbfb8aa3b, v76
	v_mul_f32_e32 v81, 0xbfb8aa3b, v81
	v_mul_f32_e32 v77, 0xbfb8aa3b, v77
	v_mul_f32_e32 v94, 0xbfb8aa3b, v94
	v_mul_f32_e32 v78, 0xbfb8aa3b, v78
	v_mul_f32_e32 v95, 0xbfb8aa3b, v95
	v_mul_f32_e32 v79, 0xbfb8aa3b, v79
	v_exp_f32_e32 v80, v80
	v_exp_f32_e32 v76, v76
	v_exp_f32_e32 v81, v81
	v_exp_f32_e32 v77, v77
	v_exp_f32_e32 v94, v94
	v_exp_f32_e32 v78, v78
	v_exp_f32_e32 v95, v95
	v_exp_f32_e32 v79, v79
	v_add_f32_e32 v80, 1.0, v80
	v_add_f32_e32 v76, 1.0, v76
	v_add_f32_e32 v81, 1.0, v81
	v_add_f32_e32 v77, 1.0, v77
	v_add_f32_e32 v94, 1.0, v94
	v_add_f32_e32 v78, 1.0, v78
	v_add_f32_e32 v95, 1.0, v95
	v_add_f32_e32 v79, 1.0, v79
	v_rcp_f32_e32 v80, v80
	v_rcp_f32_e32 v76, v76
	v_rcp_f32_e32 v81, v81
	v_rcp_f32_e32 v77, v77
	v_rcp_f32_e32 v94, v94
	v_rcp_f32_e32 v78, v78
	v_rcp_f32_e32 v95, v95
	v_rcp_f32_e32 v79, v79
	v_lshlrev_b32_e32 v96, 16, v220
	v_and_b32_e32 v86, 0xffff0000, v220
	v_lshlrev_b32_e32 v97, 16, v221
	v_and_b32_e32 v87, 0xffff0000, v221
	v_lshlrev_b32_e32 v102, 16, v222
	v_and_b32_e32 v88, 0xffff0000, v222
	v_lshlrev_b32_e32 v103, 16, v223
	v_and_b32_e32 v89, 0xffff0000, v223
	s_mov_b64 s[98:99], 0x18000
	v_lshl_add_u64 v[248:249], v[252:253], 0, s[98:99]
	global_load_dwordx4 v[220:223], v[248:249], off offset:256
	v_fmac_f32_e32 v96, v62, v80
	v_fmac_f32_e32 v86, v63, v76
	v_fmac_f32_e32 v97, v64, v81
	v_fmac_f32_e32 v87, v65, v77
	v_fmac_f32_e32 v102, v58, v94
	v_fmac_f32_e32 v88, v59, v78
	v_fmac_f32_e32 v103, v60, v95
	v_fmac_f32_e32 v89, v61, v79
	v_cvt_pk_bf16_f32 v58, v96, v86
	v_cvt_pk_bf16_f32 v59, v97, v87
	v_cvt_pk_bf16_f32 v60, v102, v88
	v_cvt_pk_bf16_f32 v61, v103, v89
	global_store_dwordx4 v[154:155], v[58:61], off offset:256
	s_nop 0
	s_nop 0
	s_nop 0
	s_waitcnt vmcnt(8)
; __device__ __forceinline__ unsigned cvt_pk_bf16(float lo, float hi) { unsigned r; asm volatile("v_cvt_pk_bf16_f32 %0, %1, %2" : "=v"(r) : "v"(lo), "v"(hi)); return r; }
; __device__ __forceinline__ float bflo(unsigned u) { return __uint_as_float(u << 16); }
; __device__ __forceinline__ float bfhi(unsigned u) { return __uint_as_float(u & 0xffff0000u); }
; __device__ __forceinline__ float sigm(float v) { return __builtin_amdgcn_rcpf(1.0f + __expf(-v)); }
; DI float bflo(unsigned u) { return __uint_as_float(u << 16); }
; DI float bfhi(unsigned u) { return __uint_as_float(u & 0xffff0000u); }
;     __device__ __forceinline__ void operator()(const f32x4 (&acc)[2][2][4][2], const Unit& u, int wr, int wc, int fr, int fq) const {
;     ...
;         for (int bj = 0; bj < 2; ++bj) {
;             const f32x4 b0 = *(const f32x4*)(gb + col0 + bj * HALF), b1 = *(const f32x4*)(gb + col0 + bj * HALF + 4);
; #pragma unroll
;             for (int ai = 0; ai < 2; ++ai)
; #pragma unroll
;                 for (int m = 0; m < 4; ++m) { const size_t row = (size_t)(row0 + ai * HALF + m * 16);
;                     const u32x4 g = *(const u32x4*)(gbase + row * 512 + gcol0 + bj * HALF);
;                     const f32x4 v0 = acc[ai][bj][m][0], v1 = acc[ai][bj][m][1];
;                     float r0 = v0[0] * sigm(bflo(g.x) + b0[0]), r1 = v0[1] * sigm(bfhi(g.x) + b0[1]), r2 = v0[2] * sigm(bflo(g.y) + b0[2]), r3 = v0[3] * sigm(bfhi(g.y) + b0[3]);
;                     float r4 = v1[0] * sigm(bflo(g.z) + b1[0]), r5 = v1[1] * sigm(bfhi(g.z) + b1[1]), r6 = v1[2] * sigm(bflo(g.w) + b1[2]), r7 = v1[3] * sigm(bfhi(g.w) + b1[3]);
;                     bf16_t* op = Mo + row * 1024 + col0 + bj * HALF;
;                     if (accum) { const u32x4 p = *(const u32x4*)op; r0 += bflo(p.x); r1 += bfhi(p.x); r2 += bflo(p.y); r3 += bfhi(p.y); r4 += bflo(p.z); r5 += bfhi(p.z); r6 += bflo(p.w); r7 += bfhi(p.w); }
;                     u32x4 w; w.x = cvt_pk_bf16(r0, r1); w.y = cvt_pk_bf16(r2, r3); w.z = cvt_pk_bf16(r4, r5); w.w = cvt_pk_bf16(r6, r7);
;                     *(u32x4*)op = w; }
	v_lshlrev_b32_e32 v76, 16, v212
	v_and_b32_e32 v58, 0xffff0000, v212
	v_lshlrev_b32_e32 v77, 16, v213
	v_and_b32_e32 v59, 0xffff0000, v213
	v_lshlrev_b32_e32 v78, 16, v214
	v_and_b32_e32 v60, 0xffff0000, v214
	v_lshlrev_b32_e32 v79, 16, v215
	v_and_b32_e32 v61, 0xffff0000, v215
	s_mov_b64 s[98:99], 0x20000
	v_lshl_add_u64 v[248:249], v[250:251], 0, s[98:99]
	global_load_dwordx4 v[212:215], v[248:249], off offset:256
	v_add_f32_e32 v76, v70, v76
	v_add_f32_e32 v58, v71, v58
	v_add_f32_e32 v77, v72, v77
	v_add_f32_e32 v59, v73, v59
	v_add_f32_e32 v78, v66, v78
	v_add_f32_e32 v60, v67, v60
	v_add_f32_e32 v79, v68, v79
	v_add_f32_e32 v61, v69, v61
	v_mul_f32_e32 v76, 0xbfb8aa3b, v76
	v_mul_f32_e32 v58, 0xbfb8aa3b, v58
	v_mul_f32_e32 v77, 0xbfb8aa3b, v77
	v_mul_f32_e32 v59, 0xbfb8aa3b, v59
	v_mul_f32_e32 v78, 0xbfb8aa3b, v78
	v_mul_f32_e32 v60, 0xbfb8aa3b, v60
	v_mul_f32_e32 v79, 0xbfb8aa3b, v79
	v_mul_f32_e32 v61, 0xbfb8aa3b, v61
	v_exp_f32_e32 v76, v76
	v_exp_f32_e32 v58, v58
	v_exp_f32_e32 v77, v77
	v_exp_f32_e32 v59, v59
	v_exp_f32_e32 v78, v78
	v_exp_f32_e32 v60, v60
	v_exp_f32_e32 v79, v79
	v_exp_f32_e32 v61, v61
	v_add_f32_e32 v76, 1.0, v76
	v_add_f32_e32 v58, 1.0, v58
	v_add_f32_e32 v77, 1.0, v77
	v_add_f32_e32 v59, 1.0, v59
	v_add_f32_e32 v78, 1.0, v78
	v_add_f32_e32 v60, 1.0, v60
	v_add_f32_e32 v79, 1.0, v79
	v_add_f32_e32 v61, 1.0, v61
	v_rcp_f32_e32 v76, v76
	v_rcp_f32_e32 v58, v58
	v_rcp_f32_e32 v77, v77
	v_rcp_f32_e32 v59, v59
	v_rcp_f32_e32 v78, v78
	v_rcp_f32_e32 v60, v60
	v_rcp_f32_e32 v79, v79
	v_rcp_f32_e32 v61, v61
	s_waitcnt vmcnt(8)
	v_lshlrev_b32_e32 v80, 16, v224
	v_and_b32_e32 v62, 0xffff0000, v224
	v_lshlrev_b32_e32 v81, 16, v225
	v_and_b32_e32 v63, 0xffff0000, v225
	v_lshlrev_b32_e32 v86, 16, v226
	v_and_b32_e32 v64, 0xffff0000, v226
	v_lshlrev_b32_e32 v87, 16, v227
	v_and_b32_e32 v65, 0xffff0000, v227
	s_mov_b64 s[98:99], 0x40000
	v_lshl_add_u64 v[248:249], v[252:253], 0, s[98:99]
	global_load_dwordx4 v[224:227], v[248:249], off offset:256
	v_fmac_f32_e32 v80, v54, v76
	v_fmac_f32_e32 v62, v55, v58
	v_fmac_f32_e32 v81, v56, v77
	v_fmac_f32_e32 v63, v57, v59
	v_fmac_f32_e32 v86, v50, v78
	v_fmac_f32_e32 v64, v51, v60
	v_fmac_f32_e32 v87, v52, v79
	v_fmac_f32_e32 v65, v53, v61
	v_cvt_pk_bf16_f32 v50, v80, v62
	v_cvt_pk_bf16_f32 v51, v81, v63
	v_cvt_pk_bf16_f32 v52, v86, v64
	v_cvt_pk_bf16_f32 v53, v87, v65
	global_store_dwordx4 v[130:131], v[50:53], off offset:256
	s_nop 0
	s_nop 0
	s_nop 0
	s_waitcnt vmcnt(8)
	v_lshlrev_b32_e32 v58, 16, v204
	v_and_b32_e32 v50, 0xffff0000, v204
	v_lshlrev_b32_e32 v59, 16, v205
	v_and_b32_e32 v51, 0xffff0000, v205
	v_lshlrev_b32_e32 v60, 16, v206
	v_and_b32_e32 v52, 0xffff0000, v206
	v_lshlrev_b32_e32 v61, 16, v207
	v_and_b32_e32 v53, 0xffff0000, v207
	s_mov_b64 s[98:99], 0x24000
	v_lshl_add_u64 v[248:249], v[250:251], 0, s[98:99]
	global_load_dwordx4 v[204:207], v[248:249], off offset:256
	v_add_f32_e32 v58, v70, v58
	v_add_f32_e32 v50, v71, v50
	v_add_f32_e32 v59, v72, v59
	v_add_f32_e32 v51, v73, v51
	v_add_f32_e32 v60, v66, v60
	v_add_f32_e32 v52, v67, v52
	v_add_f32_e32 v61, v68, v61
	v_add_f32_e32 v53, v69, v53
	v_mul_f32_e32 v58, 0xbfb8aa3b, v58
	v_mul_f32_e32 v50, 0xbfb8aa3b, v50
	v_mul_f32_e32 v59, 0xbfb8aa3b, v59
	v_mul_f32_e32 v51, 0xbfb8aa3b, v51
	v_mul_f32_e32 v60, 0xbfb8aa3b, v60
	v_mul_f32_e32 v52, 0xbfb8aa3b, v52
	v_mul_f32_e32 v61, 0xbfb8aa3b, v61
	v_mul_f32_e32 v53, 0xbfb8aa3b, v53
	v_exp_f32_e32 v58, v58
	v_exp_f32_e32 v50, v50
	v_exp_f32_e32 v59, v59
	v_exp_f32_e32 v51, v51
	v_exp_f32_e32 v60, v60
	v_exp_f32_e32 v52, v52
	v_exp_f32_e32 v61, v61
	v_exp_f32_e32 v53, v53
	v_add_f32_e32 v58, 1.0, v58
	v_add_f32_e32 v50, 1.0, v50
	v_add_f32_e32 v59, 1.0, v59
	v_add_f32_e32 v51, 1.0, v51
	v_add_f32_e32 v60, 1.0, v60
	v_add_f32_e32 v52, 1.0, v52
	v_add_f32_e32 v61, 1.0, v61
	v_add_f32_e32 v53, 1.0, v53
	v_rcp_f32_e32 v58, v58
	v_rcp_f32_e32 v50, v50
	v_rcp_f32_e32 v59, v59
	v_rcp_f32_e32 v51, v51
	v_rcp_f32_e32 v60, v60
	v_rcp_f32_e32 v52, v52
	v_rcp_f32_e32 v61, v61
	v_rcp_f32_e32 v53, v53
	s_waitcnt vmcnt(8)
	v_lshlrev_b32_e32 v62, 16, v216
	v_and_b32_e32 v54, 0xffff0000, v216
	v_lshlrev_b32_e32 v63, 16, v217
	v_and_b32_e32 v55, 0xffff0000, v217
	v_lshlrev_b32_e32 v64, 16, v218
	v_and_b32_e32 v56, 0xffff0000, v218
	v_lshlrev_b32_e32 v65, 16, v219
	v_and_b32_e32 v57, 0xffff0000, v219
	s_mov_b64 s[98:99], 0x48000
	v_lshl_add_u64 v[248:249], v[252:253], 0, s[98:99]
	global_load_dwordx4 v[216:219], v[248:249], off offset:256
	v_fmac_f32_e32 v62, v46, v58
	v_fmac_f32_e32 v54, v47, v50
	v_fmac_f32_e32 v63, v48, v59
	v_fmac_f32_e32 v55, v49, v51
	v_fmac_f32_e32 v64, v42, v60
	v_fmac_f32_e32 v56, v43, v52
	v_fmac_f32_e32 v65, v44, v61
	v_fmac_f32_e32 v57, v45, v53
	v_cvt_pk_bf16_f32 v42, v62, v54
	v_cvt_pk_bf16_f32 v43, v63, v55
	v_cvt_pk_bf16_f32 v44, v64, v56
	v_cvt_pk_bf16_f32 v45, v65, v57
	global_store_dwordx4 v[122:123], v[42:45], off offset:256
	s_nop 0
	s_nop 0
	s_nop 0
	s_waitcnt vmcnt(8)
; __device__ __forceinline__ unsigned cvt_pk_bf16(float lo, float hi) { unsigned r; asm volatile("v_cvt_pk_bf16_f32 %0, %1, %2" : "=v"(r) : "v"(lo), "v"(hi)); return r; }
; __device__ __forceinline__ float bflo(unsigned u) { return __uint_as_float(u << 16); }
; __device__ __forceinline__ float bfhi(unsigned u) { return __uint_as_float(u & 0xffff0000u); }
; __device__ __forceinline__ float sigm(float v) { return __builtin_amdgcn_rcpf(1.0f + __expf(-v)); }
; DI float bflo(unsigned u) { return __uint_as_float(u << 16); }
; DI float bfhi(unsigned u) { return __uint_as_float(u & 0xffff0000u); }
;     __device__ __forceinline__ void operator()(const f32x4 (&acc)[2][2][4][2], const Unit& u, int wr, int wc, int fr, int fq) const {
;     ...
;         for (int bj = 0; bj < 2; ++bj) {
;             const f32x4 b0 = *(const f32x4*)(gb + col0 + bj * HALF), b1 = *(const f32x4*)(gb + col0 + bj * HALF + 4);
; #pragma unroll
;             for (int ai = 0; ai < 2; ++ai)
; #pragma unroll
;                 for (int m = 0; m < 4; ++m) { const size_t row = (size_t)(row0 + ai * HALF + m * 16);
;                     const u32x4 g = *(const u32x4*)(gbase + row * 512 + gcol0 + bj * HALF);
;                     const f32x4 v0 = acc[ai][bj][m][0], v1 = acc[ai][bj][m][1];
;                     float r0 = v0[0] * sigm(bflo(g.x) + b0[0]), r1 = v0[1] * sigm(bfhi(g.x) + b0[1]), r2 = v0[2] * sigm(bflo(g.y) + b0[2]), r3 = v0[3] * sigm(bfhi(g.y) + b0[3]);
;                     float r4 = v1[0] * sigm(bflo(g.z) + b1[0]), r5 = v1[1] * sigm(bfhi(g.z) + b1[1]), r6 = v1[2] * sigm(bflo(g.w) + b1[2]), r7 = v1[3] * sigm(bfhi(g.w) + b1[3]);
;                     bf16_t* op = Mo + row * 1024 + col0 + bj * HALF;
;                     if (accum) { const u32x4 p = *(const u32x4*)op; r0 += bflo(p.x); r1 += bfhi(p.x); r2 += bflo(p.y); r3 += bfhi(p.y); r4 += bflo(p.z); r5 += bfhi(p.z); r6 += bflo(p.w); r7 += bfhi(p.w); }
;                     u32x4 w; w.x = cvt_pk_bf16(r0, r1); w.y = cvt_pk_bf16(r2, r3); w.z = cvt_pk_bf16(r4, r5); w.w = cvt_pk_bf16(r6, r7);
;                     *(u32x4*)op = w; }
	v_lshlrev_b32_e32 v50, 16, v208
	v_and_b32_e32 v42, 0xffff0000, v208
	v_lshlrev_b32_e32 v51, 16, v209
	v_and_b32_e32 v43, 0xffff0000, v209
	v_lshlrev_b32_e32 v52, 16, v210
	v_and_b32_e32 v44, 0xffff0000, v210
	v_lshlrev_b32_e32 v53, 16, v211
	v_and_b32_e32 v45, 0xffff0000, v211
	s_mov_b64 s[98:99], 0x28000
	v_lshl_add_u64 v[248:249], v[250:251], 0, s[98:99]
	global_load_dwordx4 v[208:211], v[248:249], off offset:256
	v_add_f32_e32 v50, v70, v50
	v_add_f32_e32 v42, v71, v42
	v_add_f32_e32 v51, v72, v51
	v_add_f32_e32 v43, v73, v43
	v_add_f32_e32 v52, v66, v52
	v_add_f32_e32 v44, v67, v44
	v_add_f32_e32 v53, v68, v53
	v_add_f32_e32 v45, v69, v45
	v_mul_f32_e32 v50, 0xbfb8aa3b, v50
	v_mul_f32_e32 v42, 0xbfb8aa3b, v42
	v_mul_f32_e32 v51, 0xbfb8aa3b, v51
	v_mul_f32_e32 v43, 0xbfb8aa3b, v43
	v_mul_f32_e32 v52, 0xbfb8aa3b, v52
	v_mul_f32_e32 v44, 0xbfb8aa3b, v44
	v_mul_f32_e32 v53, 0xbfb8aa3b, v53
	v_mul_f32_e32 v45, 0xbfb8aa3b, v45
	v_exp_f32_e32 v50, v50
	v_exp_f32_e32 v42, v42
	v_exp_f32_e32 v51, v51
	v_exp_f32_e32 v43, v43
	v_exp_f32_e32 v52, v52
	v_exp_f32_e32 v44, v44
	v_exp_f32_e32 v53, v53
	v_exp_f32_e32 v45, v45
	v_add_f32_e32 v50, 1.0, v50
	v_add_f32_e32 v42, 1.0, v42
	v_add_f32_e32 v51, 1.0, v51
	v_add_f32_e32 v43, 1.0, v43
	v_add_f32_e32 v52, 1.0, v52
	v_add_f32_e32 v44, 1.0, v44
	v_add_f32_e32 v53, 1.0, v53
	v_add_f32_e32 v45, 1.0, v45
	v_rcp_f32_e32 v50, v50
	v_rcp_f32_e32 v42, v42
	v_rcp_f32_e32 v51, v51
	v_rcp_f32_e32 v43, v43
	v_rcp_f32_e32 v52, v52
	v_rcp_f32_e32 v44, v44
	v_rcp_f32_e32 v53, v53
	v_rcp_f32_e32 v45, v45
	s_waitcnt vmcnt(8)
	v_lshlrev_b32_e32 v54, 16, v220
	v_and_b32_e32 v46, 0xffff0000, v220
	v_lshlrev_b32_e32 v55, 16, v221
	v_and_b32_e32 v47, 0xffff0000, v221
	v_lshlrev_b32_e32 v56, 16, v222
	v_and_b32_e32 v48, 0xffff0000, v222
	v_lshlrev_b32_e32 v57, 16, v223
	v_and_b32_e32 v49, 0xffff0000, v223
	s_mov_b64 s[98:99], 0x50000
	v_lshl_add_u64 v[248:249], v[252:253], 0, s[98:99]
	global_load_dwordx4 v[220:223], v[248:249], off offset:256
	v_fmac_f32_e32 v54, v38, v50
	v_fmac_f32_e32 v46, v39, v42
	v_fmac_f32_e32 v55, v40, v51
	v_fmac_f32_e32 v47, v41, v43
	v_fmac_f32_e32 v56, v34, v52
	v_fmac_f32_e32 v48, v35, v44
	v_fmac_f32_e32 v57, v36, v53
	v_fmac_f32_e32 v49, v37, v45
	v_cvt_pk_bf16_f32 v34, v54, v46
	v_cvt_pk_bf16_f32 v35, v55, v47
	v_cvt_pk_bf16_f32 v36, v56, v48
	v_cvt_pk_bf16_f32 v37, v57, v49
	global_store_dwordx4 v[106:107], v[34:37], off offset:256
	s_nop 0
	s_nop 0
	s_nop 0
	s_waitcnt vmcnt(8)
	v_lshlrev_b32_e32 v42, 16, v212
	v_and_b32_e32 v34, 0xffff0000, v212
	v_lshlrev_b32_e32 v43, 16, v213
	v_and_b32_e32 v35, 0xffff0000, v213
	v_lshlrev_b32_e32 v44, 16, v214
	v_and_b32_e32 v36, 0xffff0000, v214
	v_lshlrev_b32_e32 v45, 16, v215
	v_and_b32_e32 v37, 0xffff0000, v215
	s_mov_b64 s[98:99], 0x2c000
	v_lshl_add_u64 v[248:249], v[250:251], 0, s[98:99]
	global_load_dwordx4 v[212:215], v[248:249], off offset:256
	v_add_f32_e32 v42, v70, v42
	v_add_f32_e32 v34, v71, v34
	v_add_f32_e32 v43, v72, v43
	v_add_f32_e32 v35, v73, v35
	v_add_f32_e32 v44, v66, v44
	v_add_f32_e32 v36, v67, v36
	v_add_f32_e32 v45, v68, v45
	v_add_f32_e32 v37, v69, v37
	v_mul_f32_e32 v42, 0xbfb8aa3b, v42
	v_mul_f32_e32 v34, 0xbfb8aa3b, v34
	v_mul_f32_e32 v43, 0xbfb8aa3b, v43
	v_mul_f32_e32 v35, 0xbfb8aa3b, v35
	v_mul_f32_e32 v44, 0xbfb8aa3b, v44
	v_mul_f32_e32 v36, 0xbfb8aa3b, v36
	v_mul_f32_e32 v45, 0xbfb8aa3b, v45
	v_mul_f32_e32 v37, 0xbfb8aa3b, v37
	v_exp_f32_e32 v42, v42
	v_exp_f32_e32 v34, v34
	v_exp_f32_e32 v43, v43
	v_exp_f32_e32 v35, v35
	v_exp_f32_e32 v44, v44
	v_exp_f32_e32 v36, v36
	v_exp_f32_e32 v45, v45
	v_exp_f32_e32 v37, v37
	v_add_f32_e32 v42, 1.0, v42
	v_add_f32_e32 v34, 1.0, v34
	v_add_f32_e32 v43, 1.0, v43
	v_add_f32_e32 v35, 1.0, v35
	v_add_f32_e32 v44, 1.0, v44
	v_add_f32_e32 v36, 1.0, v36
	v_add_f32_e32 v45, 1.0, v45
	v_add_f32_e32 v37, 1.0, v37
	v_rcp_f32_e32 v42, v42
	v_rcp_f32_e32 v34, v34
	v_rcp_f32_e32 v43, v43
	v_rcp_f32_e32 v35, v35
	v_rcp_f32_e32 v44, v44
	v_rcp_f32_e32 v36, v36
	v_rcp_f32_e32 v45, v45
	v_rcp_f32_e32 v37, v37
	s_waitcnt vmcnt(8)
	v_lshlrev_b32_e32 v46, 16, v224
	v_and_b32_e32 v38, 0xffff0000, v224
	v_lshlrev_b32_e32 v47, 16, v225
	v_and_b32_e32 v39, 0xffff0000, v225
	v_lshlrev_b32_e32 v48, 16, v226
	v_and_b32_e32 v40, 0xffff0000, v226
	v_lshlrev_b32_e32 v49, 16, v227
	v_and_b32_e32 v41, 0xffff0000, v227
	s_mov_b64 s[98:99], 0x58000
	v_lshl_add_u64 v[248:249], v[252:253], 0, s[98:99]
	global_load_dwordx4 v[224:227], v[248:249], off offset:256
	v_fmac_f32_e32 v46, v30, v42
	v_fmac_f32_e32 v38, v31, v34
	v_fmac_f32_e32 v47, v32, v43
	v_fmac_f32_e32 v39, v33, v35
	v_fmac_f32_e32 v48, v26, v44
	v_fmac_f32_e32 v40, v27, v36
	v_fmac_f32_e32 v49, v28, v45
	v_fmac_f32_e32 v41, v29, v37
	v_cvt_pk_bf16_f32 v26, v46, v38
	v_cvt_pk_bf16_f32 v27, v47, v39
	v_cvt_pk_bf16_f32 v28, v48, v40
	v_cvt_pk_bf16_f32 v29, v49, v41
	global_store_dwordx4 v[98:99], v[26:29], off offset:256
	s_nop 0
	s_nop 0
	s_nop 0
	s_waitcnt vmcnt(8)
; __device__ __forceinline__ unsigned cvt_pk_bf16(float lo, float hi) { unsigned r; asm volatile("v_cvt_pk_bf16_f32 %0, %1, %2" : "=v"(r) : "v"(lo), "v"(hi)); return r; }
; __device__ __forceinline__ float bflo(unsigned u) { return __uint_as_float(u << 16); }
; __device__ __forceinline__ float bfhi(unsigned u) { return __uint_as_float(u & 0xffff0000u); }
; __device__ __forceinline__ float sigm(float v) { return __builtin_amdgcn_rcpf(1.0f + __expf(-v)); }
; DI float bflo(unsigned u) { return __uint_as_float(u << 16); }
; DI float bfhi(unsigned u) { return __uint_as_float(u & 0xffff0000u); }
;     __device__ __forceinline__ void operator()(const f32x4 (&acc)[2][2][4][2], const Unit& u, int wr, int wc, int fr, int fq) const {
;     ...
;         for (int bj = 0; bj < 2; ++bj) {
;             const f32x4 b0 = *(const f32x4*)(gb + col0 + bj * HALF), b1 = *(const f32x4*)(gb + col0 + bj * HALF + 4);
; #pragma unroll
;             for (int ai = 0; ai < 2; ++ai)
; #pragma unroll
;                 for (int m = 0; m < 4; ++m) { const size_t row = (size_t)(row0 + ai * HALF + m * 16);
;                     const u32x4 g = *(const u32x4*)(gbase + row * 512 + gcol0 + bj * HALF);
;                     const f32x4 v0 = acc[ai][bj][m][0], v1 = acc[ai][bj][m][1];
;                     float r0 = v0[0] * sigm(bflo(g.x) + b0[0]), r1 = v0[1] * sigm(bfhi(g.x) + b0[1]), r2 = v0[2] * sigm(bflo(g.y) + b0[2]), r3 = v0[3] * sigm(bfhi(g.y) + b0[3]);
;                     float r4 = v1[0] * sigm(bflo(g.z) + b1[0]), r5 = v1[1] * sigm(bfhi(g.z) + b1[1]), r6 = v1[2] * sigm(bflo(g.w) + b1[2]), r7 = v1[3] * sigm(bfhi(g.w) + b1[3]);
;                     bf16_t* op = Mo + row * 1024 + col0 + bj * HALF;
;                     if (accum) { const u32x4 p = *(const u32x4*)op; r0 += bflo(p.x); r1 += bfhi(p.x); r2 += bflo(p.y); r3 += bfhi(p.y); r4 += bflo(p.z); r5 += bfhi(p.z); r6 += bflo(p.w); r7 += bfhi(p.w); }
;                     u32x4 w; w.x = cvt_pk_bf16(r0, r1); w.y = cvt_pk_bf16(r2, r3); w.z = cvt_pk_bf16(r4, r5); w.w = cvt_pk_bf16(r6, r7);
;                     *(u32x4*)op = w; }
	v_lshlrev_b32_e32 v34, 16, v204
	v_and_b32_e32 v26, 0xffff0000, v204
	v_lshlrev_b32_e32 v35, 16, v205
	v_and_b32_e32 v27, 0xffff0000, v205
	v_lshlrev_b32_e32 v36, 16, v206
	v_and_b32_e32 v28, 0xffff0000, v206
	v_lshlrev_b32_e32 v37, 16, v207
	v_and_b32_e32 v29, 0xffff0000, v207
	v_add_f32_e32 v34, v70, v34
	v_add_f32_e32 v26, v71, v26
	v_add_f32_e32 v35, v72, v35
	v_add_f32_e32 v27, v73, v27
	v_add_f32_e32 v36, v66, v36
	v_add_f32_e32 v28, v67, v28
	v_add_f32_e32 v37, v68, v37
	v_add_f32_e32 v29, v69, v29
	v_mul_f32_e32 v34, 0xbfb8aa3b, v34
	v_mul_f32_e32 v26, 0xbfb8aa3b, v26
	v_mul_f32_e32 v35, 0xbfb8aa3b, v35
	v_mul_f32_e32 v27, 0xbfb8aa3b, v27
	v_mul_f32_e32 v36, 0xbfb8aa3b, v36
	v_mul_f32_e32 v28, 0xbfb8aa3b, v28
	v_mul_f32_e32 v37, 0xbfb8aa3b, v37
	v_mul_f32_e32 v29, 0xbfb8aa3b, v29
	v_exp_f32_e32 v34, v34
	v_exp_f32_e32 v26, v26
	v_exp_f32_e32 v35, v35
	v_exp_f32_e32 v27, v27
	v_exp_f32_e32 v36, v36
	v_exp_f32_e32 v28, v28
	v_exp_f32_e32 v37, v37
	v_exp_f32_e32 v29, v29
	v_add_f32_e32 v34, 1.0, v34
	v_add_f32_e32 v26, 1.0, v26
	v_add_f32_e32 v35, 1.0, v35
	v_add_f32_e32 v27, 1.0, v27
	v_add_f32_e32 v36, 1.0, v36
	v_add_f32_e32 v28, 1.0, v28
	v_add_f32_e32 v37, 1.0, v37
	v_add_f32_e32 v29, 1.0, v29
	v_rcp_f32_e32 v34, v34
	v_rcp_f32_e32 v26, v26
	v_rcp_f32_e32 v35, v35
	v_rcp_f32_e32 v27, v27
	v_rcp_f32_e32 v36, v36
	v_rcp_f32_e32 v28, v28
	v_rcp_f32_e32 v37, v37
	v_rcp_f32_e32 v29, v29
	s_waitcnt vmcnt(7)
	v_lshlrev_b32_e32 v38, 16, v216
	v_and_b32_e32 v30, 0xffff0000, v216
	v_lshlrev_b32_e32 v39, 16, v217
	v_and_b32_e32 v31, 0xffff0000, v217
	v_lshlrev_b32_e32 v40, 16, v218
	v_and_b32_e32 v32, 0xffff0000, v218
	v_lshlrev_b32_e32 v41, 16, v219
	v_and_b32_e32 v33, 0xffff0000, v219
	v_fmac_f32_e32 v38, v22, v34
	v_fmac_f32_e32 v30, v23, v26
	v_fmac_f32_e32 v39, v24, v35
	v_fmac_f32_e32 v31, v25, v27
	v_fmac_f32_e32 v40, v18, v36
	v_fmac_f32_e32 v32, v19, v28
	v_fmac_f32_e32 v41, v20, v37
	v_fmac_f32_e32 v33, v21, v29
	v_cvt_pk_bf16_f32 v18, v38, v30
	v_cvt_pk_bf16_f32 v19, v39, v31
	v_cvt_pk_bf16_f32 v20, v40, v32
	v_cvt_pk_bf16_f32 v21, v41, v33
	global_store_dwordx4 v[90:91], v[18:21], off offset:256
	s_nop 0
	s_nop 0
	s_nop 0
	s_waitcnt vmcnt(6)
	v_lshlrev_b32_e32 v26, 16, v208
	v_and_b32_e32 v18, 0xffff0000, v208
	v_lshlrev_b32_e32 v27, 16, v209
	v_and_b32_e32 v19, 0xffff0000, v209
	v_lshlrev_b32_e32 v28, 16, v210
	v_and_b32_e32 v20, 0xffff0000, v210
	v_lshlrev_b32_e32 v29, 16, v211
	v_and_b32_e32 v21, 0xffff0000, v211
	v_add_f32_e32 v26, v70, v26
	v_add_f32_e32 v18, v71, v18
	v_add_f32_e32 v27, v72, v27
	v_add_f32_e32 v19, v73, v19
	v_add_f32_e32 v28, v66, v28
	v_add_f32_e32 v20, v67, v20
	v_add_f32_e32 v29, v68, v29
	v_add_f32_e32 v21, v69, v21
	v_mul_f32_e32 v26, 0xbfb8aa3b, v26
	v_mul_f32_e32 v18, 0xbfb8aa3b, v18
	v_mul_f32_e32 v27, 0xbfb8aa3b, v27
	v_mul_f32_e32 v19, 0xbfb8aa3b, v19
	v_mul_f32_e32 v28, 0xbfb8aa3b, v28
	v_mul_f32_e32 v20, 0xbfb8aa3b, v20
	v_mul_f32_e32 v29, 0xbfb8aa3b, v29
	v_mul_f32_e32 v21, 0xbfb8aa3b, v21
	v_exp_f32_e32 v26, v26
	v_exp_f32_e32 v18, v18
	v_exp_f32_e32 v27, v27
	v_exp_f32_e32 v19, v19
	v_exp_f32_e32 v28, v28
	v_exp_f32_e32 v20, v20
	v_exp_f32_e32 v29, v29
	v_exp_f32_e32 v21, v21
	v_add_f32_e32 v26, 1.0, v26
	v_add_f32_e32 v18, 1.0, v18
	v_add_f32_e32 v27, 1.0, v27
	v_add_f32_e32 v19, 1.0, v19
	v_add_f32_e32 v28, 1.0, v28
	v_add_f32_e32 v20, 1.0, v20
	v_add_f32_e32 v29, 1.0, v29
	v_add_f32_e32 v21, 1.0, v21
	v_rcp_f32_e32 v26, v26
	v_rcp_f32_e32 v18, v18
	v_rcp_f32_e32 v27, v27
	v_rcp_f32_e32 v19, v19
	v_rcp_f32_e32 v28, v28
	v_rcp_f32_e32 v20, v20
	v_rcp_f32_e32 v29, v29
	v_rcp_f32_e32 v21, v21
	s_waitcnt vmcnt(5)
	v_lshlrev_b32_e32 v30, 16, v220
	v_and_b32_e32 v22, 0xffff0000, v220
	v_lshlrev_b32_e32 v31, 16, v221
	v_and_b32_e32 v23, 0xffff0000, v221
	v_lshlrev_b32_e32 v32, 16, v222
	v_and_b32_e32 v24, 0xffff0000, v222
	v_lshlrev_b32_e32 v33, 16, v223
	v_and_b32_e32 v25, 0xffff0000, v223
	v_fmac_f32_e32 v30, v14, v26
	v_fmac_f32_e32 v22, v15, v18
	v_fmac_f32_e32 v31, v16, v27
	v_fmac_f32_e32 v23, v17, v19
	v_fmac_f32_e32 v32, v10, v28
	v_fmac_f32_e32 v24, v11, v20
	v_fmac_f32_e32 v33, v12, v29
	v_fmac_f32_e32 v25, v13, v21
	v_cvt_pk_bf16_f32 v10, v30, v22
	v_cvt_pk_bf16_f32 v11, v31, v23
	v_cvt_pk_bf16_f32 v12, v32, v24
	v_cvt_pk_bf16_f32 v13, v33, v25
	global_store_dwordx4 v[82:83], v[10:13], off offset:256
	s_nop 0
	s_nop 0
	s_nop 0
	s_waitcnt vmcnt(4)
	v_lshlrev_b32_e32 v18, 16, v212
	v_and_b32_e32 v10, 0xffff0000, v212
	v_lshlrev_b32_e32 v19, 16, v213
	v_and_b32_e32 v11, 0xffff0000, v213
	v_lshlrev_b32_e32 v20, 16, v214
	v_and_b32_e32 v12, 0xffff0000, v214
	v_lshlrev_b32_e32 v21, 16, v215
	v_and_b32_e32 v13, 0xffff0000, v215
	v_add_f32_e32 v18, v70, v18
	v_add_f32_e32 v10, v71, v10
	v_add_f32_e32 v19, v72, v19
	v_add_f32_e32 v11, v73, v11
	v_add_f32_e32 v20, v66, v20
	v_add_f32_e32 v12, v67, v12
	v_add_f32_e32 v21, v68, v21
	v_add_f32_e32 v13, v69, v13
	v_mul_f32_e32 v18, 0xbfb8aa3b, v18
	v_mul_f32_e32 v10, 0xbfb8aa3b, v10
	v_mul_f32_e32 v19, 0xbfb8aa3b, v19
	v_mul_f32_e32 v11, 0xbfb8aa3b, v11
	v_mul_f32_e32 v20, 0xbfb8aa3b, v20
	v_mul_f32_e32 v12, 0xbfb8aa3b, v12
	v_mul_f32_e32 v21, 0xbfb8aa3b, v21
	v_mul_f32_e32 v13, 0xbfb8aa3b, v13
	v_exp_f32_e32 v18, v18
	v_exp_f32_e32 v10, v10
	v_exp_f32_e32 v19, v19
	v_exp_f32_e32 v11, v11
	v_exp_f32_e32 v20, v20
	v_exp_f32_e32 v12, v12
	v_exp_f32_e32 v21, v21
	v_exp_f32_e32 v13, v13
	v_add_f32_e32 v18, 1.0, v18
	v_add_f32_e32 v10, 1.0, v10
	v_add_f32_e32 v19, 1.0, v19
	v_add_f32_e32 v11, 1.0, v11
	v_add_f32_e32 v20, 1.0, v20
	v_add_f32_e32 v12, 1.0, v12
	v_add_f32_e32 v21, 1.0, v21
	v_add_f32_e32 v13, 1.0, v13
	v_rcp_f32_e32 v18, v18
	v_rcp_f32_e32 v10, v10
	v_rcp_f32_e32 v19, v19
	v_rcp_f32_e32 v11, v11
	v_rcp_f32_e32 v20, v20
	v_rcp_f32_e32 v12, v12
	v_rcp_f32_e32 v21, v21
	v_rcp_f32_e32 v13, v13
	s_waitcnt vmcnt(3)
	v_lshlrev_b32_e32 v22, 16, v224
	v_and_b32_e32 v14, 0xffff0000, v224
	v_lshlrev_b32_e32 v23, 16, v225
	v_and_b32_e32 v15, 0xffff0000, v225
	v_lshlrev_b32_e32 v24, 16, v226
	v_and_b32_e32 v16, 0xffff0000, v226
	v_lshlrev_b32_e32 v25, 16, v227
	v_and_b32_e32 v17, 0xffff0000, v227
	v_fmac_f32_e32 v22, v6, v18
	v_fmac_f32_e32 v14, v7, v10
	v_fmac_f32_e32 v23, v8, v19
	v_fmac_f32_e32 v15, v9, v11
	v_fmac_f32_e32 v24, v2, v20
	v_fmac_f32_e32 v16, v3, v12
	v_fmac_f32_e32 v25, v4, v21
	v_fmac_f32_e32 v17, v5, v13
	v_cvt_pk_bf16_f32 v2, v22, v14
	v_cvt_pk_bf16_f32 v3, v23, v15
	v_cvt_pk_bf16_f32 v4, v24, v16
	v_cvt_pk_bf16_f32 v5, v25, v17
	global_store_dwordx4 v[74:75], v[2:5], off offset:256
	s_cbranch_vccnz .LBB0_893
	s_andn2_b64 vcc, exec, s[0:1]
	s_cbranch_vccnz .LBB0_892
	s_barrier
	s_branch .LBB0_892

; __global__ void __launch_bounds__(512, 2) mega_fwd(Params P) {
	.amdhsa_kernel _Z8mega_fwd6Params
		.amdhsa_group_segment_fixed_size 0
		.amdhsa_private_segment_fixed_size 0
		.amdhsa_kernarg_size 400
		.amdhsa_user_sgpr_count 2
		.amdhsa_user_sgpr_dispatch_ptr 0
		.amdhsa_user_sgpr_queue_ptr 0
		.amdhsa_user_sgpr_kernarg_segment_ptr 1
		.amdhsa_user_sgpr_dispatch_id 0
		.amdhsa_user_sgpr_kernarg_preload_length 0
		.amdhsa_user_sgpr_kernarg_preload_offset 0
		.amdhsa_user_sgpr_private_segment_size 0
		.amdhsa_uses_dynamic_stack 0
		.amdhsa_enable_private_segment 0
		.amdhsa_system_sgpr_workgroup_id_x 1
		.amdhsa_system_sgpr_workgroup_id_y 0
		.amdhsa_system_sgpr_workgroup_id_z 0
		.amdhsa_system_sgpr_workgroup_info 0
		.amdhsa_system_vgpr_workitem_id 2
		.amdhsa_next_free_vgpr 256
		.amdhsa_next_free_sgpr 100
		.amdhsa_accum_offset 256
		.amdhsa_reserve_vcc 1
		.amdhsa_float_round_mode_32 0
		.amdhsa_float_round_mode_16_64 0
		.amdhsa_float_denorm_mode_32 3
		.amdhsa_float_denorm_mode_16_64 3
		.amdhsa_dx10_clamp 1
		.amdhsa_ieee_mode 1
		.amdhsa_fp16_overflow 0
		.amdhsa_tg_split 0
		.amdhsa_exception_fp_ieee_invalid_op 0
		.amdhsa_exception_fp_denorm_src 0
		.amdhsa_exception_fp_ieee_div_zero 0
		.amdhsa_exception_fp_ieee_overflow 0
		.amdhsa_exception_fp_ieee_underflow 0
		.amdhsa_exception_fp_ieee_inexact 0
		.amdhsa_exception_int_div_zero 0
	.end_amdhsa_kernel

; __global__ void __launch_bounds__(512, 2) mega_fwd(Params P) {
amdhsa.kernels:
  - .agpr_count:     0
    .args:
      - .offset:         0
        .size:           144
        .value_kind:     by_value
      - .offset:         144
        .size:           4
        .value_kind:     hidden_block_count_x
      - .offset:         148
        .size:           4
        .value_kind:     hidden_block_count_y
      - .offset:         152
        .size:           4
        .value_kind:     hidden_block_count_z
      - .offset:         156
        .size:           2
        .value_kind:     hidden_group_size_x
      - .offset:         158
        .size:           2
        .value_kind:     hidden_group_size_y
      - .offset:         160
        .size:           2
        .value_kind:     hidden_group_size_z
      - .offset:         162
        .size:           2
        .value_kind:     hidden_remainder_x
      - .offset:         164
        .size:           2
        .value_kind:     hidden_remainder_y
      - .offset:         166
        .size:           2
        .value_kind:     hidden_remainder_z
      - .offset:         184
        .size:           8
        .value_kind:     hidden_global_offset_x
      - .offset:         192
        .size:           8
        .value_kind:     hidden_global_offset_y
      - .offset:         200
        .size:           8
        .value_kind:     hidden_global_offset_z
      - .offset:         208
        .size:           2
        .value_kind:     hidden_grid_dims
      - .offset:         232
        .size:           8
        .value_kind:     hidden_multigrid_sync_arg
      - .offset:         264
        .size:           4
        .value_kind:     hidden_dynamic_lds_size
    .group_segment_fixed_size: 0
    .kernarg_segment_align: 8
    .kernarg_segment_size: 400
    .language:       OpenCL C
    .language_version:
      - 2
      - 0
    .max_flat_workgroup_size: 512
    .name:           _Z8mega_fwd6Params
    .private_segment_fixed_size: 0
    .sgpr_count:     106
    .sgpr_spill_count: 85
    .symbol:         _Z8mega_fwd6Params.kd
    .uniform_work_group_size: 1
    .uses_dynamic_stack: false
    .vgpr_count:     256
    .vgpr_spill_count: 0
    .wavefront_size: 64
